# phase-scoped static priority raise: waves 0-3 keep s_setprio 1 from the first K-loop of a GEMM phase through its epilogues, reset at every seam entry instead of after each K-loop; otherwise v78
# speedup vs baseline: 1.0010x; 1.0010x over previous
; __device__ __forceinline__ unsigned xb_ld(unsigned* p)              { return __hip_atomic_load(p, __ATOMIC_RELAXED, __HIP_MEMORY_SCOPE_AGENT); }
; __device__ __forceinline__ unsigned xb_add(unsigned* p, unsigned v) { return __hip_atomic_fetch_add(p, v, __ATOMIC_RELAXED, __HIP_MEMORY_SCOPE_AGENT); }
; __device__ __forceinline__ void xcd_barrier_complete(unsigned* bar, unsigned x, unsigned& nloc, unsigned& nx) {
;     const unsigned G = gridDim.x * gridDim.y * gridDim.z;
;     unsigned sum, cnt, mine, sp = 0u;
;     for (;;) {
;         sum = 0u; cnt = 0u; mine = 0u;
; #pragma unroll
;         for (unsigned j = 0; j < 16; ++j) { const unsigned c = xb_ld(&bar[XB_XCNT(j)]); sum += c; cnt += (c > 0u) ? 1u : 0u; mine = (j == x) ? c : mine; }
; __device__ __forceinline__ void xcd_barrier(const XcdBarrier& b) {
;     asm volatile("s_waitcnt vmcnt(0)" ::: "memory");
;     __syncthreads();
;     if (threadIdx.x == 0) {
;         unsigned* bar = b.bar;
;         __builtin_amdgcn_s_waitcnt(0);
;         unsigned nloc = b.st[0], nx = b.st[1];
;         if (nloc == 0u) { xcd_barrier_complete(bar, b.x, nloc, nx); b.st[0] = nloc; b.st[1] = nx; }
;         const unsigned old = xb_add(&bar[XB_XSUB(b.x)], 1u);
.LBB0_135:
	s_or_b64 exec, exec, s[0:1]
	s_cmp_lt_i32 s57, 2
	s_cbranch_scc1 .LBB0_189
	s_setprio 0
	s_add_i32 s0, 0, 0x20520
	v_mov_b32_e32 v0, s0
	ds_read_b64 v[0:1], v0
	s_getreg_b32 s3, hwreg(HW_REG_XCC_ID, 0, 4)
	s_waitcnt vmcnt(0)
	s_waitcnt lgkmcnt(0)
	s_barrier
	v_readfirstlane_b32 s4, v0
	v_readfirstlane_b32 s5, v1
	s_mov_b64 s[0:1], exec
	v_readlane_b32 s6, v246, 2
	v_readlane_b32 s7, v246, 3
	s_and_b64 s[6:7], s[0:1], s[6:7]
	s_mov_b64 exec, s[6:7]
	s_cbranch_execz .LBB0_188
	s_add_i32 s6, 0, 0x20160
	v_mov_b32_e32 v0, s6
	s_waitcnt vmcnt(0) expcnt(0) lgkmcnt(0)
	ds_read_b32 v2, v0
	s_add_i32 s6, 0, 0x20164
	v_mov_b32_e32 v0, s6
	ds_read_b32 v0, v0
	s_and_b32 s3, s3, 15
	s_waitcnt lgkmcnt(1)
	v_cmp_ne_u32_e32 vcc, 0, v2
	s_cbranch_vccnz .LBB0_152
	v_readlane_b32 s6, v246, 0
	v_readlane_b32 s7, v246, 1
	s_load_dwordx2 s[10:11], s[6:7], 0x4
	s_add_u32 s6, s4, 0x4200
	s_addc_u32 s7, s5, 0
	s_add_u32 s8, s4, 0x4400
	s_addc_u32 s9, s5, 0
	s_waitcnt lgkmcnt(0)
	s_mul_i32 s33, s10, s52
	s_add_u32 s10, s4, 0x4500
	s_mul_i32 s33, s33, s11
	s_addc_u32 s11, s5, 0
	s_add_u32 s12, s4, 0x4600
	s_addc_u32 s13, s5, 0
	s_add_u32 s14, s4, 0x4700
	s_addc_u32 s15, s5, 0
	s_add_u32 s16, s4, 0x4800
	s_addc_u32 s17, s5, 0
	s_add_u32 s18, s4, 0x4900
	s_addc_u32 s19, s5, 0
	s_add_u32 s20, s4, 0x4a00
	s_addc_u32 s21, s5, 0
	s_add_u32 s22, s4, 0x4b00
	s_addc_u32 s23, s5, 0
	s_add_u32 s24, s4, 0x4c00
	s_addc_u32 s25, s5, 0
	s_add_u32 s26, s4, 0x4d00
	s_addc_u32 s27, s5, 0
	s_add_u32 s28, s4, 0x4e00
	s_addc_u32 s29, s5, 0
	s_add_u32 s30, s4, 0x4f00
	s_addc_u32 s31, s5, 0
	s_add_u32 s36, s4, 0x5000
	s_addc_u32 s37, s5, 0
	s_add_u32 s38, s4, 0x5100
	s_addc_u32 s39, s5, 0
	s_add_u32 s40, s4, 0x5200
	s_addc_u32 s41, s5, 0
	s_add_u32 s42, s4, 0x5300
	s_addc_u32 s43, s5, 0
	s_mov_b32 s34, 1
	v_mov_b32_e32 v16, 0
	s_branch .LBB0_140

; #define PG8_STAGE(bufoff, soff, voff) do { _Pragma("unroll") for (int _i = 0; _i < 2; ++_i) \
;         __builtin_amdgcn_raw_ptr_buffer_load_lds(rs_##voff, (PG8_LAS unsigned*)(lds + (bufoff) + ldsw + _i * 8192), 16, (int)(voff)[_i], (int)(soff), 0, 0); } while (0)
; #define PG8_LDA(dst, b, h) do { _Pragma("unroll") for (int m = 0; m < 4; ++m) _Pragma("unroll") for (int k = 0; k < 2; ++k) dst[m][k] = *(const PG8_LAS bf16x8*)(lds + PG8_SA(b, h) + aoff + m * 2048 + k * 1024); } while (0)
; #define PG8_LDB(dst, b, h) do { _Pragma("unroll") for (int n = 0; n < 2; ++n) _Pragma("unroll") for (int k = 0; k < 2; ++k) dst[n][k] = *(const PG8_LAS bf16x8*)(lds + PG8_SB(b, h) + boff + n * 2048 + k * 1024); } while (0)
; #define PG8_MMA(ai, bj, At, Bt) do { __builtin_amdgcn_s_setprio(1); _Pragma("unroll") for (int m = 0; m < 4; ++m) _Pragma("unroll") for (int n = 0; n < 2; ++n) _Pragma("unroll") for (int k = 0; k < 2; ++k) \
;         acc[ai][bj][m][n] = __builtin_amdgcn_mfma_f32_16x16x32_bf16(Bt[n][k], At[m][k], acc[ai][bj][m][n], 0, 0, 0); __builtin_amdgcn_s_setprio(0); } while (0)
; #define PG8_WAIT_V(n) asm volatile("s_waitcnt vmcnt(" #n ")" ::: "memory")
; #define PG8_BAR __builtin_amdgcn_s_barrier()
; template <class Epi, class Sched, bool ALIGN_EPI = false, bool SP2 = false>
; __device__ __forceinline__ void gemm_phase(PG8_LAS unsigned char* lds, const Gemm g, const Sched& S, const Epi& E, const int wid  ) {
;     ...
;         for (int t = 0; t < nt; t += 2) {
;             const bool last = (t == nt - 2);
;             const unsigned a1 = cA + (unsigned)(t + 1) * kstep;
;             const unsigned a2 = last ? nA : cA + (unsigned)(t + 2) * kstep, b2 = last ? nB : cB + (unsigned)(t + 2) * kstep;
;             const unsigned a3 = a2 + kstep, b3 = b2 + kstep;
;             if (last && has_next) S.a_ready(nxt);
;             if constexpr (SP2) {
;             PG8_LDB(B0, 0, 0); PG8_LDB(B1, 0, 1); PG8_SCHED; PG8_LDA(At, 0, 0); PG8_STAGE(PG8_SA(1, 1), a1 + hstep, voffA);
;             PG8_WAIT_V(8); PG8_WAIT_L(0); PG8_BAR; PG8_MMA(0, 0, At, B0); PG8_MMA(0, 1, At, B1); PG8_BAR; PG8_SCHED;
;             PG8_LDA(At, 0, 1); PG8_STAGE(PG8_SB(0, 0), b2, voffB); PG8_STAGE(PG8_SB(0, 1), b2 + hstep, voffB); PG8_STAGE(PG8_SA(0, 0), a2, voffA);
;             PG8_WAIT_V(8); PG8_WAIT_L(0); PG8_BAR; PG8_MMA(1, 0, At, B0); PG8_MMA(1, 1, At, B1); PG8_BAR; PG8_SCHED;
.Lprio_204:
.LBB0_204:
	ds_read_b128 v[132:135], v144
	ds_read_b128 v[150:153], v144 offset:1024
	ds_read_b128 v[154:157], v144 offset:2048
	ds_read_b128 v[158:161], v144 offset:3072
	ds_read_b128 v[162:165], v145
	ds_read_b128 v[166:169], v145 offset:1024
	ds_read_b128 v[170:173], v145 offset:2048
	ds_read_b128 v[174:177], v145 offset:3072
	s_add_i32 s14, s65, 0xfff80080
	s_cmp_eq_u32 s67, 28
	s_cselect_b32 s70, s63, s14
	s_cselect_b32 s69, s64, s66
	s_or_b32 s68, s70, 0x80
	s_mov_b32 m0, s47
	ds_read_b128 v[178:181], v146
	ds_read_b128 v[182:185], v146 offset:1024
	ds_read_b128 v[186:189], v146 offset:2048
	ds_read_b128 v[190:193], v146 offset:3072
	ds_read_b128 v[194:197], v146 offset:4096
	ds_read_b128 v[198:201], v146 offset:5120
	ds_read_b128 v[202:205], v146 offset:6144
	ds_read_b128 v[206:209], v146 offset:7168
	buffer_load_dwordx4 v138, s[8:11], s65 offen lds
	s_mov_b32 m0, s48
	s_nop 0
	buffer_load_dwordx4 v140, s[8:11], s65 offen lds
	s_waitcnt vmcnt(8)
	s_waitcnt lgkmcnt(0)
	s_barrier
	s_waitcnt lgkmcnt(7)
	v_mfma_f32_16x16x32_bf16 v[124:127], v[132:135], v[178:181], v[124:127]
	v_mfma_f32_16x16x32_bf16 v[120:123], v[154:157], v[178:181], v[120:123]
	s_waitcnt lgkmcnt(5)
	v_mfma_f32_16x16x32_bf16 v[112:115], v[132:135], v[186:189], v[112:115]
	v_mfma_f32_16x16x32_bf16 v[104:107], v[154:157], v[186:189], v[104:107]
	s_waitcnt lgkmcnt(3)
	v_mfma_f32_16x16x32_bf16 v[96:99], v[132:135], v[194:197], v[96:99]
	v_mfma_f32_16x16x32_bf16 v[88:91], v[154:157], v[194:197], v[88:91]
	s_waitcnt lgkmcnt(1)
	v_mfma_f32_16x16x32_bf16 v[80:83], v[132:135], v[202:205], v[80:83]
	v_mfma_f32_16x16x32_bf16 v[72:75], v[154:157], v[202:205], v[72:75]
	v_mfma_f32_16x16x32_bf16 v[124:127], v[150:153], v[182:185], v[124:127]
	v_mfma_f32_16x16x32_bf16 v[120:123], v[158:161], v[182:185], v[120:123]
	v_mfma_f32_16x16x32_bf16 v[112:115], v[150:153], v[190:193], v[112:115]
	v_mfma_f32_16x16x32_bf16 v[104:107], v[158:161], v[190:193], v[104:107]
	v_mfma_f32_16x16x32_bf16 v[96:99], v[150:153], v[198:201], v[96:99]
	v_mfma_f32_16x16x32_bf16 v[88:91], v[158:161], v[198:201], v[88:91]
	s_waitcnt lgkmcnt(0)
	v_mfma_f32_16x16x32_bf16 v[80:83], v[150:153], v[206:209], v[80:83]
	v_mfma_f32_16x16x32_bf16 v[72:75], v[158:161], v[206:209], v[72:75]
	v_mfma_f32_16x16x32_bf16 v[116:119], v[162:165], v[178:181], v[116:119]
	v_mfma_f32_16x16x32_bf16 v[108:111], v[170:173], v[178:181], v[108:111]
	v_mfma_f32_16x16x32_bf16 v[100:103], v[162:165], v[186:189], v[100:103]
	v_mfma_f32_16x16x32_bf16 v[92:95], v[170:173], v[186:189], v[92:95]
	v_mfma_f32_16x16x32_bf16 v[84:87], v[162:165], v[194:197], v[84:87]
	v_mfma_f32_16x16x32_bf16 v[76:79], v[170:173], v[194:197], v[76:79]
	v_mfma_f32_16x16x32_bf16 v[68:71], v[162:165], v[202:205], v[68:71]
	v_mfma_f32_16x16x32_bf16 v[64:67], v[170:173], v[202:205], v[64:67]
	v_mfma_f32_16x16x32_bf16 v[116:119], v[166:169], v[182:185], v[116:119]
	v_mfma_f32_16x16x32_bf16 v[108:111], v[174:177], v[182:185], v[108:111]
	v_mfma_f32_16x16x32_bf16 v[100:103], v[166:169], v[190:193], v[100:103]
	v_mfma_f32_16x16x32_bf16 v[92:95], v[174:177], v[190:193], v[92:95]
	v_mfma_f32_16x16x32_bf16 v[84:87], v[166:169], v[198:201], v[84:87]
	v_mfma_f32_16x16x32_bf16 v[76:79], v[174:177], v[198:201], v[76:79]
	v_mfma_f32_16x16x32_bf16 v[68:71], v[166:169], v[206:209], v[68:71]
	v_mfma_f32_16x16x32_bf16 v[64:67], v[174:177], v[206:209], v[64:67]
	s_barrier
	s_mov_b32 m0, s30
	s_mov_b32 s14, s10
	s_mov_b32 s15, s11
	ds_read_b128 v[178:181], v146 offset:16384
	ds_read_b128 v[182:185], v146 offset:17408
	ds_read_b128 v[186:189], v146 offset:18432
	ds_read_b128 v[190:193], v146 offset:19456
	ds_read_b128 v[194:197], v146 offset:20480
	ds_read_b128 v[198:201], v146 offset:21504
	ds_read_b128 v[202:205], v146 offset:22528
	ds_read_b128 v[206:209], v146 offset:23552
	buffer_load_dwordx4 v139, s[12:15], s69 offen lds
	s_mov_b32 m0, s31
	s_add_i32 s71, s69, 0x80000
	buffer_load_dwordx4 v141, s[12:15], s69 offen lds
	s_mov_b32 m0, s33
	s_nop 0
	buffer_load_dwordx4 v139, s[12:15], s71 offen lds
	s_mov_b32 m0, s34
	s_nop 0
	buffer_load_dwordx4 v141, s[12:15], s71 offen lds
	s_mov_b32 m0, s29
	s_nop 0
	buffer_load_dwordx4 v138, s[8:11], s70 offen lds
	s_mov_b32 m0, s35
	s_nop 0
	buffer_load_dwordx4 v140, s[8:11], s70 offen lds
	s_waitcnt vmcnt(8)
	s_waitcnt lgkmcnt(0)
	s_barrier
	s_waitcnt lgkmcnt(7)
	v_mfma_f32_16x16x32_bf16 v[60:63], v[132:135], v[178:181], v[60:63]
	v_mfma_f32_16x16x32_bf16 v[56:59], v[154:157], v[178:181], v[56:59]
	s_waitcnt lgkmcnt(5)
	v_mfma_f32_16x16x32_bf16 v[48:51], v[132:135], v[186:189], v[48:51]
	v_mfma_f32_16x16x32_bf16 v[40:43], v[154:157], v[186:189], v[40:43]
	s_waitcnt lgkmcnt(3)
	v_mfma_f32_16x16x32_bf16 v[32:35], v[132:135], v[194:197], v[32:35]
	v_mfma_f32_16x16x32_bf16 v[24:27], v[154:157], v[194:197], v[24:27]
	s_waitcnt lgkmcnt(1)
	v_mfma_f32_16x16x32_bf16 v[16:19], v[132:135], v[202:205], v[16:19]
	v_mfma_f32_16x16x32_bf16 v[8:11], v[154:157], v[202:205], v[8:11]
	v_mfma_f32_16x16x32_bf16 v[60:63], v[150:153], v[182:185], v[60:63]
	v_mfma_f32_16x16x32_bf16 v[56:59], v[158:161], v[182:185], v[56:59]
	v_mfma_f32_16x16x32_bf16 v[48:51], v[150:153], v[190:193], v[48:51]
	v_mfma_f32_16x16x32_bf16 v[40:43], v[158:161], v[190:193], v[40:43]
	v_mfma_f32_16x16x32_bf16 v[32:35], v[150:153], v[198:201], v[32:35]
	v_mfma_f32_16x16x32_bf16 v[24:27], v[158:161], v[198:201], v[24:27]
	s_waitcnt lgkmcnt(0)
	v_mfma_f32_16x16x32_bf16 v[16:19], v[150:153], v[206:209], v[16:19]
	v_mfma_f32_16x16x32_bf16 v[8:11], v[158:161], v[206:209], v[8:11]
	v_mfma_f32_16x16x32_bf16 v[52:55], v[162:165], v[178:181], v[52:55]
	v_mfma_f32_16x16x32_bf16 v[44:47], v[170:173], v[178:181], v[44:47]
	v_mfma_f32_16x16x32_bf16 v[36:39], v[162:165], v[186:189], v[36:39]
	v_mfma_f32_16x16x32_bf16 v[28:31], v[170:173], v[186:189], v[28:31]
	v_mfma_f32_16x16x32_bf16 v[20:23], v[162:165], v[194:197], v[20:23]
	v_mfma_f32_16x16x32_bf16 v[12:15], v[170:173], v[194:197], v[12:15]
	v_mfma_f32_16x16x32_bf16 v[4:7], v[162:165], v[202:205], v[4:7]
	v_mfma_f32_16x16x32_bf16 v[0:3], v[170:173], v[202:205], v[0:3]
	v_mfma_f32_16x16x32_bf16 v[52:55], v[166:169], v[182:185], v[52:55]
	v_mfma_f32_16x16x32_bf16 v[44:47], v[174:177], v[182:185], v[44:47]
	v_mfma_f32_16x16x32_bf16 v[36:39], v[166:169], v[190:193], v[36:39]
	v_mfma_f32_16x16x32_bf16 v[28:31], v[174:177], v[190:193], v[28:31]
	v_mfma_f32_16x16x32_bf16 v[20:23], v[166:169], v[198:201], v[20:23]
	v_mfma_f32_16x16x32_bf16 v[12:15], v[174:177], v[198:201], v[12:15]
	v_mfma_f32_16x16x32_bf16 v[4:7], v[166:169], v[206:209], v[4:7]
	v_mfma_f32_16x16x32_bf16 v[0:3], v[174:177], v[206:209], v[0:3]
	s_barrier
; #define PG8_STAGE(bufoff, soff, voff) do { _Pragma("unroll") for (int _i = 0; _i < 2; ++_i) \
;         __builtin_amdgcn_raw_ptr_buffer_load_lds(rs_##voff, (PG8_LAS unsigned*)(lds + (bufoff) + ldsw + _i * 8192), 16, (int)(voff)[_i], (int)(soff), 0, 0); } while (0)
; #define PG8_BAR __builtin_amdgcn_s_barrier()
; template <class Epi, class Sched, bool ALIGN_EPI = false, bool SP2 = false>
; __device__ __forceinline__ void gemm_phase(PG8_LAS unsigned char* lds, const Gemm g, const Sched& S, const Epi& E, const int wid  ) {
;     ...
;             PG8_LDB(B0, 1, 0); PG8_LDB(B1, 1, 1); PG8_SCHED; PG8_LDA(At, 1, 0); PG8_STAGE(PG8_SA(0, 1), a2 + hstep, voffA);
;             PG8_WAIT_V(8); PG8_WAIT_L(0); PG8_BAR; PG8_MMA(0, 0, At, B0); PG8_MMA(0, 1, At, B1); PG8_BAR; PG8_SCHED;
;             PG8_LDA(At, 1, 1); PG8_STAGE(PG8_SB(1, 0), b3, voffB); PG8_STAGE(PG8_SB(1, 1), b3 + hstep, voffB); PG8_STAGE(PG8_SA(1, 0), a3, voffA);
;             PG8_WAIT_V(8); PG8_WAIT_L(0); PG8_BAR; PG8_MMA(1, 0, At, B0); PG8_MMA(1, 1, At, B1); PG8_BAR; PG8_SCHED;
;             } else {
;             PG8_LDB(B0, 0, 0); PG8_SCHED; PG8_LDA(At, 0, 0); PG8_STAGE(PG8_SA(1, 1), a1 + hstep, voffA);
;             PG8_WAIT_L(8); PG8_BAR; PG8_WAIT_L(0); PG8_MMA(0, 0, At, B0); PG8_BAR; PG8_SCHED;
;             PG8_LDB(B1, 0, 1); PG8_STAGE(PG8_SB(0, 0), b2, voffB);
;             PG8_BAR; PG8_WAIT_L(0); PG8_MMA(0, 1, At, B1); PG8_BAR;
;             PG8_LDA(At, 0, 1); PG8_STAGE(PG8_SA(0, 0), a2, voffA);
;             PG8_BAR; PG8_WAIT_L(0); PG8_MMA(1, 0, At, B0); PG8_BAR; PG8_SCHED;
;             PG8_STAGE(PG8_SB(0, 1), b2 + hstep, voffB);
;             PG8_WAIT_V(6); PG8_BAR; PG8_MMA(1, 1, At, B1); PG8_BAR;
;             PG8_LDB(B0, 1, 0); PG8_SCHED; PG8_LDA(At, 1, 0); PG8_STAGE(PG8_SA(0, 1), a2 + hstep, voffA);
;             PG8_WAIT_L(8); PG8_BAR; PG8_WAIT_L(0); PG8_MMA(0, 0, At, B0); PG8_BAR; PG8_SCHED;
;             PG8_LDB(B1, 1, 1); PG8_STAGE(PG8_SB(1, 0), b3, voffB);
;             PG8_BAR; PG8_WAIT_L(0); PG8_MMA(0, 1, At, B1); PG8_BAR;
;             PG8_LDA(At, 1, 1); PG8_STAGE(PG8_SA(1, 0), a3, voffA);
;             PG8_BAR; PG8_WAIT_L(0); PG8_MMA(1, 0, At, B0); PG8_BAR; PG8_SCHED;
;             PG8_STAGE(PG8_SB(1, 1), b3 + hstep, voffB);
;             PG8_WAIT_V(6); PG8_BAR; PG8_MMA(1, 1, At, B1); PG8_BAR;
;             }
;         }
;         if constexpr (ALIGN_EPI) { if (wr == 0) PG8_BAR; }
	ds_read_b128 v[132:135], v147
	ds_read_b128 v[150:153], v147 offset:1024
	ds_read_b128 v[154:157], v147 offset:2048
	ds_read_b128 v[158:161], v147 offset:3072
	ds_read_b128 v[162:165], v148
	ds_read_b128 v[166:169], v148 offset:1024
	ds_read_b128 v[170:173], v148 offset:2048
	ds_read_b128 v[174:177], v148 offset:3072
	s_add_i32 s70, s70, 0x80000
	s_mov_b32 m0, s36
	ds_read_b128 v[178:181], v146 offset:32768
	ds_read_b128 v[182:185], v146 offset:33792
	ds_read_b128 v[186:189], v146 offset:34816
	ds_read_b128 v[190:193], v146 offset:35840
	ds_read_b128 v[194:197], v146 offset:36864
	ds_read_b128 v[198:201], v146 offset:37888
	ds_read_b128 v[202:205], v146 offset:38912
	ds_read_b128 v[206:209], v146 offset:39936
	buffer_load_dwordx4 v138, s[8:11], s70 offen lds
	s_mov_b32 m0, s37
	s_nop 0
	buffer_load_dwordx4 v140, s[8:11], s70 offen lds
	s_waitcnt vmcnt(8)
	s_waitcnt lgkmcnt(0)
	s_barrier
	s_waitcnt lgkmcnt(7)
	v_mfma_f32_16x16x32_bf16 v[124:127], v[132:135], v[178:181], v[124:127]
	v_mfma_f32_16x16x32_bf16 v[120:123], v[154:157], v[178:181], v[120:123]
	s_waitcnt lgkmcnt(5)
	v_mfma_f32_16x16x32_bf16 v[112:115], v[132:135], v[186:189], v[112:115]
	v_mfma_f32_16x16x32_bf16 v[104:107], v[154:157], v[186:189], v[104:107]
	s_waitcnt lgkmcnt(3)
	v_mfma_f32_16x16x32_bf16 v[96:99], v[132:135], v[194:197], v[96:99]
	v_mfma_f32_16x16x32_bf16 v[88:91], v[154:157], v[194:197], v[88:91]
	s_waitcnt lgkmcnt(1)
	v_mfma_f32_16x16x32_bf16 v[80:83], v[132:135], v[202:205], v[80:83]
	v_mfma_f32_16x16x32_bf16 v[72:75], v[154:157], v[202:205], v[72:75]
	v_mfma_f32_16x16x32_bf16 v[124:127], v[150:153], v[182:185], v[124:127]
	v_mfma_f32_16x16x32_bf16 v[120:123], v[158:161], v[182:185], v[120:123]
	v_mfma_f32_16x16x32_bf16 v[112:115], v[150:153], v[190:193], v[112:115]
	v_mfma_f32_16x16x32_bf16 v[104:107], v[158:161], v[190:193], v[104:107]
	v_mfma_f32_16x16x32_bf16 v[96:99], v[150:153], v[198:201], v[96:99]
	v_mfma_f32_16x16x32_bf16 v[88:91], v[158:161], v[198:201], v[88:91]
	s_waitcnt lgkmcnt(0)
	v_mfma_f32_16x16x32_bf16 v[80:83], v[150:153], v[206:209], v[80:83]
	v_mfma_f32_16x16x32_bf16 v[72:75], v[158:161], v[206:209], v[72:75]
	v_mfma_f32_16x16x32_bf16 v[116:119], v[162:165], v[178:181], v[116:119]
	v_mfma_f32_16x16x32_bf16 v[108:111], v[170:173], v[178:181], v[108:111]
	v_mfma_f32_16x16x32_bf16 v[100:103], v[162:165], v[186:189], v[100:103]
	v_mfma_f32_16x16x32_bf16 v[92:95], v[170:173], v[186:189], v[92:95]
	v_mfma_f32_16x16x32_bf16 v[84:87], v[162:165], v[194:197], v[84:87]
	v_mfma_f32_16x16x32_bf16 v[76:79], v[170:173], v[194:197], v[76:79]
	v_mfma_f32_16x16x32_bf16 v[68:71], v[162:165], v[202:205], v[68:71]
	v_mfma_f32_16x16x32_bf16 v[64:67], v[170:173], v[202:205], v[64:67]
	v_mfma_f32_16x16x32_bf16 v[116:119], v[166:169], v[182:185], v[116:119]
	v_mfma_f32_16x16x32_bf16 v[108:111], v[174:177], v[182:185], v[108:111]
	v_mfma_f32_16x16x32_bf16 v[100:103], v[166:169], v[190:193], v[100:103]
	v_mfma_f32_16x16x32_bf16 v[92:95], v[174:177], v[190:193], v[92:95]
	v_mfma_f32_16x16x32_bf16 v[84:87], v[166:169], v[198:201], v[84:87]
	v_mfma_f32_16x16x32_bf16 v[76:79], v[174:177], v[198:201], v[76:79]
	v_mfma_f32_16x16x32_bf16 v[68:71], v[166:169], v[206:209], v[68:71]
	v_mfma_f32_16x16x32_bf16 v[64:67], v[174:177], v[206:209], v[64:67]
	s_barrier
	s_mov_b32 m0, s40
	s_or_b32 s70, s69, 0x80
	ds_read_b128 v[178:181], v146 offset:49152
	ds_read_b128 v[182:185], v146 offset:50176
	ds_read_b128 v[186:189], v146 offset:51200
	ds_read_b128 v[190:193], v146 offset:52224
	ds_read_b128 v[194:197], v146 offset:53248
	ds_read_b128 v[198:201], v146 offset:54272
	ds_read_b128 v[202:205], v146 offset:55296
	ds_read_b128 v[206:209], v146 offset:56320
	buffer_load_dwordx4 v139, s[12:15], s70 offen lds
	s_mov_b32 m0, s41
	s_add_i32 s69, s69, 0x80080
	buffer_load_dwordx4 v141, s[12:15], s70 offen lds
	s_mov_b32 m0, s44
	s_nop 0
	buffer_load_dwordx4 v139, s[12:15], s69 offen lds
	s_mov_b32 m0, s45
	s_nop 0
	buffer_load_dwordx4 v141, s[12:15], s69 offen lds
	s_mov_b32 m0, s42
	s_nop 0
	buffer_load_dwordx4 v138, s[8:11], s68 offen lds
	s_mov_b32 m0, s43
	s_nop 0
	buffer_load_dwordx4 v140, s[8:11], s68 offen lds
	s_waitcnt vmcnt(8)
	s_waitcnt lgkmcnt(0)
	s_barrier
	s_waitcnt lgkmcnt(7)
	v_mfma_f32_16x16x32_bf16 v[60:63], v[132:135], v[178:181], v[60:63]
	v_mfma_f32_16x16x32_bf16 v[56:59], v[154:157], v[178:181], v[56:59]
	s_waitcnt lgkmcnt(5)
	v_mfma_f32_16x16x32_bf16 v[48:51], v[132:135], v[186:189], v[48:51]
	v_mfma_f32_16x16x32_bf16 v[40:43], v[154:157], v[186:189], v[40:43]
	s_waitcnt lgkmcnt(3)
	v_mfma_f32_16x16x32_bf16 v[32:35], v[132:135], v[194:197], v[32:35]
	v_mfma_f32_16x16x32_bf16 v[24:27], v[154:157], v[194:197], v[24:27]
	s_waitcnt lgkmcnt(1)
	v_mfma_f32_16x16x32_bf16 v[16:19], v[132:135], v[202:205], v[16:19]
	v_mfma_f32_16x16x32_bf16 v[8:11], v[154:157], v[202:205], v[8:11]
	v_mfma_f32_16x16x32_bf16 v[60:63], v[150:153], v[182:185], v[60:63]
	v_mfma_f32_16x16x32_bf16 v[56:59], v[158:161], v[182:185], v[56:59]
	v_mfma_f32_16x16x32_bf16 v[48:51], v[150:153], v[190:193], v[48:51]
	v_mfma_f32_16x16x32_bf16 v[40:43], v[158:161], v[190:193], v[40:43]
	v_mfma_f32_16x16x32_bf16 v[32:35], v[150:153], v[198:201], v[32:35]
	v_mfma_f32_16x16x32_bf16 v[24:27], v[158:161], v[198:201], v[24:27]
	s_waitcnt lgkmcnt(0)
	v_mfma_f32_16x16x32_bf16 v[16:19], v[150:153], v[206:209], v[16:19]
	v_mfma_f32_16x16x32_bf16 v[8:11], v[158:161], v[206:209], v[8:11]
	v_mfma_f32_16x16x32_bf16 v[52:55], v[162:165], v[178:181], v[52:55]
	v_mfma_f32_16x16x32_bf16 v[44:47], v[170:173], v[178:181], v[44:47]
	v_mfma_f32_16x16x32_bf16 v[36:39], v[162:165], v[186:189], v[36:39]
	v_mfma_f32_16x16x32_bf16 v[28:31], v[170:173], v[186:189], v[28:31]
	v_mfma_f32_16x16x32_bf16 v[20:23], v[162:165], v[194:197], v[20:23]
	v_mfma_f32_16x16x32_bf16 v[12:15], v[170:173], v[194:197], v[12:15]
	v_mfma_f32_16x16x32_bf16 v[4:7], v[162:165], v[202:205], v[4:7]
	v_mfma_f32_16x16x32_bf16 v[0:3], v[170:173], v[202:205], v[0:3]
	v_mfma_f32_16x16x32_bf16 v[52:55], v[166:169], v[182:185], v[52:55]
	v_mfma_f32_16x16x32_bf16 v[44:47], v[174:177], v[182:185], v[44:47]
	v_mfma_f32_16x16x32_bf16 v[36:39], v[166:169], v[190:193], v[36:39]
	v_mfma_f32_16x16x32_bf16 v[28:31], v[174:177], v[190:193], v[28:31]
	v_mfma_f32_16x16x32_bf16 v[20:23], v[166:169], v[198:201], v[20:23]
	v_mfma_f32_16x16x32_bf16 v[12:15], v[174:177], v[198:201], v[12:15]
	v_mfma_f32_16x16x32_bf16 v[4:7], v[166:169], v[206:209], v[4:7]
	v_mfma_f32_16x16x32_bf16 v[0:3], v[174:177], v[206:209], v[0:3]
	s_barrier
	s_add_i32 s67, s67, 2
	s_addk_i32 s65, 0x100
	s_addk_i32 s66, 0x100
	s_cmp_gt_u32 s67, 29
	s_cbranch_scc0 .LBB0_204
	s_and_b64 vcc, exec, s[18:19]
	s_cbranch_vccz .LBB0_207
	s_barrier

; __device__ __forceinline__ unsigned xb_ld(unsigned* p)              { return __hip_atomic_load(p, __ATOMIC_RELAXED, __HIP_MEMORY_SCOPE_AGENT); }
; __device__ __forceinline__ unsigned xb_add(unsigned* p, unsigned v) { return __hip_atomic_fetch_add(p, v, __ATOMIC_RELAXED, __HIP_MEMORY_SCOPE_AGENT); }
; __device__ __forceinline__ void xcd_barrier_complete(unsigned* bar, unsigned x, unsigned& nloc, unsigned& nx) {
;     const unsigned G = gridDim.x * gridDim.y * gridDim.z;
;     unsigned sum, cnt, mine, sp = 0u;
;     for (;;) {
;         sum = 0u; cnt = 0u; mine = 0u;
; #pragma unroll
;         for (unsigned j = 0; j < 16; ++j) { const unsigned c = xb_ld(&bar[XB_XCNT(j)]); sum += c; cnt += (c > 0u) ? 1u : 0u; mine = (j == x) ? c : mine; }
; __device__ __forceinline__ void xcd_barrier(const XcdBarrier& b) {
;     asm volatile("s_waitcnt vmcnt(0)" ::: "memory");
;     __syncthreads();
;     if (threadIdx.x == 0) {
;         unsigned* bar = b.bar;
;         __builtin_amdgcn_s_waitcnt(0);
;         unsigned nloc = b.st[0], nx = b.st[1];
;         if (nloc == 0u) { xcd_barrier_complete(bar, b.x, nloc, nx); b.st[0] = nloc; b.st[1] = nx; }
;         const unsigned old = xb_add(&bar[XB_XSUB(b.x)], 1u);
.LBB0_215:
	s_cmp_lt_i32 s57, 4
	s_cbranch_scc1 .LBB0_269
	s_setprio 0
	s_add_i32 s0, 0, 0x20520
	v_mov_b32_e32 v0, s0
	ds_read_b64 v[0:1], v0
	s_getreg_b32 s3, hwreg(HW_REG_XCC_ID, 0, 4)
	s_waitcnt vmcnt(0)
	s_waitcnt vmcnt(16) lgkmcnt(0)
	s_barrier
	v_readfirstlane_b32 s4, v0
	v_readfirstlane_b32 s5, v1
	s_mov_b64 s[0:1], exec
	v_readlane_b32 s6, v246, 2
	v_readlane_b32 s7, v246, 3
	s_and_b64 s[6:7], s[0:1], s[6:7]
	s_mov_b64 exec, s[6:7]
	s_cbranch_execz .LBB0_268
	s_add_i32 s6, 0, 0x20160
	v_mov_b32_e32 v0, s6
	s_waitcnt vmcnt(0) expcnt(0) lgkmcnt(0)
	ds_read_b32 v2, v0
	s_add_i32 s6, 0, 0x20164
	v_mov_b32_e32 v0, s6
	ds_read_b32 v0, v0
	s_and_b32 s3, s3, 15
	s_waitcnt lgkmcnt(1)
	v_cmp_ne_u32_e32 vcc, 0, v2
	s_cbranch_vccnz .LBB0_232
	v_readlane_b32 s6, v246, 0
	v_readlane_b32 s7, v246, 1
	s_load_dwordx2 s[10:11], s[6:7], 0x4
	s_add_u32 s6, s4, 0x4200
	s_addc_u32 s7, s5, 0
	s_add_u32 s8, s4, 0x4400
	s_addc_u32 s9, s5, 0
	s_waitcnt lgkmcnt(0)
	s_mul_i32 s33, s10, s52
	s_add_u32 s10, s4, 0x4500
	s_mul_i32 s33, s33, s11
	s_addc_u32 s11, s5, 0
	s_add_u32 s12, s4, 0x4600
	s_addc_u32 s13, s5, 0
	s_add_u32 s14, s4, 0x4700
	s_addc_u32 s15, s5, 0
	s_add_u32 s16, s4, 0x4800
	s_addc_u32 s17, s5, 0
	s_add_u32 s18, s4, 0x4900
	s_addc_u32 s19, s5, 0
	s_add_u32 s20, s4, 0x4a00
	s_addc_u32 s21, s5, 0
	s_add_u32 s22, s4, 0x4b00
	s_addc_u32 s23, s5, 0
	s_add_u32 s24, s4, 0x4c00
	s_addc_u32 s25, s5, 0
	s_add_u32 s26, s4, 0x4d00
	s_addc_u32 s27, s5, 0
	s_add_u32 s28, s4, 0x4e00
	s_addc_u32 s29, s5, 0
	s_add_u32 s30, s4, 0x4f00
	s_addc_u32 s31, s5, 0
	s_add_u32 s36, s4, 0x5000
	s_addc_u32 s37, s5, 0
	s_add_u32 s38, s4, 0x5100
	s_addc_u32 s39, s5, 0
	s_add_u32 s40, s4, 0x5200
	s_addc_u32 s41, s5, 0
	s_add_u32 s42, s4, 0x5300
	s_addc_u32 s43, s5, 0
	s_mov_b32 s34, 1
	v_mov_b32_e32 v16, 0
	s_branch .LBB0_220

; __device__ __forceinline__ unsigned xb_ld(unsigned* p)              { return __hip_atomic_load(p, __ATOMIC_RELAXED, __HIP_MEMORY_SCOPE_AGENT); }
; __device__ __forceinline__ unsigned xb_add(unsigned* p, unsigned v) { return __hip_atomic_fetch_add(p, v, __ATOMIC_RELAXED, __HIP_MEMORY_SCOPE_AGENT); }
; __device__ __forceinline__ void xcd_barrier_complete(unsigned* bar, unsigned x, unsigned& nloc, unsigned& nx) {
;     const unsigned G = gridDim.x * gridDim.y * gridDim.z;
;     unsigned sum, cnt, mine, sp = 0u;
;     for (;;) {
;         sum = 0u; cnt = 0u; mine = 0u;
; #pragma unroll
;         for (unsigned j = 0; j < 16; ++j) { const unsigned c = xb_ld(&bar[XB_XCNT(j)]); sum += c; cnt += (c > 0u) ? 1u : 0u; mine = (j == x) ? c : mine; }
; __device__ __forceinline__ void xcd_barrier(const XcdBarrier& b) {
;     asm volatile("s_waitcnt vmcnt(0)" ::: "memory");
;     __syncthreads();
;     if (threadIdx.x == 0) {
;         unsigned* bar = b.bar;
;         __builtin_amdgcn_s_waitcnt(0);
;         unsigned nloc = b.st[0], nx = b.st[1];
;         if (nloc == 0u) { xcd_barrier_complete(bar, b.x, nloc, nx); b.st[0] = nloc; b.st[1] = nx; }
;         const unsigned old = xb_add(&bar[XB_XSUB(b.x)], 1u);
.LBB0_354:
	s_cmp_lt_i32 s57, 5
	v_readlane_b32 s96, v246, 4
	v_readlane_b32 s80, v246, 6
	s_waitcnt vmcnt(16)
	s_barrier
	v_readlane_b32 s97, v246, 5
	s_cbranch_scc1 .LBB0_408
	s_setprio 0
	s_add_i32 s0, 0, 0x20520
	v_mov_b32_e32 v0, s0
	ds_read_b64 v[0:1], v0
	s_getreg_b32 s3, hwreg(HW_REG_XCC_ID, 0, 4)
	s_waitcnt vmcnt(0)
	s_waitcnt lgkmcnt(0)
	s_barrier
	v_readfirstlane_b32 s4, v0
	v_readfirstlane_b32 s5, v1
	s_mov_b64 s[0:1], exec
	v_readlane_b32 s6, v246, 2
	v_readlane_b32 s7, v246, 3
	s_and_b64 s[6:7], s[0:1], s[6:7]
	s_mov_b64 exec, s[6:7]
	s_cbranch_execz .LBB0_407
	s_add_i32 s6, 0, 0x20160
	v_mov_b32_e32 v0, s6
	s_waitcnt vmcnt(0) expcnt(0) lgkmcnt(0)
	ds_read_b32 v2, v0
	s_add_i32 s6, 0, 0x20164
	v_mov_b32_e32 v0, s6
	ds_read_b32 v0, v0
	s_and_b32 s3, s3, 15
	s_waitcnt lgkmcnt(1)
	v_cmp_ne_u32_e32 vcc, 0, v2
	s_cbranch_vccnz .LBB0_371
	v_readlane_b32 s6, v246, 0
	v_readlane_b32 s7, v246, 1
	s_load_dwordx2 s[10:11], s[6:7], 0x4
	s_add_u32 s6, s4, 0x4200
	s_addc_u32 s7, s5, 0
	s_add_u32 s8, s4, 0x4400
	s_addc_u32 s9, s5, 0
	s_waitcnt lgkmcnt(0)
	s_mul_i32 s33, s10, s52
	s_add_u32 s10, s4, 0x4500
	s_mul_i32 s33, s33, s11
	s_addc_u32 s11, s5, 0
	s_add_u32 s12, s4, 0x4600
	s_addc_u32 s13, s5, 0
	s_add_u32 s14, s4, 0x4700
	s_addc_u32 s15, s5, 0
	s_add_u32 s16, s4, 0x4800
	s_addc_u32 s17, s5, 0
	s_add_u32 s18, s4, 0x4900
	s_addc_u32 s19, s5, 0
	s_add_u32 s20, s4, 0x4a00
	s_addc_u32 s21, s5, 0
	s_add_u32 s22, s4, 0x4b00
	s_addc_u32 s23, s5, 0
	s_add_u32 s24, s4, 0x4c00
	s_addc_u32 s25, s5, 0
	s_add_u32 s26, s4, 0x4d00
	s_addc_u32 s27, s5, 0
	s_add_u32 s28, s4, 0x4e00
	s_addc_u32 s29, s5, 0
	s_add_u32 s30, s4, 0x4f00
	s_addc_u32 s31, s5, 0
	s_add_u32 s36, s4, 0x5000
	s_addc_u32 s37, s5, 0
	s_add_u32 s38, s4, 0x5100
	s_addc_u32 s39, s5, 0
	s_add_u32 s40, s4, 0x5200
	s_addc_u32 s41, s5, 0
	s_add_u32 s42, s4, 0x5300
	s_addc_u32 s43, s5, 0
	s_mov_b32 s34, 1
	v_mov_b32_e32 v16, 0
	s_branch .LBB0_359

; __device__ __forceinline__ unsigned xb_ld(unsigned* p)              { return __hip_atomic_load(p, __ATOMIC_RELAXED, __HIP_MEMORY_SCOPE_AGENT); }
; __device__ __forceinline__ unsigned xb_add(unsigned* p, unsigned v) { return __hip_atomic_fetch_add(p, v, __ATOMIC_RELAXED, __HIP_MEMORY_SCOPE_AGENT); }
; __device__ __forceinline__ void xcd_barrier_complete(unsigned* bar, unsigned x, unsigned& nloc, unsigned& nx) {
;     const unsigned G = gridDim.x * gridDim.y * gridDim.z;
;     unsigned sum, cnt, mine, sp = 0u;
;     for (;;) {
;         sum = 0u; cnt = 0u; mine = 0u;
; #pragma unroll
;         for (unsigned j = 0; j < 16; ++j) { const unsigned c = xb_ld(&bar[XB_XCNT(j)]); sum += c; cnt += (c > 0u) ? 1u : 0u; mine = (j == x) ? c : mine; }
; __device__ __forceinline__ void xcd_barrier(const XcdBarrier& b) {
;     asm volatile("s_waitcnt vmcnt(0)" ::: "memory");
;     __syncthreads();
;     if (threadIdx.x == 0) {
;         unsigned* bar = b.bar;
;         __builtin_amdgcn_s_waitcnt(0);
;         unsigned nloc = b.st[0], nx = b.st[1];
;         if (nloc == 0u) { xcd_barrier_complete(bar, b.x, nloc, nx); b.st[0] = nloc; b.st[1] = nx; }
;         const unsigned old = xb_add(&bar[XB_XSUB(b.x)], 1u);
.LBB0_493:
	s_cmp_lt_i32 s57, 6
	v_readlane_b32 s96, v246, 4
	v_readlane_b32 s80, v246, 6
	s_waitcnt vmcnt(16)
	s_barrier
	v_readlane_b32 s97, v246, 5
	s_cbranch_scc1 .LBB0_547
	s_setprio 0
	s_add_i32 s0, 0, 0x20520
	v_mov_b32_e32 v0, s0
	ds_read_b64 v[0:1], v0
	s_getreg_b32 s3, hwreg(HW_REG_XCC_ID, 0, 4)
	s_waitcnt vmcnt(0)
	s_waitcnt lgkmcnt(0)
	s_barrier
	v_readfirstlane_b32 s4, v0
	v_readfirstlane_b32 s5, v1
	s_mov_b64 s[0:1], exec
	v_readlane_b32 s6, v246, 2
	v_readlane_b32 s7, v246, 3
	s_and_b64 s[6:7], s[0:1], s[6:7]
	s_mov_b64 exec, s[6:7]
	s_cbranch_execz .LBB0_546
	s_add_i32 s6, 0, 0x20160
	v_mov_b32_e32 v0, s6
	s_waitcnt vmcnt(0) expcnt(0) lgkmcnt(0)
	ds_read_b32 v2, v0
	s_add_i32 s6, 0, 0x20164
	v_mov_b32_e32 v0, s6
	ds_read_b32 v0, v0
	s_and_b32 s3, s3, 15
	s_waitcnt lgkmcnt(1)
	v_cmp_ne_u32_e32 vcc, 0, v2
	s_cbranch_vccnz .LBB0_510
	v_readlane_b32 s6, v246, 0
	v_readlane_b32 s7, v246, 1
	s_load_dwordx2 s[10:11], s[6:7], 0x4
	s_add_u32 s6, s4, 0x4200
	s_addc_u32 s7, s5, 0
	s_add_u32 s8, s4, 0x4400
	s_addc_u32 s9, s5, 0
	s_waitcnt lgkmcnt(0)
	s_mul_i32 s33, s10, s52
	s_add_u32 s10, s4, 0x4500
	s_mul_i32 s33, s33, s11
	s_addc_u32 s11, s5, 0
	s_add_u32 s12, s4, 0x4600
	s_addc_u32 s13, s5, 0
	s_add_u32 s14, s4, 0x4700
	s_addc_u32 s15, s5, 0
	s_add_u32 s16, s4, 0x4800
	s_addc_u32 s17, s5, 0
	s_add_u32 s18, s4, 0x4900
	s_addc_u32 s19, s5, 0
	s_add_u32 s20, s4, 0x4a00
	s_addc_u32 s21, s5, 0
	s_add_u32 s22, s4, 0x4b00
	s_addc_u32 s23, s5, 0
	s_add_u32 s24, s4, 0x4c00
	s_addc_u32 s25, s5, 0
	s_add_u32 s26, s4, 0x4d00
	s_addc_u32 s27, s5, 0
	s_add_u32 s28, s4, 0x4e00
	s_addc_u32 s29, s5, 0
	s_add_u32 s30, s4, 0x4f00
	s_addc_u32 s31, s5, 0
	s_add_u32 s36, s4, 0x5000
	s_addc_u32 s37, s5, 0
	s_add_u32 s38, s4, 0x5100
	s_addc_u32 s39, s5, 0
	s_add_u32 s40, s4, 0x5200
	s_addc_u32 s41, s5, 0
	s_add_u32 s42, s4, 0x5300
	s_addc_u32 s43, s5, 0
	s_mov_b32 s34, 1
	v_mov_b32_e32 v16, 0
	s_branch .LBB0_498

; #define PG8_STAGE(bufoff, soff, voff) do { _Pragma("unroll") for (int _i = 0; _i < 2; ++_i) \
;         __builtin_amdgcn_raw_ptr_buffer_load_lds(rs_##voff, (PG8_LAS unsigned*)(lds + (bufoff) + ldsw + _i * 8192), 16, (int)(voff)[_i], (int)(soff), 0, 0); } while (0)
; #define PG8_LDA(dst, b, h) do { _Pragma("unroll") for (int m = 0; m < 4; ++m) _Pragma("unroll") for (int k = 0; k < 2; ++k) dst[m][k] = *(const PG8_LAS bf16x8*)(lds + PG8_SA(b, h) + aoff + m * 2048 + k * 1024); } while (0)
; #define PG8_LDB(dst, b, h) do { _Pragma("unroll") for (int n = 0; n < 2; ++n) _Pragma("unroll") for (int k = 0; k < 2; ++k) dst[n][k] = *(const PG8_LAS bf16x8*)(lds + PG8_SB(b, h) + boff + n * 2048 + k * 1024); } while (0)
; #define PG8_MMA(ai, bj, At, Bt) do { __builtin_amdgcn_s_setprio(1); _Pragma("unroll") for (int m = 0; m < 4; ++m) _Pragma("unroll") for (int n = 0; n < 2; ++n) _Pragma("unroll") for (int k = 0; k < 2; ++k) \
;         acc[ai][bj][m][n] = __builtin_amdgcn_mfma_f32_16x16x32_bf16(Bt[n][k], At[m][k], acc[ai][bj][m][n], 0, 0, 0); __builtin_amdgcn_s_setprio(0); } while (0)
; #define PG8_WAIT_V(n) asm volatile("s_waitcnt vmcnt(" #n ")" ::: "memory")
; #define PG8_BAR __builtin_amdgcn_s_barrier()
; template <class Epi, class Sched, bool ALIGN_EPI = false, bool SP2 = false>
; __device__ __forceinline__ void gemm_phase(PG8_LAS unsigned char* lds, const Gemm g, const Sched& S, const Epi& E, const int wid  ) {
;     ...
;         for (int t = 0; t < nt; t += 2) {
;             const bool last = (t == nt - 2);
;             const unsigned a1 = cA + (unsigned)(t + 1) * kstep;
;             const unsigned a2 = last ? nA : cA + (unsigned)(t + 2) * kstep, b2 = last ? nB : cB + (unsigned)(t + 2) * kstep;
;             const unsigned a3 = a2 + kstep, b3 = b2 + kstep;
;             if (last && has_next) S.a_ready(nxt);
;             if constexpr (SP2) {
;             PG8_LDB(B0, 0, 0); PG8_LDB(B1, 0, 1); PG8_SCHED; PG8_LDA(At, 0, 0); PG8_STAGE(PG8_SA(1, 1), a1 + hstep, voffA);
;             PG8_WAIT_V(8); PG8_WAIT_L(0); PG8_BAR; PG8_MMA(0, 0, At, B0); PG8_MMA(0, 1, At, B1); PG8_BAR; PG8_SCHED;
;             PG8_LDA(At, 0, 1); PG8_STAGE(PG8_SB(0, 0), b2, voffB); PG8_STAGE(PG8_SB(0, 1), b2 + hstep, voffB); PG8_STAGE(PG8_SA(0, 0), a2, voffA);
;             PG8_WAIT_V(8); PG8_WAIT_L(0); PG8_BAR; PG8_MMA(1, 0, At, B0); PG8_MMA(1, 1, At, B1); PG8_BAR; PG8_SCHED;
.Lprio_564:
.LBB0_564:
	ds_read_b128 v[132:135], v140
	ds_read_b128 v[146:149], v140 offset:1024
	ds_read_b128 v[150:153], v140 offset:2048
	ds_read_b128 v[154:157], v140 offset:3072
	ds_read_b128 v[158:161], v141
	ds_read_b128 v[162:165], v141 offset:1024
	ds_read_b128 v[166:169], v141 offset:2048
	ds_read_b128 v[170:173], v141 offset:3072
	s_add_i32 s14, s54, 0xfff80080
	s_cmp_eq_u32 s58, 28
	s_cselect_b32 s61, s0, s14
	s_cselect_b32 s60, s1, s55
	s_or_b32 s59, s61, 0x80
	s_mov_b32 m0, s43
	ds_read_b128 v[174:177], v142
	ds_read_b128 v[178:181], v142 offset:1024
	ds_read_b128 v[182:185], v142 offset:2048
	ds_read_b128 v[186:189], v142 offset:3072
	ds_read_b128 v[190:193], v142 offset:4096
	ds_read_b128 v[194:197], v142 offset:5120
	ds_read_b128 v[198:201], v142 offset:6144
	ds_read_b128 v[202:205], v142 offset:7168
	buffer_load_dwordx4 v136, s[8:11], s54 offen lds
	s_mov_b32 m0, s44
	s_nop 0
	buffer_load_dwordx4 v138, s[8:11], s54 offen lds
	s_waitcnt vmcnt(8)
	s_waitcnt lgkmcnt(0)
	s_barrier
	s_waitcnt lgkmcnt(7)
	v_mfma_f32_16x16x32_bf16 v[124:127], v[132:135], v[174:177], v[124:127]
	v_mfma_f32_16x16x32_bf16 v[120:123], v[150:153], v[174:177], v[120:123]
	s_waitcnt lgkmcnt(5)
	v_mfma_f32_16x16x32_bf16 v[108:111], v[132:135], v[182:185], v[108:111]
	v_mfma_f32_16x16x32_bf16 v[104:107], v[150:153], v[182:185], v[104:107]
	s_waitcnt lgkmcnt(3)
	v_mfma_f32_16x16x32_bf16 v[92:95], v[132:135], v[190:193], v[92:95]
	v_mfma_f32_16x16x32_bf16 v[88:91], v[150:153], v[190:193], v[88:91]
	s_waitcnt lgkmcnt(1)
	v_mfma_f32_16x16x32_bf16 v[76:79], v[132:135], v[198:201], v[76:79]
	v_mfma_f32_16x16x32_bf16 v[72:75], v[150:153], v[198:201], v[72:75]
	v_mfma_f32_16x16x32_bf16 v[124:127], v[146:149], v[178:181], v[124:127]
	v_mfma_f32_16x16x32_bf16 v[120:123], v[154:157], v[178:181], v[120:123]
	v_mfma_f32_16x16x32_bf16 v[108:111], v[146:149], v[186:189], v[108:111]
	v_mfma_f32_16x16x32_bf16 v[104:107], v[154:157], v[186:189], v[104:107]
	v_mfma_f32_16x16x32_bf16 v[92:95], v[146:149], v[194:197], v[92:95]
	v_mfma_f32_16x16x32_bf16 v[88:91], v[154:157], v[194:197], v[88:91]
	s_waitcnt lgkmcnt(0)
	v_mfma_f32_16x16x32_bf16 v[76:79], v[146:149], v[202:205], v[76:79]
	v_mfma_f32_16x16x32_bf16 v[72:75], v[154:157], v[202:205], v[72:75]
	v_mfma_f32_16x16x32_bf16 v[116:119], v[158:161], v[174:177], v[116:119]
	v_mfma_f32_16x16x32_bf16 v[112:115], v[166:169], v[174:177], v[112:115]
	v_mfma_f32_16x16x32_bf16 v[100:103], v[158:161], v[182:185], v[100:103]
	v_mfma_f32_16x16x32_bf16 v[96:99], v[166:169], v[182:185], v[96:99]
	v_mfma_f32_16x16x32_bf16 v[84:87], v[158:161], v[190:193], v[84:87]
	v_mfma_f32_16x16x32_bf16 v[80:83], v[166:169], v[190:193], v[80:83]
	v_mfma_f32_16x16x32_bf16 v[68:71], v[158:161], v[198:201], v[68:71]
	v_mfma_f32_16x16x32_bf16 v[64:67], v[166:169], v[198:201], v[64:67]
	v_mfma_f32_16x16x32_bf16 v[116:119], v[162:165], v[178:181], v[116:119]
	v_mfma_f32_16x16x32_bf16 v[112:115], v[170:173], v[178:181], v[112:115]
	v_mfma_f32_16x16x32_bf16 v[100:103], v[162:165], v[186:189], v[100:103]
	v_mfma_f32_16x16x32_bf16 v[96:99], v[170:173], v[186:189], v[96:99]
	v_mfma_f32_16x16x32_bf16 v[84:87], v[162:165], v[194:197], v[84:87]
	v_mfma_f32_16x16x32_bf16 v[80:83], v[170:173], v[194:197], v[80:83]
	v_mfma_f32_16x16x32_bf16 v[68:71], v[162:165], v[202:205], v[68:71]
	v_mfma_f32_16x16x32_bf16 v[64:67], v[170:173], v[202:205], v[64:67]
	s_barrier
	s_mov_b32 m0, s26
	s_mov_b32 s14, s10
	s_mov_b32 s15, s11
	ds_read_b128 v[174:177], v142 offset:16384
	ds_read_b128 v[178:181], v142 offset:17408
	ds_read_b128 v[182:185], v142 offset:18432
	ds_read_b128 v[186:189], v142 offset:19456
	ds_read_b128 v[190:193], v142 offset:20480
	ds_read_b128 v[194:197], v142 offset:21504
	ds_read_b128 v[198:201], v142 offset:22528
	ds_read_b128 v[202:205], v142 offset:23552
	buffer_load_dwordx4 v137, s[12:15], s60 offen lds
	s_mov_b32 m0, s27
	s_add_i32 s62, s60, 0x80000
	buffer_load_dwordx4 v139, s[12:15], s60 offen lds
	s_mov_b32 m0, s28
	s_nop 0
	buffer_load_dwordx4 v137, s[12:15], s62 offen lds
	s_mov_b32 m0, s29
	s_nop 0
	buffer_load_dwordx4 v139, s[12:15], s62 offen lds
	s_mov_b32 m0, s3
	s_nop 0
	buffer_load_dwordx4 v136, s[8:11], s61 offen lds
	s_mov_b32 m0, s30
	s_nop 0
	buffer_load_dwordx4 v138, s[8:11], s61 offen lds
	s_waitcnt vmcnt(8)
	s_waitcnt lgkmcnt(0)
	s_barrier
	s_waitcnt lgkmcnt(7)
	v_mfma_f32_16x16x32_bf16 v[60:63], v[132:135], v[174:177], v[60:63]
	v_mfma_f32_16x16x32_bf16 v[56:59], v[150:153], v[174:177], v[56:59]
	s_waitcnt lgkmcnt(5)
	v_mfma_f32_16x16x32_bf16 v[44:47], v[132:135], v[182:185], v[44:47]
	v_mfma_f32_16x16x32_bf16 v[40:43], v[150:153], v[182:185], v[40:43]
	s_waitcnt lgkmcnt(3)
	v_mfma_f32_16x16x32_bf16 v[28:31], v[132:135], v[190:193], v[28:31]
	v_mfma_f32_16x16x32_bf16 v[24:27], v[150:153], v[190:193], v[24:27]
	s_waitcnt lgkmcnt(1)
	v_mfma_f32_16x16x32_bf16 v[12:15], v[132:135], v[198:201], v[12:15]
	v_mfma_f32_16x16x32_bf16 v[8:11], v[150:153], v[198:201], v[8:11]
	v_mfma_f32_16x16x32_bf16 v[60:63], v[146:149], v[178:181], v[60:63]
	v_mfma_f32_16x16x32_bf16 v[56:59], v[154:157], v[178:181], v[56:59]
	v_mfma_f32_16x16x32_bf16 v[44:47], v[146:149], v[186:189], v[44:47]
	v_mfma_f32_16x16x32_bf16 v[40:43], v[154:157], v[186:189], v[40:43]
	v_mfma_f32_16x16x32_bf16 v[28:31], v[146:149], v[194:197], v[28:31]
	v_mfma_f32_16x16x32_bf16 v[24:27], v[154:157], v[194:197], v[24:27]
	s_waitcnt lgkmcnt(0)
	v_mfma_f32_16x16x32_bf16 v[12:15], v[146:149], v[202:205], v[12:15]
	v_mfma_f32_16x16x32_bf16 v[8:11], v[154:157], v[202:205], v[8:11]
	v_mfma_f32_16x16x32_bf16 v[52:55], v[158:161], v[174:177], v[52:55]
	v_mfma_f32_16x16x32_bf16 v[48:51], v[166:169], v[174:177], v[48:51]
	v_mfma_f32_16x16x32_bf16 v[36:39], v[158:161], v[182:185], v[36:39]
	v_mfma_f32_16x16x32_bf16 v[32:35], v[166:169], v[182:185], v[32:35]
	v_mfma_f32_16x16x32_bf16 v[20:23], v[158:161], v[190:193], v[20:23]
	v_mfma_f32_16x16x32_bf16 v[16:19], v[166:169], v[190:193], v[16:19]
	v_mfma_f32_16x16x32_bf16 v[4:7], v[158:161], v[198:201], v[4:7]
	v_mfma_f32_16x16x32_bf16 v[0:3], v[166:169], v[198:201], v[0:3]
	v_mfma_f32_16x16x32_bf16 v[52:55], v[162:165], v[178:181], v[52:55]
	v_mfma_f32_16x16x32_bf16 v[48:51], v[170:173], v[178:181], v[48:51]
	v_mfma_f32_16x16x32_bf16 v[36:39], v[162:165], v[186:189], v[36:39]
	v_mfma_f32_16x16x32_bf16 v[32:35], v[170:173], v[186:189], v[32:35]
	v_mfma_f32_16x16x32_bf16 v[20:23], v[162:165], v[194:197], v[20:23]
	v_mfma_f32_16x16x32_bf16 v[16:19], v[170:173], v[194:197], v[16:19]
	v_mfma_f32_16x16x32_bf16 v[4:7], v[162:165], v[202:205], v[4:7]
	v_mfma_f32_16x16x32_bf16 v[0:3], v[170:173], v[202:205], v[0:3]
	s_barrier
; #define PG8_STAGE(bufoff, soff, voff) do { _Pragma("unroll") for (int _i = 0; _i < 2; ++_i) \
;         __builtin_amdgcn_raw_ptr_buffer_load_lds(rs_##voff, (PG8_LAS unsigned*)(lds + (bufoff) + ldsw + _i * 8192), 16, (int)(voff)[_i], (int)(soff), 0, 0); } while (0)
; #define PG8_BAR __builtin_amdgcn_s_barrier()
; template <class Epi, class Sched, bool ALIGN_EPI = false, bool SP2 = false>
; __device__ __forceinline__ void gemm_phase(PG8_LAS unsigned char* lds, const Gemm g, const Sched& S, const Epi& E, const int wid  ) {
;     ...
;             PG8_LDB(B0, 1, 0); PG8_LDB(B1, 1, 1); PG8_SCHED; PG8_LDA(At, 1, 0); PG8_STAGE(PG8_SA(0, 1), a2 + hstep, voffA);
;             PG8_WAIT_V(8); PG8_WAIT_L(0); PG8_BAR; PG8_MMA(0, 0, At, B0); PG8_MMA(0, 1, At, B1); PG8_BAR; PG8_SCHED;
;             PG8_LDA(At, 1, 1); PG8_STAGE(PG8_SB(1, 0), b3, voffB); PG8_STAGE(PG8_SB(1, 1), b3 + hstep, voffB); PG8_STAGE(PG8_SA(1, 0), a3, voffA);
;             PG8_WAIT_V(8); PG8_WAIT_L(0); PG8_BAR; PG8_MMA(1, 0, At, B0); PG8_MMA(1, 1, At, B1); PG8_BAR; PG8_SCHED;
;             } else {
;             PG8_LDB(B0, 0, 0); PG8_SCHED; PG8_LDA(At, 0, 0); PG8_STAGE(PG8_SA(1, 1), a1 + hstep, voffA);
;             PG8_WAIT_L(8); PG8_BAR; PG8_WAIT_L(0); PG8_MMA(0, 0, At, B0); PG8_BAR; PG8_SCHED;
;             PG8_LDB(B1, 0, 1); PG8_STAGE(PG8_SB(0, 0), b2, voffB);
;             PG8_BAR; PG8_WAIT_L(0); PG8_MMA(0, 1, At, B1); PG8_BAR;
;             PG8_LDA(At, 0, 1); PG8_STAGE(PG8_SA(0, 0), a2, voffA);
;             PG8_BAR; PG8_WAIT_L(0); PG8_MMA(1, 0, At, B0); PG8_BAR; PG8_SCHED;
;             PG8_STAGE(PG8_SB(0, 1), b2 + hstep, voffB);
;             PG8_WAIT_V(6); PG8_BAR; PG8_MMA(1, 1, At, B1); PG8_BAR;
;             PG8_LDB(B0, 1, 0); PG8_SCHED; PG8_LDA(At, 1, 0); PG8_STAGE(PG8_SA(0, 1), a2 + hstep, voffA);
;             PG8_WAIT_L(8); PG8_BAR; PG8_WAIT_L(0); PG8_MMA(0, 0, At, B0); PG8_BAR; PG8_SCHED;
;             PG8_LDB(B1, 1, 1); PG8_STAGE(PG8_SB(1, 0), b3, voffB);
;             PG8_BAR; PG8_WAIT_L(0); PG8_MMA(0, 1, At, B1); PG8_BAR;
;             PG8_LDA(At, 1, 1); PG8_STAGE(PG8_SA(1, 0), a3, voffA);
;             PG8_BAR; PG8_WAIT_L(0); PG8_MMA(1, 0, At, B0); PG8_BAR; PG8_SCHED;
;             PG8_STAGE(PG8_SB(1, 1), b3 + hstep, voffB);
;             PG8_WAIT_V(6); PG8_BAR; PG8_MMA(1, 1, At, B1); PG8_BAR;
;             }
;         }
;         if constexpr (ALIGN_EPI) { if (wr == 0) PG8_BAR; }
	ds_read_b128 v[132:135], v143
	ds_read_b128 v[146:149], v143 offset:1024
	ds_read_b128 v[150:153], v143 offset:2048
	ds_read_b128 v[154:157], v143 offset:3072
	ds_read_b128 v[158:161], v144
	ds_read_b128 v[162:165], v144 offset:1024
	ds_read_b128 v[166:169], v144 offset:2048
	ds_read_b128 v[170:173], v144 offset:3072
	s_add_i32 s61, s61, 0x80000
	s_mov_b32 m0, s31
	ds_read_b128 v[174:177], v142 offset:32768
	ds_read_b128 v[178:181], v142 offset:33792
	ds_read_b128 v[182:185], v142 offset:34816
	ds_read_b128 v[186:189], v142 offset:35840
	ds_read_b128 v[190:193], v142 offset:36864
	ds_read_b128 v[194:197], v142 offset:37888
	ds_read_b128 v[198:201], v142 offset:38912
	ds_read_b128 v[202:205], v142 offset:39936
	buffer_load_dwordx4 v136, s[8:11], s61 offen lds
	s_mov_b32 m0, s33
	s_nop 0
	buffer_load_dwordx4 v138, s[8:11], s61 offen lds
	s_waitcnt vmcnt(8)
	s_waitcnt lgkmcnt(0)
	s_barrier
	s_waitcnt lgkmcnt(7)
	v_mfma_f32_16x16x32_bf16 v[124:127], v[132:135], v[174:177], v[124:127]
	v_mfma_f32_16x16x32_bf16 v[120:123], v[150:153], v[174:177], v[120:123]
	s_waitcnt lgkmcnt(5)
	v_mfma_f32_16x16x32_bf16 v[108:111], v[132:135], v[182:185], v[108:111]
	v_mfma_f32_16x16x32_bf16 v[104:107], v[150:153], v[182:185], v[104:107]
	s_waitcnt lgkmcnt(3)
	v_mfma_f32_16x16x32_bf16 v[92:95], v[132:135], v[190:193], v[92:95]
	v_mfma_f32_16x16x32_bf16 v[88:91], v[150:153], v[190:193], v[88:91]
	s_waitcnt lgkmcnt(1)
	v_mfma_f32_16x16x32_bf16 v[76:79], v[132:135], v[198:201], v[76:79]
	v_mfma_f32_16x16x32_bf16 v[72:75], v[150:153], v[198:201], v[72:75]
	v_mfma_f32_16x16x32_bf16 v[124:127], v[146:149], v[178:181], v[124:127]
	v_mfma_f32_16x16x32_bf16 v[120:123], v[154:157], v[178:181], v[120:123]
	v_mfma_f32_16x16x32_bf16 v[108:111], v[146:149], v[186:189], v[108:111]
	v_mfma_f32_16x16x32_bf16 v[104:107], v[154:157], v[186:189], v[104:107]
	v_mfma_f32_16x16x32_bf16 v[92:95], v[146:149], v[194:197], v[92:95]
	v_mfma_f32_16x16x32_bf16 v[88:91], v[154:157], v[194:197], v[88:91]
	s_waitcnt lgkmcnt(0)
	v_mfma_f32_16x16x32_bf16 v[76:79], v[146:149], v[202:205], v[76:79]
	v_mfma_f32_16x16x32_bf16 v[72:75], v[154:157], v[202:205], v[72:75]
	v_mfma_f32_16x16x32_bf16 v[116:119], v[158:161], v[174:177], v[116:119]
	v_mfma_f32_16x16x32_bf16 v[112:115], v[166:169], v[174:177], v[112:115]
	v_mfma_f32_16x16x32_bf16 v[100:103], v[158:161], v[182:185], v[100:103]
	v_mfma_f32_16x16x32_bf16 v[96:99], v[166:169], v[182:185], v[96:99]
	v_mfma_f32_16x16x32_bf16 v[84:87], v[158:161], v[190:193], v[84:87]
	v_mfma_f32_16x16x32_bf16 v[80:83], v[166:169], v[190:193], v[80:83]
	v_mfma_f32_16x16x32_bf16 v[68:71], v[158:161], v[198:201], v[68:71]
	v_mfma_f32_16x16x32_bf16 v[64:67], v[166:169], v[198:201], v[64:67]
	v_mfma_f32_16x16x32_bf16 v[116:119], v[162:165], v[178:181], v[116:119]
	v_mfma_f32_16x16x32_bf16 v[112:115], v[170:173], v[178:181], v[112:115]
	v_mfma_f32_16x16x32_bf16 v[100:103], v[162:165], v[186:189], v[100:103]
	v_mfma_f32_16x16x32_bf16 v[96:99], v[170:173], v[186:189], v[96:99]
	v_mfma_f32_16x16x32_bf16 v[84:87], v[162:165], v[194:197], v[84:87]
	v_mfma_f32_16x16x32_bf16 v[80:83], v[170:173], v[194:197], v[80:83]
	v_mfma_f32_16x16x32_bf16 v[68:71], v[162:165], v[202:205], v[68:71]
	v_mfma_f32_16x16x32_bf16 v[64:67], v[170:173], v[202:205], v[64:67]
	s_barrier
	s_mov_b32 m0, s34
	s_or_b32 s61, s60, 0x80
	ds_read_b128 v[174:177], v142 offset:49152
	ds_read_b128 v[178:181], v142 offset:50176
	ds_read_b128 v[182:185], v142 offset:51200
	ds_read_b128 v[186:189], v142 offset:52224
	ds_read_b128 v[190:193], v142 offset:53248
	ds_read_b128 v[194:197], v142 offset:54272
	ds_read_b128 v[198:201], v142 offset:55296
	ds_read_b128 v[202:205], v142 offset:56320
	buffer_load_dwordx4 v137, s[12:15], s61 offen lds
	s_mov_b32 m0, s35
	s_add_i32 s60, s60, 0x80080
	buffer_load_dwordx4 v139, s[12:15], s61 offen lds
	s_mov_b32 m0, s38
	s_nop 0
	buffer_load_dwordx4 v137, s[12:15], s60 offen lds
	s_mov_b32 m0, s39
	s_nop 0
	buffer_load_dwordx4 v139, s[12:15], s60 offen lds
	s_mov_b32 m0, s36
	s_nop 0
	buffer_load_dwordx4 v136, s[8:11], s59 offen lds
	s_mov_b32 m0, s37
	s_nop 0
	buffer_load_dwordx4 v138, s[8:11], s59 offen lds
	s_waitcnt vmcnt(8)
	s_waitcnt lgkmcnt(0)
	s_barrier
	s_waitcnt lgkmcnt(7)
	v_mfma_f32_16x16x32_bf16 v[60:63], v[132:135], v[174:177], v[60:63]
	v_mfma_f32_16x16x32_bf16 v[56:59], v[150:153], v[174:177], v[56:59]
	s_waitcnt lgkmcnt(5)
	v_mfma_f32_16x16x32_bf16 v[44:47], v[132:135], v[182:185], v[44:47]
	v_mfma_f32_16x16x32_bf16 v[40:43], v[150:153], v[182:185], v[40:43]
	s_waitcnt lgkmcnt(3)
	v_mfma_f32_16x16x32_bf16 v[28:31], v[132:135], v[190:193], v[28:31]
	v_mfma_f32_16x16x32_bf16 v[24:27], v[150:153], v[190:193], v[24:27]
	s_waitcnt lgkmcnt(1)
	v_mfma_f32_16x16x32_bf16 v[12:15], v[132:135], v[198:201], v[12:15]
	v_mfma_f32_16x16x32_bf16 v[8:11], v[150:153], v[198:201], v[8:11]
	v_mfma_f32_16x16x32_bf16 v[60:63], v[146:149], v[178:181], v[60:63]
	v_mfma_f32_16x16x32_bf16 v[56:59], v[154:157], v[178:181], v[56:59]
	v_mfma_f32_16x16x32_bf16 v[44:47], v[146:149], v[186:189], v[44:47]
	v_mfma_f32_16x16x32_bf16 v[40:43], v[154:157], v[186:189], v[40:43]
	v_mfma_f32_16x16x32_bf16 v[28:31], v[146:149], v[194:197], v[28:31]
	v_mfma_f32_16x16x32_bf16 v[24:27], v[154:157], v[194:197], v[24:27]
	s_waitcnt lgkmcnt(0)
	v_mfma_f32_16x16x32_bf16 v[12:15], v[146:149], v[202:205], v[12:15]
	v_mfma_f32_16x16x32_bf16 v[8:11], v[154:157], v[202:205], v[8:11]
	v_mfma_f32_16x16x32_bf16 v[52:55], v[158:161], v[174:177], v[52:55]
	v_mfma_f32_16x16x32_bf16 v[48:51], v[166:169], v[174:177], v[48:51]
	v_mfma_f32_16x16x32_bf16 v[36:39], v[158:161], v[182:185], v[36:39]
	v_mfma_f32_16x16x32_bf16 v[32:35], v[166:169], v[182:185], v[32:35]
	v_mfma_f32_16x16x32_bf16 v[20:23], v[158:161], v[190:193], v[20:23]
	v_mfma_f32_16x16x32_bf16 v[16:19], v[166:169], v[190:193], v[16:19]
	v_mfma_f32_16x16x32_bf16 v[4:7], v[158:161], v[198:201], v[4:7]
	v_mfma_f32_16x16x32_bf16 v[0:3], v[166:169], v[198:201], v[0:3]
	v_mfma_f32_16x16x32_bf16 v[52:55], v[162:165], v[178:181], v[52:55]
	v_mfma_f32_16x16x32_bf16 v[48:51], v[170:173], v[178:181], v[48:51]
	v_mfma_f32_16x16x32_bf16 v[36:39], v[162:165], v[186:189], v[36:39]
	v_mfma_f32_16x16x32_bf16 v[32:35], v[170:173], v[186:189], v[32:35]
	v_mfma_f32_16x16x32_bf16 v[20:23], v[162:165], v[194:197], v[20:23]
	v_mfma_f32_16x16x32_bf16 v[16:19], v[170:173], v[194:197], v[16:19]
	v_mfma_f32_16x16x32_bf16 v[4:7], v[162:165], v[202:205], v[4:7]
	v_mfma_f32_16x16x32_bf16 v[0:3], v[170:173], v[202:205], v[0:3]
	s_barrier
	s_add_i32 s58, s58, 2
	s_addk_i32 s54, 0x100
	s_addk_i32 s55, 0x100
	s_cmp_gt_u32 s58, 29
	s_cbranch_scc0 .LBB0_564
	s_and_b64 vcc, exec, s[24:25]
	s_cbranch_vccz .LBB0_567
	s_barrier

; __device__ __forceinline__ unsigned xb_ld(unsigned* p)              { return __hip_atomic_load(p, __ATOMIC_RELAXED, __HIP_MEMORY_SCOPE_AGENT); }
; __device__ __forceinline__ unsigned xb_add(unsigned* p, unsigned v) { return __hip_atomic_fetch_add(p, v, __ATOMIC_RELAXED, __HIP_MEMORY_SCOPE_AGENT); }
; __device__ __forceinline__ void xcd_barrier_complete(unsigned* bar, unsigned x, unsigned& nloc, unsigned& nx) {
;     const unsigned G = gridDim.x * gridDim.y * gridDim.z;
;     unsigned sum, cnt, mine, sp = 0u;
;     for (;;) {
;         sum = 0u; cnt = 0u; mine = 0u;
; #pragma unroll
;         for (unsigned j = 0; j < 16; ++j) { const unsigned c = xb_ld(&bar[XB_XCNT(j)]); sum += c; cnt += (c > 0u) ? 1u : 0u; mine = (j == x) ? c : mine; }
; __device__ __forceinline__ void xcd_barrier(const XcdBarrier& b) {
;     asm volatile("s_waitcnt vmcnt(0)" ::: "memory");
;     __syncthreads();
;     if (threadIdx.x == 0) {
;         unsigned* bar = b.bar;
;         __builtin_amdgcn_s_waitcnt(0);
;         unsigned nloc = b.st[0], nx = b.st[1];
;         if (nloc == 0u) { xcd_barrier_complete(bar, b.x, nloc, nx); b.st[0] = nloc; b.st[1] = nx; }
;         const unsigned old = xb_add(&bar[XB_XSUB(b.x)], 1u);
.LBB0_591:
	s_setprio 0
	s_add_i32 s0, 0, 0x20520
	v_mov_b32_e32 v0, s0
	s_waitcnt lgkmcnt(0)
	ds_read_b64 v[0:1], v0
	s_getreg_b32 s3, hwreg(HW_REG_XCC_ID, 0, 4)
	s_waitcnt vmcnt(0)
	s_waitcnt vmcnt(16) lgkmcnt(0)
	s_barrier
	v_readfirstlane_b32 s4, v0
	v_readfirstlane_b32 s5, v1
	s_mov_b64 s[0:1], exec
	v_readlane_b32 s6, v246, 2
	v_readlane_b32 s7, v246, 3
	s_and_b64 s[6:7], s[0:1], s[6:7]
	s_mov_b64 exec, s[6:7]
	s_cbranch_execz .LBB0_643
	s_add_i32 s6, 0, 0x20160
	v_mov_b32_e32 v0, s6
	s_waitcnt vmcnt(0) expcnt(0) lgkmcnt(0)
	ds_read_b32 v2, v0
	s_add_i32 s6, 0, 0x20164
	v_mov_b32_e32 v0, s6
	ds_read_b32 v0, v0
	s_and_b32 s3, s3, 15
	s_waitcnt lgkmcnt(1)
	v_cmp_ne_u32_e32 vcc, 0, v2
	s_cbranch_vccnz .LBB0_607
	v_readlane_b32 s6, v246, 0
	v_readlane_b32 s7, v246, 1
	s_load_dwordx2 s[10:11], s[6:7], 0x4
	s_add_u32 s6, s4, 0x4200
	s_addc_u32 s7, s5, 0
	s_add_u32 s8, s4, 0x4400
	s_addc_u32 s9, s5, 0
	s_waitcnt lgkmcnt(0)
	s_mul_i32 s33, s10, s52
	s_add_u32 s10, s4, 0x4500
	s_mul_i32 s33, s33, s11
	s_addc_u32 s11, s5, 0
	s_add_u32 s12, s4, 0x4600
	s_addc_u32 s13, s5, 0
	s_add_u32 s14, s4, 0x4700
	s_addc_u32 s15, s5, 0
	s_add_u32 s16, s4, 0x4800
	s_addc_u32 s17, s5, 0
	s_add_u32 s18, s4, 0x4900
	s_addc_u32 s19, s5, 0
	s_add_u32 s20, s4, 0x4a00
	s_addc_u32 s21, s5, 0
	s_add_u32 s22, s4, 0x4b00
	s_addc_u32 s23, s5, 0
	s_add_u32 s24, s4, 0x4c00
	s_addc_u32 s25, s5, 0
	s_add_u32 s26, s4, 0x4d00
	s_addc_u32 s27, s5, 0
	s_add_u32 s28, s4, 0x4e00
	s_addc_u32 s29, s5, 0
	s_add_u32 s30, s4, 0x4f00
	s_addc_u32 s31, s5, 0
	s_add_u32 s36, s4, 0x5000
	s_addc_u32 s37, s5, 0
	s_add_u32 s38, s4, 0x5100
	s_addc_u32 s39, s5, 0
	s_add_u32 s40, s4, 0x5200
	s_addc_u32 s41, s5, 0
	s_add_u32 s42, s4, 0x5300
	s_addc_u32 s43, s5, 0
	s_mov_b32 s34, 1
	v_mov_b32_e32 v16, 0
	s_branch .LBB0_595

; #define PG8_STAGE(bufoff, soff, voff) do { _Pragma("unroll") for (int _i = 0; _i < 2; ++_i) \
;         __builtin_amdgcn_raw_ptr_buffer_load_lds(rs_##voff, (PG8_LAS unsigned*)(lds + (bufoff) + ldsw + _i * 8192), 16, (int)(voff)[_i], (int)(soff), 0, 0); } while (0)
; #define PG8_LDA(dst, b, h) do { _Pragma("unroll") for (int m = 0; m < 4; ++m) _Pragma("unroll") for (int k = 0; k < 2; ++k) dst[m][k] = *(const PG8_LAS bf16x8*)(lds + PG8_SA(b, h) + aoff + m * 2048 + k * 1024); } while (0)
; #define PG8_LDB(dst, b, h) do { _Pragma("unroll") for (int n = 0; n < 2; ++n) _Pragma("unroll") for (int k = 0; k < 2; ++k) dst[n][k] = *(const PG8_LAS bf16x8*)(lds + PG8_SB(b, h) + boff + n * 2048 + k * 1024); } while (0)
; #define PG8_MMA(ai, bj, At, Bt) do { __builtin_amdgcn_s_setprio(1); _Pragma("unroll") for (int m = 0; m < 4; ++m) _Pragma("unroll") for (int n = 0; n < 2; ++n) _Pragma("unroll") for (int k = 0; k < 2; ++k) \
;         acc[ai][bj][m][n] = __builtin_amdgcn_mfma_f32_16x16x32_bf16(Bt[n][k], At[m][k], acc[ai][bj][m][n], 0, 0, 0); __builtin_amdgcn_s_setprio(0); } while (0)
; #define PG8_WAIT_V(n) asm volatile("s_waitcnt vmcnt(" #n ")" ::: "memory")
; #define PG8_BAR __builtin_amdgcn_s_barrier()
; template <class Epi, class Sched, bool ALIGN_EPI = false, bool SP2 = false>
; __device__ __forceinline__ void gemm_phase(PG8_LAS unsigned char* lds, const Gemm g, const Sched& S, const Epi& E, const int wid  ) {
;     ...
;         for (int t = 0; t < nt; t += 2) {
;             const bool last = (t == nt - 2);
;             const unsigned a1 = cA + (unsigned)(t + 1) * kstep;
;             const unsigned a2 = last ? nA : cA + (unsigned)(t + 2) * kstep, b2 = last ? nB : cB + (unsigned)(t + 2) * kstep;
;             const unsigned a3 = a2 + kstep, b3 = b2 + kstep;
;             if (last && has_next) S.a_ready(nxt);
;             if constexpr (SP2) {
;             PG8_LDB(B0, 0, 0); PG8_LDB(B1, 0, 1); PG8_SCHED; PG8_LDA(At, 0, 0); PG8_STAGE(PG8_SA(1, 1), a1 + hstep, voffA);
;             PG8_WAIT_V(8); PG8_WAIT_L(0); PG8_BAR; PG8_MMA(0, 0, At, B0); PG8_MMA(0, 1, At, B1); PG8_BAR; PG8_SCHED;
;             PG8_LDA(At, 0, 1); PG8_STAGE(PG8_SB(0, 0), b2, voffB); PG8_STAGE(PG8_SB(0, 1), b2 + hstep, voffB); PG8_STAGE(PG8_SA(0, 0), a2, voffA);
;             PG8_WAIT_V(8); PG8_WAIT_L(0); PG8_BAR; PG8_MMA(1, 0, At, B0); PG8_MMA(1, 1, At, B1); PG8_BAR; PG8_SCHED;
.Lprio_658:
.LBB0_658:
	s_waitcnt lgkmcnt(0)
	ds_read_b128 v[16:19], v188
	ds_read_b128 v[20:23], v188 offset:1024
	ds_read_b128 v[24:27], v188 offset:2048
	ds_read_b128 v[28:31], v188 offset:3072
	ds_read_b128 v[32:35], v189
	ds_read_b128 v[36:39], v189 offset:1024
	ds_read_b128 v[40:43], v189 offset:2048
	ds_read_b128 v[44:47], v189 offset:3072
	s_add_i32 s18, s8, 0xfff80080
	s_cmp_eq_u32 s46, 28
	s_cselect_b32 s94, s6, s18
	s_cselect_b32 s93, s7, s9
	s_or_b32 s47, s94, 0x80
	s_mov_b32 m0, s75
	ds_read_b128 v[160:163], v190
	ds_read_b128 v[170:173], v190 offset:1024
	ds_read_b128 v[174:177], v190 offset:2048
	ds_read_b128 v[178:181], v190 offset:3072
	ds_read_b128 v[194:197], v190 offset:4096
	ds_read_b128 v[198:201], v190 offset:5120
	ds_read_b128 v[202:205], v190 offset:6144
	ds_read_b128 v[206:209], v190 offset:7168
	buffer_load_dwordx4 v182, s[12:15], s8 offen lds
	s_mov_b32 m0, s77
	s_nop 0
	buffer_load_dwordx4 v184, s[12:15], s8 offen lds
	s_waitcnt vmcnt(8)
	s_waitcnt lgkmcnt(0)
	s_barrier
	s_waitcnt lgkmcnt(7)
	v_mfma_f32_16x16x32_bf16 v[152:155], v[16:19], v[160:163], v[152:155]
	v_mfma_f32_16x16x32_bf16 v[52:55], v[24:27], v[160:163], v[52:55]
	s_waitcnt lgkmcnt(5)
	v_mfma_f32_16x16x32_bf16 v[148:151], v[16:19], v[174:177], v[148:151]
	v_mfma_f32_16x16x32_bf16 v[144:147], v[24:27], v[174:177], v[144:147]
	s_waitcnt lgkmcnt(3)
	v_mfma_f32_16x16x32_bf16 v[140:143], v[16:19], v[194:197], v[140:143]
	v_mfma_f32_16x16x32_bf16 v[132:135], v[24:27], v[194:197], v[132:135]
	s_waitcnt lgkmcnt(1)
	v_mfma_f32_16x16x32_bf16 v[156:159], v[16:19], v[202:205], v[156:159]
	v_mfma_f32_16x16x32_bf16 v[120:123], v[24:27], v[202:205], v[120:123]
	v_mfma_f32_16x16x32_bf16 v[152:155], v[20:23], v[170:173], v[152:155]
	v_mfma_f32_16x16x32_bf16 v[52:55], v[28:31], v[170:173], v[52:55]
	v_mfma_f32_16x16x32_bf16 v[148:151], v[20:23], v[178:181], v[148:151]
	v_mfma_f32_16x16x32_bf16 v[144:147], v[28:31], v[178:181], v[144:147]
	v_mfma_f32_16x16x32_bf16 v[140:143], v[20:23], v[198:201], v[140:143]
	v_mfma_f32_16x16x32_bf16 v[132:135], v[28:31], v[198:201], v[132:135]
	s_waitcnt lgkmcnt(0)
	v_mfma_f32_16x16x32_bf16 v[156:159], v[20:23], v[206:209], v[156:159]
	v_mfma_f32_16x16x32_bf16 v[120:123], v[28:31], v[206:209], v[120:123]
	v_mfma_f32_16x16x32_bf16 v[12:15], v[32:35], v[160:163], v[12:15]
	v_mfma_f32_16x16x32_bf16 v[8:11], v[40:43], v[160:163], v[8:11]
	v_mfma_f32_16x16x32_bf16 v[136:139], v[32:35], v[174:177], v[136:139]
	v_mfma_f32_16x16x32_bf16 v[128:131], v[40:43], v[174:177], v[128:131]
	v_mfma_f32_16x16x32_bf16 v[124:127], v[32:35], v[194:197], v[124:127]
	v_mfma_f32_16x16x32_bf16 v[116:119], v[40:43], v[194:197], v[116:119]
	v_mfma_f32_16x16x32_bf16 v[112:115], v[32:35], v[202:205], v[112:115]
	v_mfma_f32_16x16x32_bf16 v[108:111], v[40:43], v[202:205], v[108:111]
	v_mfma_f32_16x16x32_bf16 v[12:15], v[36:39], v[170:173], v[12:15]
	v_mfma_f32_16x16x32_bf16 v[8:11], v[44:47], v[170:173], v[8:11]
	v_mfma_f32_16x16x32_bf16 v[136:139], v[36:39], v[178:181], v[136:139]
	v_mfma_f32_16x16x32_bf16 v[128:131], v[44:47], v[178:181], v[128:131]
	v_mfma_f32_16x16x32_bf16 v[124:127], v[36:39], v[198:201], v[124:127]
	v_mfma_f32_16x16x32_bf16 v[116:119], v[44:47], v[198:201], v[116:119]
	v_mfma_f32_16x16x32_bf16 v[112:115], v[36:39], v[206:209], v[112:115]
	v_mfma_f32_16x16x32_bf16 v[108:111], v[44:47], v[206:209], v[108:111]
	s_barrier
	s_mov_b32 m0, s33
	s_mov_b32 s18, s14
	s_mov_b32 s19, s15
	ds_read_b128 v[160:163], v190 offset:16384
	ds_read_b128 v[170:173], v190 offset:17408
	ds_read_b128 v[174:177], v190 offset:18432
	ds_read_b128 v[178:181], v190 offset:19456
	ds_read_b128 v[194:197], v190 offset:20480
	ds_read_b128 v[198:201], v190 offset:21504
	ds_read_b128 v[202:205], v190 offset:22528
	ds_read_b128 v[206:209], v190 offset:23552
	buffer_load_dwordx4 v183, s[16:19], s93 offen lds
	s_mov_b32 m0, s50
	s_add_i32 s95, s93, 0x80000
	buffer_load_dwordx4 v185, s[16:19], s93 offen lds
	s_mov_b32 m0, s51
	s_nop 0
	buffer_load_dwordx4 v183, s[16:19], s95 offen lds
	s_mov_b32 m0, s53
	s_nop 0
	buffer_load_dwordx4 v185, s[16:19], s95 offen lds
	s_mov_b32 m0, s3
	s_nop 0
	buffer_load_dwordx4 v182, s[12:15], s94 offen lds
	s_mov_b32 m0, s54
	s_nop 0
	buffer_load_dwordx4 v184, s[12:15], s94 offen lds
	s_waitcnt vmcnt(8)
	s_waitcnt lgkmcnt(0)
	s_barrier
	s_waitcnt lgkmcnt(7)
	v_mfma_f32_16x16x32_bf16 v[104:107], v[16:19], v[160:163], v[104:107]
	v_mfma_f32_16x16x32_bf16 v[100:103], v[24:27], v[160:163], v[100:103]
	s_waitcnt lgkmcnt(5)
	v_mfma_f32_16x16x32_bf16 v[96:99], v[16:19], v[174:177], v[96:99]
	v_mfma_f32_16x16x32_bf16 v[88:91], v[24:27], v[174:177], v[88:91]
	s_waitcnt lgkmcnt(3)
	v_mfma_f32_16x16x32_bf16 v[84:87], v[16:19], v[194:197], v[84:87]
	v_mfma_f32_16x16x32_bf16 v[76:79], v[24:27], v[194:197], v[76:79]
	s_waitcnt lgkmcnt(1)
	v_mfma_f32_16x16x32_bf16 v[16:19], v[16:19], v[202:205], v[92:95]
	v_mfma_f32_16x16x32_bf16 v[104:107], v[20:23], v[170:173], v[104:107]
	v_mfma_f32_16x16x32_bf16 v[100:103], v[28:31], v[170:173], v[100:103]
	v_mfma_f32_16x16x32_bf16 v[96:99], v[20:23], v[178:181], v[96:99]
	v_mfma_f32_16x16x32_bf16 v[88:91], v[28:31], v[178:181], v[88:91]
	v_mfma_f32_16x16x32_bf16 v[84:87], v[20:23], v[198:201], v[84:87]
	v_mfma_f32_16x16x32_bf16 v[76:79], v[28:31], v[198:201], v[76:79]
	s_waitcnt lgkmcnt(0)
	v_mfma_f32_16x16x32_bf16 v[16:19], v[20:23], v[206:209], v[16:19]
	v_mfma_f32_16x16x32_bf16 v[20:23], v[24:27], v[202:205], v[48:51]
	v_mfma_f32_16x16x32_bf16 v[20:23], v[28:31], v[206:209], v[20:23]
	v_mfma_f32_16x16x32_bf16 v[48:51], v[32:35], v[194:197], v[68:71]
	v_mfma_f32_16x16x32_bf16 v[4:7], v[32:35], v[160:163], v[4:7]
	v_mfma_f32_16x16x32_bf16 v[0:3], v[40:43], v[160:163], v[0:3]
	v_mfma_f32_16x16x32_bf16 v[24:27], v[32:35], v[174:177], v[80:83]
	v_mfma_f32_16x16x32_bf16 v[68:71], v[36:39], v[198:201], v[48:51]
	v_mfma_f32_16x16x32_bf16 v[48:51], v[40:43], v[194:197], v[64:67]
	v_mfma_f32_16x16x32_bf16 v[32:35], v[32:35], v[202:205], v[60:63]
	v_mfma_f32_16x16x32_bf16 v[4:7], v[36:39], v[170:173], v[4:7]
	v_mfma_f32_16x16x32_bf16 v[0:3], v[44:47], v[170:173], v[0:3]
	v_mfma_f32_16x16x32_bf16 v[24:27], v[36:39], v[178:181], v[24:27]
	v_mfma_f32_16x16x32_bf16 v[28:31], v[40:43], v[174:177], v[72:75]
	v_mfma_f32_16x16x32_bf16 v[64:67], v[44:47], v[198:201], v[48:51]
	v_mfma_f32_16x16x32_bf16 v[32:35], v[36:39], v[206:209], v[32:35]
	v_mfma_f32_16x16x32_bf16 v[36:39], v[40:43], v[202:205], v[56:59]
	v_mfma_f32_16x16x32_bf16 v[28:31], v[44:47], v[178:181], v[28:31]
	v_mfma_f32_16x16x32_bf16 v[36:39], v[44:47], v[206:209], v[36:39]
	s_barrier
; #define PG8_STAGE(bufoff, soff, voff) do { _Pragma("unroll") for (int _i = 0; _i < 2; ++_i) \
;         __builtin_amdgcn_raw_ptr_buffer_load_lds(rs_##voff, (PG8_LAS unsigned*)(lds + (bufoff) + ldsw + _i * 8192), 16, (int)(voff)[_i], (int)(soff), 0, 0); } while (0)
; #define PG8_BAR __builtin_amdgcn_s_barrier()
; template <class Epi, class Sched, bool ALIGN_EPI = false, bool SP2 = false>
; __device__ __forceinline__ void gemm_phase(PG8_LAS unsigned char* lds, const Gemm g, const Sched& S, const Epi& E, const int wid  ) {
;     ...
;             PG8_LDB(B0, 1, 0); PG8_LDB(B1, 1, 1); PG8_SCHED; PG8_LDA(At, 1, 0); PG8_STAGE(PG8_SA(0, 1), a2 + hstep, voffA);
;             PG8_WAIT_V(8); PG8_WAIT_L(0); PG8_BAR; PG8_MMA(0, 0, At, B0); PG8_MMA(0, 1, At, B1); PG8_BAR; PG8_SCHED;
;             PG8_LDA(At, 1, 1); PG8_STAGE(PG8_SB(1, 0), b3, voffB); PG8_STAGE(PG8_SB(1, 1), b3 + hstep, voffB); PG8_STAGE(PG8_SA(1, 0), a3, voffA);
;             PG8_WAIT_V(8); PG8_WAIT_L(0); PG8_BAR; PG8_MMA(1, 0, At, B0); PG8_MMA(1, 1, At, B1); PG8_BAR; PG8_SCHED;
;             } else {
;             PG8_LDB(B0, 0, 0); PG8_SCHED; PG8_LDA(At, 0, 0); PG8_STAGE(PG8_SA(1, 1), a1 + hstep, voffA);
;             PG8_WAIT_L(8); PG8_BAR; PG8_WAIT_L(0); PG8_MMA(0, 0, At, B0); PG8_BAR; PG8_SCHED;
;             PG8_LDB(B1, 0, 1); PG8_STAGE(PG8_SB(0, 0), b2, voffB);
;             PG8_BAR; PG8_WAIT_L(0); PG8_MMA(0, 1, At, B1); PG8_BAR;
;             PG8_LDA(At, 0, 1); PG8_STAGE(PG8_SA(0, 0), a2, voffA);
;             PG8_BAR; PG8_WAIT_L(0); PG8_MMA(1, 0, At, B0); PG8_BAR; PG8_SCHED;
;             PG8_STAGE(PG8_SB(0, 1), b2 + hstep, voffB);
;             PG8_WAIT_V(6); PG8_BAR; PG8_MMA(1, 1, At, B1); PG8_BAR;
;             PG8_LDB(B0, 1, 0); PG8_SCHED; PG8_LDA(At, 1, 0); PG8_STAGE(PG8_SA(0, 1), a2 + hstep, voffA);
;             PG8_WAIT_L(8); PG8_BAR; PG8_WAIT_L(0); PG8_MMA(0, 0, At, B0); PG8_BAR; PG8_SCHED;
;             PG8_LDB(B1, 1, 1); PG8_STAGE(PG8_SB(1, 0), b3, voffB);
;             PG8_BAR; PG8_WAIT_L(0); PG8_MMA(0, 1, At, B1); PG8_BAR;
;             PG8_LDA(At, 1, 1); PG8_STAGE(PG8_SA(1, 0), a3, voffA);
;             PG8_BAR; PG8_WAIT_L(0); PG8_MMA(1, 0, At, B0); PG8_BAR; PG8_SCHED;
;             PG8_STAGE(PG8_SB(1, 1), b3 + hstep, voffB);
;             PG8_WAIT_V(6); PG8_BAR; PG8_MMA(1, 1, At, B1); PG8_BAR;
;             }
;         }
;         if constexpr (ALIGN_EPI) { if (wr == 0) PG8_BAR; }
	ds_read_b128 v[40:43], v191
	ds_read_b128 v[44:47], v191 offset:1024
	ds_read_b128 v[48:51], v191 offset:2048
	ds_read_b128 v[56:59], v191 offset:3072
	ds_read_b128 v[60:63], v192
	ds_read_b128 v[160:163], v192 offset:1024
	ds_read_b128 v[170:173], v192 offset:2048
	ds_read_b128 v[174:177], v192 offset:3072
	s_add_i32 s94, s94, 0x80000
	s_mov_b32 m0, s55
	ds_read_b128 v[72:75], v190 offset:32768
	ds_read_b128 v[80:83], v190 offset:33792
	ds_read_b128 v[92:95], v190 offset:34816
	ds_read_b128 v[178:181], v190 offset:35840
	ds_read_b128 v[194:197], v190 offset:36864
	ds_read_b128 v[198:201], v190 offset:37888
	ds_read_b128 v[202:205], v190 offset:38912
	ds_read_b128 v[206:209], v190 offset:39936
	buffer_load_dwordx4 v182, s[12:15], s94 offen lds
	s_mov_b32 m0, s59
	s_nop 0
	buffer_load_dwordx4 v184, s[12:15], s94 offen lds
	s_waitcnt vmcnt(8)
	s_waitcnt lgkmcnt(0)
	s_barrier
	s_waitcnt lgkmcnt(7)
	v_mfma_f32_16x16x32_bf16 v[152:155], v[40:43], v[72:75], v[152:155]
	v_mfma_f32_16x16x32_bf16 v[52:55], v[48:51], v[72:75], v[52:55]
	s_waitcnt lgkmcnt(5)
	v_mfma_f32_16x16x32_bf16 v[148:151], v[40:43], v[92:95], v[148:151]
	v_mfma_f32_16x16x32_bf16 v[144:147], v[48:51], v[92:95], v[144:147]
	s_waitcnt lgkmcnt(3)
	v_mfma_f32_16x16x32_bf16 v[140:143], v[40:43], v[194:197], v[140:143]
	v_mfma_f32_16x16x32_bf16 v[132:135], v[48:51], v[194:197], v[132:135]
	s_waitcnt lgkmcnt(1)
	v_mfma_f32_16x16x32_bf16 v[156:159], v[40:43], v[202:205], v[156:159]
	v_mfma_f32_16x16x32_bf16 v[120:123], v[48:51], v[202:205], v[120:123]
	v_mfma_f32_16x16x32_bf16 v[152:155], v[44:47], v[80:83], v[152:155]
	v_mfma_f32_16x16x32_bf16 v[52:55], v[56:59], v[80:83], v[52:55]
	v_mfma_f32_16x16x32_bf16 v[148:151], v[44:47], v[178:181], v[148:151]
	v_mfma_f32_16x16x32_bf16 v[144:147], v[56:59], v[178:181], v[144:147]
	v_mfma_f32_16x16x32_bf16 v[140:143], v[44:47], v[198:201], v[140:143]
	v_mfma_f32_16x16x32_bf16 v[132:135], v[56:59], v[198:201], v[132:135]
	s_waitcnt lgkmcnt(0)
	v_mfma_f32_16x16x32_bf16 v[156:159], v[44:47], v[206:209], v[156:159]
	v_mfma_f32_16x16x32_bf16 v[120:123], v[56:59], v[206:209], v[120:123]
	v_mfma_f32_16x16x32_bf16 v[12:15], v[60:63], v[72:75], v[12:15]
	v_mfma_f32_16x16x32_bf16 v[8:11], v[170:173], v[72:75], v[8:11]
	v_mfma_f32_16x16x32_bf16 v[72:75], v[60:63], v[92:95], v[136:139]
	v_mfma_f32_16x16x32_bf16 v[136:139], v[160:163], v[178:181], v[72:75]
	v_mfma_f32_16x16x32_bf16 v[72:75], v[170:173], v[92:95], v[128:131]
	v_mfma_f32_16x16x32_bf16 v[128:131], v[174:177], v[178:181], v[72:75]
	v_mfma_f32_16x16x32_bf16 v[72:75], v[60:63], v[194:197], v[124:127]
	v_mfma_f32_16x16x32_bf16 v[124:127], v[160:163], v[198:201], v[72:75]
	v_mfma_f32_16x16x32_bf16 v[72:75], v[170:173], v[194:197], v[116:119]
	v_mfma_f32_16x16x32_bf16 v[116:119], v[174:177], v[198:201], v[72:75]
	v_mfma_f32_16x16x32_bf16 v[72:75], v[60:63], v[202:205], v[112:115]
	v_mfma_f32_16x16x32_bf16 v[112:115], v[160:163], v[206:209], v[72:75]
	v_mfma_f32_16x16x32_bf16 v[72:75], v[170:173], v[202:205], v[108:111]
	v_mfma_f32_16x16x32_bf16 v[12:15], v[160:163], v[80:83], v[12:15]
	v_mfma_f32_16x16x32_bf16 v[8:11], v[174:177], v[80:83], v[8:11]
	v_mfma_f32_16x16x32_bf16 v[108:111], v[174:177], v[206:209], v[72:75]
	s_barrier
	s_mov_b32 m0, s64
	s_or_b32 s94, s93, 0x80
	s_nop 0
	ds_read_b128 v[72:75], v190 offset:49152
	ds_read_b128 v[80:83], v190 offset:50176
	ds_read_b128 v[178:181], v190 offset:51200
	ds_read_b128 v[194:197], v190 offset:52224
	ds_read_b128 v[198:201], v190 offset:53248
	ds_read_b128 v[202:205], v190 offset:54272
	ds_read_b128 v[206:209], v190 offset:55296
	ds_read_b128 v[210:213], v190 offset:56320
	buffer_load_dwordx4 v183, s[16:19], s94 offen lds
	s_mov_b32 m0, s66
	s_add_i32 s93, s93, 0x80080
	buffer_load_dwordx4 v185, s[16:19], s94 offen lds
	s_mov_b32 m0, s69
	s_nop 0
	buffer_load_dwordx4 v183, s[16:19], s93 offen lds
	s_mov_b32 m0, s70
	s_nop 0
	buffer_load_dwordx4 v185, s[16:19], s93 offen lds
	s_mov_b32 m0, s67
	s_nop 0
	buffer_load_dwordx4 v182, s[12:15], s47 offen lds
	s_mov_b32 m0, s68
	s_nop 0
	buffer_load_dwordx4 v184, s[12:15], s47 offen lds
	s_waitcnt vmcnt(8)
	s_waitcnt lgkmcnt(0)
	s_barrier
	s_waitcnt lgkmcnt(7)
	v_mfma_f32_16x16x32_bf16 v[92:95], v[40:43], v[72:75], v[104:107]
	s_waitcnt lgkmcnt(6)
	v_mfma_f32_16x16x32_bf16 v[104:107], v[44:47], v[80:83], v[92:95]
	v_mfma_f32_16x16x32_bf16 v[92:95], v[48:51], v[72:75], v[100:103]
	v_mfma_f32_16x16x32_bf16 v[100:103], v[56:59], v[80:83], v[92:95]
	s_waitcnt lgkmcnt(5)
	v_mfma_f32_16x16x32_bf16 v[92:95], v[40:43], v[178:181], v[96:99]
	s_waitcnt lgkmcnt(1)
	v_mfma_f32_16x16x32_bf16 v[16:19], v[40:43], v[206:209], v[16:19]
	v_mfma_f32_16x16x32_bf16 v[96:99], v[44:47], v[194:197], v[92:95]
	v_mfma_f32_16x16x32_bf16 v[88:91], v[48:51], v[178:181], v[88:91]
	v_mfma_f32_16x16x32_bf16 v[84:87], v[40:43], v[198:201], v[84:87]
	v_mfma_f32_16x16x32_bf16 v[76:79], v[48:51], v[198:201], v[76:79]
	s_waitcnt lgkmcnt(0)
	v_mfma_f32_16x16x32_bf16 v[92:95], v[44:47], v[210:213], v[16:19]
	v_mfma_f32_16x16x32_bf16 v[16:19], v[48:51], v[206:209], v[20:23]
	v_mfma_f32_16x16x32_bf16 v[88:91], v[56:59], v[194:197], v[88:91]
	v_mfma_f32_16x16x32_bf16 v[84:87], v[44:47], v[202:205], v[84:87]
	v_mfma_f32_16x16x32_bf16 v[76:79], v[56:59], v[202:205], v[76:79]
	v_mfma_f32_16x16x32_bf16 v[48:51], v[56:59], v[210:213], v[16:19]
	v_mfma_f32_16x16x32_bf16 v[4:7], v[60:63], v[72:75], v[4:7]
	v_mfma_f32_16x16x32_bf16 v[0:3], v[170:173], v[72:75], v[0:3]
	v_mfma_f32_16x16x32_bf16 v[16:19], v[60:63], v[178:181], v[24:27]
	v_mfma_f32_16x16x32_bf16 v[4:7], v[160:163], v[80:83], v[4:7]
	v_mfma_f32_16x16x32_bf16 v[0:3], v[174:177], v[80:83], v[0:3]
	v_mfma_f32_16x16x32_bf16 v[80:83], v[160:163], v[194:197], v[16:19]
	v_mfma_f32_16x16x32_bf16 v[16:19], v[170:173], v[178:181], v[28:31]
	v_mfma_f32_16x16x32_bf16 v[72:75], v[174:177], v[194:197], v[16:19]
	v_mfma_f32_16x16x32_bf16 v[16:19], v[60:63], v[198:201], v[68:71]
	v_mfma_f32_16x16x32_bf16 v[68:71], v[160:163], v[202:205], v[16:19]
	v_mfma_f32_16x16x32_bf16 v[16:19], v[170:173], v[198:201], v[64:67]
	v_mfma_f32_16x16x32_bf16 v[64:67], v[174:177], v[202:205], v[16:19]
	v_mfma_f32_16x16x32_bf16 v[16:19], v[60:63], v[206:209], v[32:35]
	v_mfma_f32_16x16x32_bf16 v[60:63], v[160:163], v[210:213], v[16:19]
	v_mfma_f32_16x16x32_bf16 v[16:19], v[170:173], v[206:209], v[36:39]
	v_mfma_f32_16x16x32_bf16 v[56:59], v[174:177], v[210:213], v[16:19]
	s_barrier
	s_add_i32 s46, s46, 2
	s_addk_i32 s8, 0x100
	s_addk_i32 s9, 0x100
	s_cmp_gt_u32 s46, 29
	s_cbranch_scc0 .LBB0_658
	s_and_b64 vcc, exec, s[26:27]
	s_cbranch_vccz .LBB0_661
	s_barrier

; __device__ __forceinline__ unsigned xb_ld(unsigned* p)              { return __hip_atomic_load(p, __ATOMIC_RELAXED, __HIP_MEMORY_SCOPE_AGENT); }
; __device__ __forceinline__ unsigned xb_add(unsigned* p, unsigned v) { return __hip_atomic_fetch_add(p, v, __ATOMIC_RELAXED, __HIP_MEMORY_SCOPE_AGENT); }
; __device__ __forceinline__ void xcd_barrier_complete(unsigned* bar, unsigned x, unsigned& nloc, unsigned& nx) {
;     const unsigned G = gridDim.x * gridDim.y * gridDim.z;
;     unsigned sum, cnt, mine, sp = 0u;
;     for (;;) {
;         sum = 0u; cnt = 0u; mine = 0u;
; #pragma unroll
;         for (unsigned j = 0; j < 16; ++j) { const unsigned c = xb_ld(&bar[XB_XCNT(j)]); sum += c; cnt += (c > 0u) ? 1u : 0u; mine = (j == x) ? c : mine; }
; __device__ __forceinline__ void xcd_barrier(const XcdBarrier& b) {
;     asm volatile("s_waitcnt vmcnt(0)" ::: "memory");
;     __syncthreads();
;     if (threadIdx.x == 0) {
;         unsigned* bar = b.bar;
;         __builtin_amdgcn_s_waitcnt(0);
;         unsigned nloc = b.st[0], nx = b.st[1];
;         if (nloc == 0u) { xcd_barrier_complete(bar, b.x, nloc, nx); b.st[0] = nloc; b.st[1] = nx; }
;         const unsigned old = xb_add(&bar[XB_XSUB(b.x)], 1u);
.LBB0_721:
	s_cmp_lt_i32 s57, 10
	s_cbranch_scc1 .LBB0_775
	s_setprio 0
	s_add_i32 s0, 0, 0x20520
	v_mov_b32_e32 v0, s0
	ds_read_b64 v[0:1], v0
	s_getreg_b32 s3, hwreg(HW_REG_XCC_ID, 0, 4)
	s_waitcnt vmcnt(0)
	s_waitcnt vmcnt(16) lgkmcnt(0)
	s_barrier
	v_readfirstlane_b32 s4, v0
	v_readfirstlane_b32 s5, v1
	s_mov_b64 s[0:1], exec
	v_readlane_b32 s6, v246, 2
	v_readlane_b32 s7, v246, 3
	s_and_b64 s[6:7], s[0:1], s[6:7]
	s_mov_b64 exec, s[6:7]
	s_cbranch_execz .LBB0_774
	s_add_i32 s6, 0, 0x20160
	v_mov_b32_e32 v0, s6
	s_waitcnt vmcnt(0) expcnt(0) lgkmcnt(0)
	ds_read_b32 v2, v0
	s_add_i32 s6, 0, 0x20164
	v_mov_b32_e32 v0, s6
	ds_read_b32 v0, v0
	s_and_b32 s3, s3, 15
	s_waitcnt lgkmcnt(1)
	v_cmp_ne_u32_e32 vcc, 0, v2
	s_cbranch_vccnz .LBB0_738
	v_readlane_b32 s6, v246, 0
	v_readlane_b32 s7, v246, 1
	s_load_dwordx2 s[10:11], s[6:7], 0x4
	s_add_u32 s6, s4, 0x4200
	s_addc_u32 s7, s5, 0
	s_add_u32 s8, s4, 0x4400
	s_addc_u32 s9, s5, 0
	s_waitcnt lgkmcnt(0)
	s_mul_i32 s33, s10, s52
	s_add_u32 s10, s4, 0x4500
	s_mul_i32 s33, s33, s11
	s_addc_u32 s11, s5, 0
	s_add_u32 s12, s4, 0x4600
	s_addc_u32 s13, s5, 0
	s_add_u32 s14, s4, 0x4700
	s_addc_u32 s15, s5, 0
	s_add_u32 s16, s4, 0x4800
	s_addc_u32 s17, s5, 0
	s_add_u32 s18, s4, 0x4900
	s_addc_u32 s19, s5, 0
	s_add_u32 s20, s4, 0x4a00
	s_addc_u32 s21, s5, 0
	s_add_u32 s22, s4, 0x4b00
	s_addc_u32 s23, s5, 0
	s_add_u32 s24, s4, 0x4c00
	s_addc_u32 s25, s5, 0
	s_add_u32 s26, s4, 0x4d00
	s_addc_u32 s27, s5, 0
	s_add_u32 s28, s4, 0x4e00
	s_addc_u32 s29, s5, 0
	s_add_u32 s30, s4, 0x4f00
	s_addc_u32 s31, s5, 0
	s_add_u32 s36, s4, 0x5000
	s_addc_u32 s37, s5, 0
	s_add_u32 s38, s4, 0x5100
	s_addc_u32 s39, s5, 0
	s_add_u32 s40, s4, 0x5200
	s_addc_u32 s41, s5, 0
	s_add_u32 s42, s4, 0x5300
	s_addc_u32 s43, s5, 0
	s_mov_b32 s34, 1
	v_mov_b32_e32 v16, 0
	s_branch .LBB0_726

; #define PG8_STAGE(bufoff, soff, voff) do { _Pragma("unroll") for (int _i = 0; _i < 2; ++_i) \
;         __builtin_amdgcn_raw_ptr_buffer_load_lds(rs_##voff, (PG8_LAS unsigned*)(lds + (bufoff) + ldsw + _i * 8192), 16, (int)(voff)[_i], (int)(soff), 0, 0); } while (0)
; #define PG8_LDA(dst, b, h) do { _Pragma("unroll") for (int m = 0; m < 4; ++m) _Pragma("unroll") for (int k = 0; k < 2; ++k) dst[m][k] = *(const PG8_LAS bf16x8*)(lds + PG8_SA(b, h) + aoff + m * 2048 + k * 1024); } while (0)
; #define PG8_LDB(dst, b, h) do { _Pragma("unroll") for (int n = 0; n < 2; ++n) _Pragma("unroll") for (int k = 0; k < 2; ++k) dst[n][k] = *(const PG8_LAS bf16x8*)(lds + PG8_SB(b, h) + boff + n * 2048 + k * 1024); } while (0)
; #define PG8_MMA(ai, bj, At, Bt) do { __builtin_amdgcn_s_setprio(1); _Pragma("unroll") for (int m = 0; m < 4; ++m) _Pragma("unroll") for (int n = 0; n < 2; ++n) _Pragma("unroll") for (int k = 0; k < 2; ++k) \
;         acc[ai][bj][m][n] = __builtin_amdgcn_mfma_f32_16x16x32_bf16(Bt[n][k], At[m][k], acc[ai][bj][m][n], 0, 0, 0); __builtin_amdgcn_s_setprio(0); } while (0)
; #define PG8_WAIT_V(n) asm volatile("s_waitcnt vmcnt(" #n ")" ::: "memory")
; #define PG8_BAR __builtin_amdgcn_s_barrier()
; template <class Epi, class Sched, bool ALIGN_EPI = false, bool SP2 = false>
; __device__ __forceinline__ void gemm_phase(PG8_LAS unsigned char* lds, const Gemm g, const Sched& S, const Epi& E, const int wid  ) {
;     ...
;         for (int t = 0; t < nt; t += 2) {
;             const bool last = (t == nt - 2);
;             const unsigned a1 = cA + (unsigned)(t + 1) * kstep;
;             const unsigned a2 = last ? nA : cA + (unsigned)(t + 2) * kstep, b2 = last ? nB : cB + (unsigned)(t + 2) * kstep;
;             const unsigned a3 = a2 + kstep, b3 = b2 + kstep;
;             if (last && has_next) S.a_ready(nxt);
;             if constexpr (SP2) {
;             PG8_LDB(B0, 0, 0); PG8_LDB(B1, 0, 1); PG8_SCHED; PG8_LDA(At, 0, 0); PG8_STAGE(PG8_SA(1, 1), a1 + hstep, voffA);
;             PG8_WAIT_V(8); PG8_WAIT_L(0); PG8_BAR; PG8_MMA(0, 0, At, B0); PG8_MMA(0, 1, At, B1); PG8_BAR; PG8_SCHED;
;             PG8_LDA(At, 0, 1); PG8_STAGE(PG8_SB(0, 0), b2, voffB); PG8_STAGE(PG8_SB(0, 1), b2 + hstep, voffB); PG8_STAGE(PG8_SA(0, 0), a2, voffA);
;             PG8_WAIT_V(8); PG8_WAIT_L(0); PG8_BAR; PG8_MMA(1, 0, At, B0); PG8_MMA(1, 1, At, B1); PG8_BAR; PG8_SCHED;
.Lprio_804:
.LBB0_804:
	ds_read_b128 v[132:135], v140
	ds_read_b128 v[146:149], v140 offset:1024
	ds_read_b128 v[150:153], v140 offset:2048
	ds_read_b128 v[154:157], v140 offset:3072
	ds_read_b128 v[158:161], v141
	ds_read_b128 v[162:165], v141 offset:1024
	ds_read_b128 v[166:169], v141 offset:2048
	ds_read_b128 v[170:173], v141 offset:3072
	s_add_i32 s14, s54, 0xffea0080
	s_cmpk_eq_i32 s58, 0x54
	s_cselect_b32 s61, s0, s14
	s_cselect_b32 s60, s1, s55
	s_or_b32 s59, s61, 0x80
	s_mov_b32 m0, s45
	ds_read_b128 v[174:177], v142
	ds_read_b128 v[178:181], v142 offset:1024
	ds_read_b128 v[182:185], v142 offset:2048
	ds_read_b128 v[186:189], v142 offset:3072
	ds_read_b128 v[190:193], v142 offset:4096
	ds_read_b128 v[194:197], v142 offset:5120
	ds_read_b128 v[198:201], v142 offset:6144
	ds_read_b128 v[202:205], v142 offset:7168
	buffer_load_dwordx4 v136, s[8:11], s54 offen lds
	s_mov_b32 m0, s46
	s_nop 0
	buffer_load_dwordx4 v138, s[8:11], s54 offen lds
	s_waitcnt vmcnt(8)
	s_waitcnt lgkmcnt(0)
	s_barrier
	s_waitcnt lgkmcnt(7)
	v_mfma_f32_16x16x32_bf16 v[124:127], v[132:135], v[174:177], v[124:127]
	v_mfma_f32_16x16x32_bf16 v[120:123], v[150:153], v[174:177], v[120:123]
	s_waitcnt lgkmcnt(5)
	v_mfma_f32_16x16x32_bf16 v[108:111], v[132:135], v[182:185], v[108:111]
	v_mfma_f32_16x16x32_bf16 v[104:107], v[150:153], v[182:185], v[104:107]
	s_waitcnt lgkmcnt(3)
	v_mfma_f32_16x16x32_bf16 v[92:95], v[132:135], v[190:193], v[92:95]
	v_mfma_f32_16x16x32_bf16 v[88:91], v[150:153], v[190:193], v[88:91]
	s_waitcnt lgkmcnt(1)
	v_mfma_f32_16x16x32_bf16 v[76:79], v[132:135], v[198:201], v[76:79]
	v_mfma_f32_16x16x32_bf16 v[72:75], v[150:153], v[198:201], v[72:75]
	v_mfma_f32_16x16x32_bf16 v[124:127], v[146:149], v[178:181], v[124:127]
	v_mfma_f32_16x16x32_bf16 v[120:123], v[154:157], v[178:181], v[120:123]
	v_mfma_f32_16x16x32_bf16 v[108:111], v[146:149], v[186:189], v[108:111]
	v_mfma_f32_16x16x32_bf16 v[104:107], v[154:157], v[186:189], v[104:107]
	v_mfma_f32_16x16x32_bf16 v[92:95], v[146:149], v[194:197], v[92:95]
	v_mfma_f32_16x16x32_bf16 v[88:91], v[154:157], v[194:197], v[88:91]
	s_waitcnt lgkmcnt(0)
	v_mfma_f32_16x16x32_bf16 v[76:79], v[146:149], v[202:205], v[76:79]
	v_mfma_f32_16x16x32_bf16 v[72:75], v[154:157], v[202:205], v[72:75]
	v_mfma_f32_16x16x32_bf16 v[116:119], v[158:161], v[174:177], v[116:119]
	v_mfma_f32_16x16x32_bf16 v[112:115], v[166:169], v[174:177], v[112:115]
	v_mfma_f32_16x16x32_bf16 v[100:103], v[158:161], v[182:185], v[100:103]
	v_mfma_f32_16x16x32_bf16 v[96:99], v[166:169], v[182:185], v[96:99]
	v_mfma_f32_16x16x32_bf16 v[84:87], v[158:161], v[190:193], v[84:87]
	v_mfma_f32_16x16x32_bf16 v[80:83], v[166:169], v[190:193], v[80:83]
	v_mfma_f32_16x16x32_bf16 v[68:71], v[158:161], v[198:201], v[68:71]
	v_mfma_f32_16x16x32_bf16 v[64:67], v[166:169], v[198:201], v[64:67]
	v_mfma_f32_16x16x32_bf16 v[116:119], v[162:165], v[178:181], v[116:119]
	v_mfma_f32_16x16x32_bf16 v[112:115], v[170:173], v[178:181], v[112:115]
	v_mfma_f32_16x16x32_bf16 v[100:103], v[162:165], v[186:189], v[100:103]
	v_mfma_f32_16x16x32_bf16 v[96:99], v[170:173], v[186:189], v[96:99]
	v_mfma_f32_16x16x32_bf16 v[84:87], v[162:165], v[194:197], v[84:87]
	v_mfma_f32_16x16x32_bf16 v[80:83], v[170:173], v[194:197], v[80:83]
	v_mfma_f32_16x16x32_bf16 v[68:71], v[162:165], v[202:205], v[68:71]
	v_mfma_f32_16x16x32_bf16 v[64:67], v[170:173], v[202:205], v[64:67]
	s_barrier
	s_mov_b32 m0, s28
	s_mov_b32 s14, s10
	s_mov_b32 s15, s11
	ds_read_b128 v[174:177], v142 offset:16384
	ds_read_b128 v[178:181], v142 offset:17408
	ds_read_b128 v[182:185], v142 offset:18432
	ds_read_b128 v[186:189], v142 offset:19456
	ds_read_b128 v[190:193], v142 offset:20480
	ds_read_b128 v[194:197], v142 offset:21504
	ds_read_b128 v[198:201], v142 offset:22528
	ds_read_b128 v[202:205], v142 offset:23552
	buffer_load_dwordx4 v137, s[12:15], s60 offen lds
	s_mov_b32 m0, s29
	s_add_i32 s62, s60, 0x160000
	buffer_load_dwordx4 v139, s[12:15], s60 offen lds
	s_mov_b32 m0, s30
	s_nop 0
	buffer_load_dwordx4 v137, s[12:15], s62 offen lds
	s_mov_b32 m0, s31
	s_nop 0
	buffer_load_dwordx4 v139, s[12:15], s62 offen lds
	s_mov_b32 m0, s27
	s_nop 0
	buffer_load_dwordx4 v136, s[8:11], s61 offen lds
	s_mov_b32 m0, s33
	s_nop 0
	buffer_load_dwordx4 v138, s[8:11], s61 offen lds
	s_waitcnt vmcnt(8)
	s_waitcnt lgkmcnt(0)
	s_barrier
	s_waitcnt lgkmcnt(7)
	v_mfma_f32_16x16x32_bf16 v[60:63], v[132:135], v[174:177], v[60:63]
	v_mfma_f32_16x16x32_bf16 v[56:59], v[150:153], v[174:177], v[56:59]
	s_waitcnt lgkmcnt(5)
	v_mfma_f32_16x16x32_bf16 v[44:47], v[132:135], v[182:185], v[44:47]
	v_mfma_f32_16x16x32_bf16 v[40:43], v[150:153], v[182:185], v[40:43]
	s_waitcnt lgkmcnt(3)
	v_mfma_f32_16x16x32_bf16 v[28:31], v[132:135], v[190:193], v[28:31]
	v_mfma_f32_16x16x32_bf16 v[24:27], v[150:153], v[190:193], v[24:27]
	s_waitcnt lgkmcnt(1)
	v_mfma_f32_16x16x32_bf16 v[12:15], v[132:135], v[198:201], v[12:15]
	v_mfma_f32_16x16x32_bf16 v[8:11], v[150:153], v[198:201], v[8:11]
	v_mfma_f32_16x16x32_bf16 v[60:63], v[146:149], v[178:181], v[60:63]
	v_mfma_f32_16x16x32_bf16 v[56:59], v[154:157], v[178:181], v[56:59]
	v_mfma_f32_16x16x32_bf16 v[44:47], v[146:149], v[186:189], v[44:47]
	v_mfma_f32_16x16x32_bf16 v[40:43], v[154:157], v[186:189], v[40:43]
	v_mfma_f32_16x16x32_bf16 v[28:31], v[146:149], v[194:197], v[28:31]
	v_mfma_f32_16x16x32_bf16 v[24:27], v[154:157], v[194:197], v[24:27]
	s_waitcnt lgkmcnt(0)
	v_mfma_f32_16x16x32_bf16 v[12:15], v[146:149], v[202:205], v[12:15]
	v_mfma_f32_16x16x32_bf16 v[8:11], v[154:157], v[202:205], v[8:11]
	v_mfma_f32_16x16x32_bf16 v[52:55], v[158:161], v[174:177], v[52:55]
	v_mfma_f32_16x16x32_bf16 v[48:51], v[166:169], v[174:177], v[48:51]
	v_mfma_f32_16x16x32_bf16 v[36:39], v[158:161], v[182:185], v[36:39]
	v_mfma_f32_16x16x32_bf16 v[32:35], v[166:169], v[182:185], v[32:35]
	v_mfma_f32_16x16x32_bf16 v[20:23], v[158:161], v[190:193], v[20:23]
	v_mfma_f32_16x16x32_bf16 v[16:19], v[166:169], v[190:193], v[16:19]
	v_mfma_f32_16x16x32_bf16 v[4:7], v[158:161], v[198:201], v[4:7]
	v_mfma_f32_16x16x32_bf16 v[0:3], v[166:169], v[198:201], v[0:3]
	v_mfma_f32_16x16x32_bf16 v[52:55], v[162:165], v[178:181], v[52:55]
	v_mfma_f32_16x16x32_bf16 v[48:51], v[170:173], v[178:181], v[48:51]
	v_mfma_f32_16x16x32_bf16 v[36:39], v[162:165], v[186:189], v[36:39]
	v_mfma_f32_16x16x32_bf16 v[32:35], v[170:173], v[186:189], v[32:35]
	v_mfma_f32_16x16x32_bf16 v[20:23], v[162:165], v[194:197], v[20:23]
	v_mfma_f32_16x16x32_bf16 v[16:19], v[170:173], v[194:197], v[16:19]
	v_mfma_f32_16x16x32_bf16 v[4:7], v[162:165], v[202:205], v[4:7]
	v_mfma_f32_16x16x32_bf16 v[0:3], v[170:173], v[202:205], v[0:3]
	s_barrier
; #define PG8_STAGE(bufoff, soff, voff) do { _Pragma("unroll") for (int _i = 0; _i < 2; ++_i) \
;         __builtin_amdgcn_raw_ptr_buffer_load_lds(rs_##voff, (PG8_LAS unsigned*)(lds + (bufoff) + ldsw + _i * 8192), 16, (int)(voff)[_i], (int)(soff), 0, 0); } while (0)
; #define PG8_BAR __builtin_amdgcn_s_barrier()
; template <class Epi, class Sched, bool ALIGN_EPI = false, bool SP2 = false>
; __device__ __forceinline__ void gemm_phase(PG8_LAS unsigned char* lds, const Gemm g, const Sched& S, const Epi& E, const int wid  ) {
;     ...
;             PG8_LDB(B0, 1, 0); PG8_LDB(B1, 1, 1); PG8_SCHED; PG8_LDA(At, 1, 0); PG8_STAGE(PG8_SA(0, 1), a2 + hstep, voffA);
;             PG8_WAIT_V(8); PG8_WAIT_L(0); PG8_BAR; PG8_MMA(0, 0, At, B0); PG8_MMA(0, 1, At, B1); PG8_BAR; PG8_SCHED;
;             PG8_LDA(At, 1, 1); PG8_STAGE(PG8_SB(1, 0), b3, voffB); PG8_STAGE(PG8_SB(1, 1), b3 + hstep, voffB); PG8_STAGE(PG8_SA(1, 0), a3, voffA);
;             PG8_WAIT_V(8); PG8_WAIT_L(0); PG8_BAR; PG8_MMA(1, 0, At, B0); PG8_MMA(1, 1, At, B1); PG8_BAR; PG8_SCHED;
;             } else {
;             PG8_LDB(B0, 0, 0); PG8_SCHED; PG8_LDA(At, 0, 0); PG8_STAGE(PG8_SA(1, 1), a1 + hstep, voffA);
;             PG8_WAIT_L(8); PG8_BAR; PG8_WAIT_L(0); PG8_MMA(0, 0, At, B0); PG8_BAR; PG8_SCHED;
;             PG8_LDB(B1, 0, 1); PG8_STAGE(PG8_SB(0, 0), b2, voffB);
;             PG8_BAR; PG8_WAIT_L(0); PG8_MMA(0, 1, At, B1); PG8_BAR;
;             PG8_LDA(At, 0, 1); PG8_STAGE(PG8_SA(0, 0), a2, voffA);
;             PG8_BAR; PG8_WAIT_L(0); PG8_MMA(1, 0, At, B0); PG8_BAR; PG8_SCHED;
;             PG8_STAGE(PG8_SB(0, 1), b2 + hstep, voffB);
;             PG8_WAIT_V(6); PG8_BAR; PG8_MMA(1, 1, At, B1); PG8_BAR;
;             PG8_LDB(B0, 1, 0); PG8_SCHED; PG8_LDA(At, 1, 0); PG8_STAGE(PG8_SA(0, 1), a2 + hstep, voffA);
;             PG8_WAIT_L(8); PG8_BAR; PG8_WAIT_L(0); PG8_MMA(0, 0, At, B0); PG8_BAR; PG8_SCHED;
;             PG8_LDB(B1, 1, 1); PG8_STAGE(PG8_SB(1, 0), b3, voffB);
;             PG8_BAR; PG8_WAIT_L(0); PG8_MMA(0, 1, At, B1); PG8_BAR;
;             PG8_LDA(At, 1, 1); PG8_STAGE(PG8_SA(1, 0), a3, voffA);
;             PG8_BAR; PG8_WAIT_L(0); PG8_MMA(1, 0, At, B0); PG8_BAR; PG8_SCHED;
;             PG8_STAGE(PG8_SB(1, 1), b3 + hstep, voffB);
;             PG8_WAIT_V(6); PG8_BAR; PG8_MMA(1, 1, At, B1); PG8_BAR;
;             }
;         }
;         if constexpr (ALIGN_EPI) { if (wr == 0) PG8_BAR; }
	ds_read_b128 v[132:135], v143
	ds_read_b128 v[146:149], v143 offset:1024
	ds_read_b128 v[150:153], v143 offset:2048
	ds_read_b128 v[154:157], v143 offset:3072
	ds_read_b128 v[158:161], v144
	ds_read_b128 v[162:165], v144 offset:1024
	ds_read_b128 v[166:169], v144 offset:2048
	ds_read_b128 v[170:173], v144 offset:3072
	s_add_i32 s61, s61, 0x160000
	s_mov_b32 m0, s34
	ds_read_b128 v[174:177], v142 offset:32768
	ds_read_b128 v[178:181], v142 offset:33792
	ds_read_b128 v[182:185], v142 offset:34816
	ds_read_b128 v[186:189], v142 offset:35840
	ds_read_b128 v[190:193], v142 offset:36864
	ds_read_b128 v[194:197], v142 offset:37888
	ds_read_b128 v[198:201], v142 offset:38912
	ds_read_b128 v[202:205], v142 offset:39936
	buffer_load_dwordx4 v136, s[8:11], s61 offen lds
	s_mov_b32 m0, s35
	s_nop 0
	buffer_load_dwordx4 v138, s[8:11], s61 offen lds
	s_waitcnt vmcnt(8)
	s_waitcnt lgkmcnt(0)
	s_barrier
	s_waitcnt lgkmcnt(7)
	v_mfma_f32_16x16x32_bf16 v[124:127], v[132:135], v[174:177], v[124:127]
	v_mfma_f32_16x16x32_bf16 v[120:123], v[150:153], v[174:177], v[120:123]
	s_waitcnt lgkmcnt(5)
	v_mfma_f32_16x16x32_bf16 v[108:111], v[132:135], v[182:185], v[108:111]
	v_mfma_f32_16x16x32_bf16 v[104:107], v[150:153], v[182:185], v[104:107]
	s_waitcnt lgkmcnt(3)
	v_mfma_f32_16x16x32_bf16 v[92:95], v[132:135], v[190:193], v[92:95]
	v_mfma_f32_16x16x32_bf16 v[88:91], v[150:153], v[190:193], v[88:91]
	s_waitcnt lgkmcnt(1)
	v_mfma_f32_16x16x32_bf16 v[76:79], v[132:135], v[198:201], v[76:79]
	v_mfma_f32_16x16x32_bf16 v[72:75], v[150:153], v[198:201], v[72:75]
	v_mfma_f32_16x16x32_bf16 v[124:127], v[146:149], v[178:181], v[124:127]
	v_mfma_f32_16x16x32_bf16 v[120:123], v[154:157], v[178:181], v[120:123]
	v_mfma_f32_16x16x32_bf16 v[108:111], v[146:149], v[186:189], v[108:111]
	v_mfma_f32_16x16x32_bf16 v[104:107], v[154:157], v[186:189], v[104:107]
	v_mfma_f32_16x16x32_bf16 v[92:95], v[146:149], v[194:197], v[92:95]
	v_mfma_f32_16x16x32_bf16 v[88:91], v[154:157], v[194:197], v[88:91]
	s_waitcnt lgkmcnt(0)
	v_mfma_f32_16x16x32_bf16 v[76:79], v[146:149], v[202:205], v[76:79]
	v_mfma_f32_16x16x32_bf16 v[72:75], v[154:157], v[202:205], v[72:75]
	v_mfma_f32_16x16x32_bf16 v[116:119], v[158:161], v[174:177], v[116:119]
	v_mfma_f32_16x16x32_bf16 v[112:115], v[166:169], v[174:177], v[112:115]
	v_mfma_f32_16x16x32_bf16 v[100:103], v[158:161], v[182:185], v[100:103]
	v_mfma_f32_16x16x32_bf16 v[96:99], v[166:169], v[182:185], v[96:99]
	v_mfma_f32_16x16x32_bf16 v[84:87], v[158:161], v[190:193], v[84:87]
	v_mfma_f32_16x16x32_bf16 v[80:83], v[166:169], v[190:193], v[80:83]
	v_mfma_f32_16x16x32_bf16 v[68:71], v[158:161], v[198:201], v[68:71]
	v_mfma_f32_16x16x32_bf16 v[64:67], v[166:169], v[198:201], v[64:67]
	v_mfma_f32_16x16x32_bf16 v[116:119], v[162:165], v[178:181], v[116:119]
	v_mfma_f32_16x16x32_bf16 v[112:115], v[170:173], v[178:181], v[112:115]
	v_mfma_f32_16x16x32_bf16 v[100:103], v[162:165], v[186:189], v[100:103]
	v_mfma_f32_16x16x32_bf16 v[96:99], v[170:173], v[186:189], v[96:99]
	v_mfma_f32_16x16x32_bf16 v[84:87], v[162:165], v[194:197], v[84:87]
	v_mfma_f32_16x16x32_bf16 v[80:83], v[170:173], v[194:197], v[80:83]
	v_mfma_f32_16x16x32_bf16 v[68:71], v[162:165], v[202:205], v[68:71]
	v_mfma_f32_16x16x32_bf16 v[64:67], v[170:173], v[202:205], v[64:67]
	s_barrier
	s_mov_b32 m0, s36
	s_or_b32 s61, s60, 0x80
	ds_read_b128 v[174:177], v142 offset:49152
	ds_read_b128 v[178:181], v142 offset:50176
	ds_read_b128 v[182:185], v142 offset:51200
	ds_read_b128 v[186:189], v142 offset:52224
	ds_read_b128 v[190:193], v142 offset:53248
	ds_read_b128 v[194:197], v142 offset:54272
	ds_read_b128 v[198:201], v142 offset:55296
	ds_read_b128 v[202:205], v142 offset:56320
	buffer_load_dwordx4 v137, s[12:15], s61 offen lds
	s_mov_b32 m0, s37
	s_add_i32 s60, s60, 0x160080
	buffer_load_dwordx4 v139, s[12:15], s61 offen lds
	s_mov_b32 m0, s40
	s_nop 0
	buffer_load_dwordx4 v137, s[12:15], s60 offen lds
	s_mov_b32 m0, s41
	s_nop 0
	buffer_load_dwordx4 v139, s[12:15], s60 offen lds
	s_mov_b32 m0, s38
	s_nop 0
	buffer_load_dwordx4 v136, s[8:11], s59 offen lds
	s_mov_b32 m0, s39
	s_nop 0
	buffer_load_dwordx4 v138, s[8:11], s59 offen lds
	s_waitcnt vmcnt(8)
	s_waitcnt lgkmcnt(0)
	s_barrier
	s_waitcnt lgkmcnt(7)
	v_mfma_f32_16x16x32_bf16 v[60:63], v[132:135], v[174:177], v[60:63]
	v_mfma_f32_16x16x32_bf16 v[56:59], v[150:153], v[174:177], v[56:59]
	s_waitcnt lgkmcnt(5)
	v_mfma_f32_16x16x32_bf16 v[44:47], v[132:135], v[182:185], v[44:47]
	v_mfma_f32_16x16x32_bf16 v[40:43], v[150:153], v[182:185], v[40:43]
	s_waitcnt lgkmcnt(3)
	v_mfma_f32_16x16x32_bf16 v[28:31], v[132:135], v[190:193], v[28:31]
	v_mfma_f32_16x16x32_bf16 v[24:27], v[150:153], v[190:193], v[24:27]
	s_waitcnt lgkmcnt(1)
	v_mfma_f32_16x16x32_bf16 v[12:15], v[132:135], v[198:201], v[12:15]
	v_mfma_f32_16x16x32_bf16 v[8:11], v[150:153], v[198:201], v[8:11]
	v_mfma_f32_16x16x32_bf16 v[60:63], v[146:149], v[178:181], v[60:63]
	v_mfma_f32_16x16x32_bf16 v[56:59], v[154:157], v[178:181], v[56:59]
	v_mfma_f32_16x16x32_bf16 v[44:47], v[146:149], v[186:189], v[44:47]
	v_mfma_f32_16x16x32_bf16 v[40:43], v[154:157], v[186:189], v[40:43]
	v_mfma_f32_16x16x32_bf16 v[28:31], v[146:149], v[194:197], v[28:31]
	v_mfma_f32_16x16x32_bf16 v[24:27], v[154:157], v[194:197], v[24:27]
	s_waitcnt lgkmcnt(0)
	v_mfma_f32_16x16x32_bf16 v[12:15], v[146:149], v[202:205], v[12:15]
	v_mfma_f32_16x16x32_bf16 v[8:11], v[154:157], v[202:205], v[8:11]
	v_mfma_f32_16x16x32_bf16 v[52:55], v[158:161], v[174:177], v[52:55]
	v_mfma_f32_16x16x32_bf16 v[48:51], v[166:169], v[174:177], v[48:51]
	v_mfma_f32_16x16x32_bf16 v[36:39], v[158:161], v[182:185], v[36:39]
	v_mfma_f32_16x16x32_bf16 v[32:35], v[166:169], v[182:185], v[32:35]
	v_mfma_f32_16x16x32_bf16 v[20:23], v[158:161], v[190:193], v[20:23]
	v_mfma_f32_16x16x32_bf16 v[16:19], v[166:169], v[190:193], v[16:19]
	v_mfma_f32_16x16x32_bf16 v[4:7], v[158:161], v[198:201], v[4:7]
	v_mfma_f32_16x16x32_bf16 v[0:3], v[166:169], v[198:201], v[0:3]
	v_mfma_f32_16x16x32_bf16 v[52:55], v[162:165], v[178:181], v[52:55]
	v_mfma_f32_16x16x32_bf16 v[48:51], v[170:173], v[178:181], v[48:51]
	v_mfma_f32_16x16x32_bf16 v[36:39], v[162:165], v[186:189], v[36:39]
	v_mfma_f32_16x16x32_bf16 v[32:35], v[170:173], v[186:189], v[32:35]
	v_mfma_f32_16x16x32_bf16 v[20:23], v[162:165], v[194:197], v[20:23]
	v_mfma_f32_16x16x32_bf16 v[16:19], v[170:173], v[194:197], v[16:19]
	v_mfma_f32_16x16x32_bf16 v[4:7], v[162:165], v[202:205], v[4:7]
	v_mfma_f32_16x16x32_bf16 v[0:3], v[170:173], v[202:205], v[0:3]
	s_barrier
	s_add_i32 s58, s58, 2
	s_addk_i32 s54, 0x100
	s_addk_i32 s55, 0x100
	s_cmpk_gt_u32 s58, 0x55
	s_cbranch_scc0 .LBB0_804
	s_and_b64 vcc, exec, s[24:25]
	s_cbranch_vccz .LBB0_807
	s_barrier

; __device__ __forceinline__ unsigned xb_ld(unsigned* p)              { return __hip_atomic_load(p, __ATOMIC_RELAXED, __HIP_MEMORY_SCOPE_AGENT); }
; __device__ __forceinline__ unsigned xb_add(unsigned* p, unsigned v) { return __hip_atomic_fetch_add(p, v, __ATOMIC_RELAXED, __HIP_MEMORY_SCOPE_AGENT); }
; __device__ __forceinline__ void xcd_barrier_complete(unsigned* bar, unsigned x, unsigned& nloc, unsigned& nx) {
;     const unsigned G = gridDim.x * gridDim.y * gridDim.z;
;     unsigned sum, cnt, mine, sp = 0u;
;     for (;;) {
;         sum = 0u; cnt = 0u; mine = 0u;
; #pragma unroll
;         for (unsigned j = 0; j < 16; ++j) { const unsigned c = xb_ld(&bar[XB_XCNT(j)]); sum += c; cnt += (c > 0u) ? 1u : 0u; mine = (j == x) ? c : mine; }
; __device__ __forceinline__ void xcd_barrier(const XcdBarrier& b) {
;     asm volatile("s_waitcnt vmcnt(0)" ::: "memory");
;     __syncthreads();
;     if (threadIdx.x == 0) {
;         unsigned* bar = b.bar;
;         __builtin_amdgcn_s_waitcnt(0);
;         unsigned nloc = b.st[0], nx = b.st[1];
;         if (nloc == 0u) { xcd_barrier_complete(bar, b.x, nloc, nx); b.st[0] = nloc; b.st[1] = nx; }
;         const unsigned old = xb_add(&bar[XB_XSUB(b.x)], 1u);
.LBB0_831:
	s_setprio 0
	s_add_i32 s0, 0, 0x20520
	v_mov_b32_e32 v0, s0
	s_waitcnt lgkmcnt(0)
	ds_read_b64 v[0:1], v0
	s_getreg_b32 s3, hwreg(HW_REG_XCC_ID, 0, 4)
	s_waitcnt vmcnt(0)
	s_waitcnt lgkmcnt(0)
	s_barrier
	v_readfirstlane_b32 s4, v0
	v_readfirstlane_b32 s5, v1
	s_mov_b64 s[0:1], exec
	v_readlane_b32 s6, v246, 2
	v_readlane_b32 s7, v246, 3
	s_and_b64 s[6:7], s[0:1], s[6:7]
	s_mov_b64 exec, s[6:7]
	s_cbranch_execz .LBB0_883
	s_add_i32 s6, 0, 0x20160
	v_mov_b32_e32 v0, s6
	s_waitcnt vmcnt(0) expcnt(0) lgkmcnt(0)
	ds_read_b32 v2, v0
	s_add_i32 s6, 0, 0x20164
	v_mov_b32_e32 v0, s6
	ds_read_b32 v0, v0
	s_and_b32 s3, s3, 15
	s_waitcnt lgkmcnt(1)
	v_cmp_ne_u32_e32 vcc, 0, v2
	s_cbranch_vccnz .LBB0_847
	v_readlane_b32 s6, v246, 0
	v_readlane_b32 s7, v246, 1
	s_load_dwordx2 s[10:11], s[6:7], 0x4
	s_add_u32 s6, s4, 0x4200
	s_addc_u32 s7, s5, 0
	s_add_u32 s8, s4, 0x4400
	s_addc_u32 s9, s5, 0
	s_waitcnt lgkmcnt(0)
	s_mul_i32 s33, s10, s52
	s_add_u32 s10, s4, 0x4500
	s_mul_i32 s33, s33, s11
	s_addc_u32 s11, s5, 0
	s_add_u32 s12, s4, 0x4600
	s_addc_u32 s13, s5, 0
	s_add_u32 s14, s4, 0x4700
	s_addc_u32 s15, s5, 0
	s_add_u32 s16, s4, 0x4800
	s_addc_u32 s17, s5, 0
	s_add_u32 s18, s4, 0x4900
	s_addc_u32 s19, s5, 0
	s_add_u32 s20, s4, 0x4a00
	s_addc_u32 s21, s5, 0
	s_add_u32 s22, s4, 0x4b00
	s_addc_u32 s23, s5, 0
	s_add_u32 s24, s4, 0x4c00
	s_addc_u32 s25, s5, 0
	s_add_u32 s26, s4, 0x4d00
	s_addc_u32 s27, s5, 0
	s_add_u32 s28, s4, 0x4e00
	s_addc_u32 s29, s5, 0
	s_add_u32 s30, s4, 0x4f00
	s_addc_u32 s31, s5, 0
	s_add_u32 s36, s4, 0x5000
	s_addc_u32 s37, s5, 0
	s_add_u32 s38, s4, 0x5100
	s_addc_u32 s39, s5, 0
	s_add_u32 s40, s4, 0x5200
	s_addc_u32 s41, s5, 0
	s_add_u32 s42, s4, 0x5300
	s_addc_u32 s43, s5, 0
	s_mov_b32 s34, 1
	v_mov_b32_e32 v16, 0
	s_branch .LBB0_835

; #define PG8_STAGE(bufoff, soff, voff) do { _Pragma("unroll") for (int _i = 0; _i < 2; ++_i) \
;         __builtin_amdgcn_raw_ptr_buffer_load_lds(rs_##voff, (PG8_LAS unsigned*)(lds + (bufoff) + ldsw + _i * 8192), 16, (int)(voff)[_i], (int)(soff), 0, 0); } while (0)
; #define PG8_LDA(dst, b, h) do { _Pragma("unroll") for (int m = 0; m < 4; ++m) _Pragma("unroll") for (int k = 0; k < 2; ++k) dst[m][k] = *(const PG8_LAS bf16x8*)(lds + PG8_SA(b, h) + aoff + m * 2048 + k * 1024); } while (0)
; #define PG8_LDB(dst, b, h) do { _Pragma("unroll") for (int n = 0; n < 2; ++n) _Pragma("unroll") for (int k = 0; k < 2; ++k) dst[n][k] = *(const PG8_LAS bf16x8*)(lds + PG8_SB(b, h) + boff + n * 2048 + k * 1024); } while (0)
; #define PG8_MMA(ai, bj, At, Bt) do { __builtin_amdgcn_s_setprio(1); _Pragma("unroll") for (int m = 0; m < 4; ++m) _Pragma("unroll") for (int n = 0; n < 2; ++n) _Pragma("unroll") for (int k = 0; k < 2; ++k) \
;         acc[ai][bj][m][n] = __builtin_amdgcn_mfma_f32_16x16x32_bf16(Bt[n][k], At[m][k], acc[ai][bj][m][n], 0, 0, 0); __builtin_amdgcn_s_setprio(0); } while (0)
; #define PG8_WAIT_V(n) asm volatile("s_waitcnt vmcnt(" #n ")" ::: "memory")
; #define PG8_BAR __builtin_amdgcn_s_barrier()
; template <class Epi, class Sched, bool ALIGN_EPI = false, bool SP2 = false>
; __device__ __forceinline__ void gemm_phase(PG8_LAS unsigned char* lds, const Gemm g, const Sched& S, const Epi& E, const int wid  ) {
;     ...
;         for (int t = 0; t < nt; t += 2) {
;             const bool last = (t == nt - 2);
;             const unsigned a1 = cA + (unsigned)(t + 1) * kstep;
;             const unsigned a2 = last ? nA : cA + (unsigned)(t + 2) * kstep, b2 = last ? nB : cB + (unsigned)(t + 2) * kstep;
;             const unsigned a3 = a2 + kstep, b3 = b2 + kstep;
;             if (last && has_next) S.a_ready(nxt);
;             if constexpr (SP2) {
;             PG8_LDB(B0, 0, 0); PG8_LDB(B1, 0, 1); PG8_SCHED; PG8_LDA(At, 0, 0); PG8_STAGE(PG8_SA(1, 1), a1 + hstep, voffA);
;             PG8_WAIT_V(8); PG8_WAIT_L(0); PG8_BAR; PG8_MMA(0, 0, At, B0); PG8_MMA(0, 1, At, B1); PG8_BAR; PG8_SCHED;
;             PG8_LDA(At, 0, 1); PG8_STAGE(PG8_SB(0, 0), b2, voffB); PG8_STAGE(PG8_SB(0, 1), b2 + hstep, voffB); PG8_STAGE(PG8_SA(0, 0), a2, voffA);
;             PG8_WAIT_V(8); PG8_WAIT_L(0); PG8_BAR; PG8_MMA(1, 0, At, B0); PG8_MMA(1, 1, At, B1); PG8_BAR; PG8_SCHED;
.Lprio_903:
.LBB0_903:
	ds_read_b128 v[132:135], v152
	ds_read_b128 v[136:139], v152 offset:1024
	ds_read_b128 v[140:143], v152 offset:2048
	ds_read_b128 v[158:161], v152 offset:3072
	ds_read_b128 v[162:165], v153
	ds_read_b128 v[166:169], v153 offset:1024
	ds_read_b128 v[170:173], v153 offset:2048
	ds_read_b128 v[174:177], v153 offset:3072
	s_add_i32 s14, s41, 0xfff80080
	s_cmp_eq_u32 s75, 28
	s_cselect_b32 s78, s33, s14
	s_cselect_b32 s77, s40, s74
	s_or_b32 s76, s78, 0x80
	s_mov_b32 m0, s60
	ds_read_b128 v[178:181], v154
	ds_read_b128 v[182:185], v154 offset:1024
	ds_read_b128 v[186:189], v154 offset:2048
	ds_read_b128 v[190:193], v154 offset:3072
	ds_read_b128 v[194:197], v154 offset:4096
	ds_read_b128 v[198:201], v154 offset:5120
	ds_read_b128 v[202:205], v154 offset:6144
	ds_read_b128 v[206:209], v154 offset:7168
	buffer_load_dwordx4 v146, s[8:11], s41 offen lds
	s_mov_b32 m0, s61
	s_nop 0
	buffer_load_dwordx4 v148, s[8:11], s41 offen lds
	s_waitcnt vmcnt(8)
	s_waitcnt lgkmcnt(0)
	s_barrier
	s_waitcnt lgkmcnt(7)
	v_mfma_f32_16x16x32_bf16 v[124:127], v[132:135], v[178:181], v[124:127]
	v_mfma_f32_16x16x32_bf16 v[120:123], v[140:143], v[178:181], v[120:123]
	s_waitcnt lgkmcnt(5)
	v_mfma_f32_16x16x32_bf16 v[108:111], v[132:135], v[186:189], v[108:111]
	v_mfma_f32_16x16x32_bf16 v[104:107], v[140:143], v[186:189], v[104:107]
	s_waitcnt lgkmcnt(3)
	v_mfma_f32_16x16x32_bf16 v[92:95], v[132:135], v[194:197], v[92:95]
	v_mfma_f32_16x16x32_bf16 v[88:91], v[140:143], v[194:197], v[88:91]
	s_waitcnt lgkmcnt(1)
	v_mfma_f32_16x16x32_bf16 v[76:79], v[132:135], v[202:205], v[76:79]
	v_mfma_f32_16x16x32_bf16 v[72:75], v[140:143], v[202:205], v[72:75]
	v_mfma_f32_16x16x32_bf16 v[124:127], v[136:139], v[182:185], v[124:127]
	v_mfma_f32_16x16x32_bf16 v[120:123], v[158:161], v[182:185], v[120:123]
	v_mfma_f32_16x16x32_bf16 v[108:111], v[136:139], v[190:193], v[108:111]
	v_mfma_f32_16x16x32_bf16 v[104:107], v[158:161], v[190:193], v[104:107]
	v_mfma_f32_16x16x32_bf16 v[92:95], v[136:139], v[198:201], v[92:95]
	v_mfma_f32_16x16x32_bf16 v[88:91], v[158:161], v[198:201], v[88:91]
	s_waitcnt lgkmcnt(0)
	v_mfma_f32_16x16x32_bf16 v[76:79], v[136:139], v[206:209], v[76:79]
	v_mfma_f32_16x16x32_bf16 v[72:75], v[158:161], v[206:209], v[72:75]
	v_mfma_f32_16x16x32_bf16 v[116:119], v[162:165], v[178:181], v[116:119]
	v_mfma_f32_16x16x32_bf16 v[112:115], v[170:173], v[178:181], v[112:115]
	v_mfma_f32_16x16x32_bf16 v[100:103], v[162:165], v[186:189], v[100:103]
	v_mfma_f32_16x16x32_bf16 v[96:99], v[170:173], v[186:189], v[96:99]
	v_mfma_f32_16x16x32_bf16 v[84:87], v[162:165], v[194:197], v[84:87]
	v_mfma_f32_16x16x32_bf16 v[80:83], v[170:173], v[194:197], v[80:83]
	v_mfma_f32_16x16x32_bf16 v[68:71], v[162:165], v[202:205], v[68:71]
	v_mfma_f32_16x16x32_bf16 v[64:67], v[170:173], v[202:205], v[64:67]
	v_mfma_f32_16x16x32_bf16 v[116:119], v[166:169], v[182:185], v[116:119]
	v_mfma_f32_16x16x32_bf16 v[112:115], v[174:177], v[182:185], v[112:115]
	v_mfma_f32_16x16x32_bf16 v[100:103], v[166:169], v[190:193], v[100:103]
	v_mfma_f32_16x16x32_bf16 v[96:99], v[174:177], v[190:193], v[96:99]
	v_mfma_f32_16x16x32_bf16 v[84:87], v[166:169], v[198:201], v[84:87]
	v_mfma_f32_16x16x32_bf16 v[80:83], v[174:177], v[198:201], v[80:83]
	v_mfma_f32_16x16x32_bf16 v[68:71], v[166:169], v[206:209], v[68:71]
	v_mfma_f32_16x16x32_bf16 v[64:67], v[174:177], v[206:209], v[64:67]
	s_barrier
	s_mov_b32 m0, s35
	s_mov_b32 s14, s10
	s_mov_b32 s15, s11
	ds_read_b128 v[178:181], v154 offset:16384
	ds_read_b128 v[182:185], v154 offset:17408
	ds_read_b128 v[186:189], v154 offset:18432
	ds_read_b128 v[190:193], v154 offset:19456
	ds_read_b128 v[194:197], v154 offset:20480
	ds_read_b128 v[198:201], v154 offset:21504
	ds_read_b128 v[202:205], v154 offset:22528
	ds_read_b128 v[206:209], v154 offset:23552
	buffer_load_dwordx4 v147, s[12:15], s77 offen lds
	s_mov_b32 m0, s42
	s_add_i32 s79, s77, 0x80000
	buffer_load_dwordx4 v149, s[12:15], s77 offen lds
	s_mov_b32 m0, s43
	s_nop 0
	buffer_load_dwordx4 v147, s[12:15], s79 offen lds
	s_mov_b32 m0, s44
	s_nop 0
	buffer_load_dwordx4 v149, s[12:15], s79 offen lds
	s_mov_b32 m0, s34
	s_nop 0
	buffer_load_dwordx4 v146, s[8:11], s78 offen lds
	s_mov_b32 m0, s45
	s_nop 0
	buffer_load_dwordx4 v148, s[8:11], s78 offen lds
	s_waitcnt vmcnt(8)
	s_waitcnt lgkmcnt(0)
	s_barrier
	s_waitcnt lgkmcnt(7)
	v_mfma_f32_16x16x32_bf16 v[60:63], v[132:135], v[178:181], v[60:63]
	v_mfma_f32_16x16x32_bf16 v[56:59], v[140:143], v[178:181], v[56:59]
	s_waitcnt lgkmcnt(5)
	v_mfma_f32_16x16x32_bf16 v[44:47], v[132:135], v[186:189], v[44:47]
	v_mfma_f32_16x16x32_bf16 v[40:43], v[140:143], v[186:189], v[40:43]
	s_waitcnt lgkmcnt(3)
	v_mfma_f32_16x16x32_bf16 v[28:31], v[132:135], v[194:197], v[28:31]
	v_mfma_f32_16x16x32_bf16 v[24:27], v[140:143], v[194:197], v[24:27]
	s_waitcnt lgkmcnt(1)
	v_mfma_f32_16x16x32_bf16 v[12:15], v[132:135], v[202:205], v[12:15]
	v_mfma_f32_16x16x32_bf16 v[8:11], v[140:143], v[202:205], v[8:11]
	v_mfma_f32_16x16x32_bf16 v[60:63], v[136:139], v[182:185], v[60:63]
	v_mfma_f32_16x16x32_bf16 v[56:59], v[158:161], v[182:185], v[56:59]
	v_mfma_f32_16x16x32_bf16 v[44:47], v[136:139], v[190:193], v[44:47]
	v_mfma_f32_16x16x32_bf16 v[40:43], v[158:161], v[190:193], v[40:43]
	v_mfma_f32_16x16x32_bf16 v[28:31], v[136:139], v[198:201], v[28:31]
	v_mfma_f32_16x16x32_bf16 v[24:27], v[158:161], v[198:201], v[24:27]
	s_waitcnt lgkmcnt(0)
	v_mfma_f32_16x16x32_bf16 v[12:15], v[136:139], v[206:209], v[12:15]
	v_mfma_f32_16x16x32_bf16 v[8:11], v[158:161], v[206:209], v[8:11]
	v_mfma_f32_16x16x32_bf16 v[52:55], v[162:165], v[178:181], v[52:55]
	v_mfma_f32_16x16x32_bf16 v[48:51], v[170:173], v[178:181], v[48:51]
	v_mfma_f32_16x16x32_bf16 v[36:39], v[162:165], v[186:189], v[36:39]
	v_mfma_f32_16x16x32_bf16 v[32:35], v[170:173], v[186:189], v[32:35]
	v_mfma_f32_16x16x32_bf16 v[20:23], v[162:165], v[194:197], v[20:23]
	v_mfma_f32_16x16x32_bf16 v[16:19], v[170:173], v[194:197], v[16:19]
	v_mfma_f32_16x16x32_bf16 v[4:7], v[162:165], v[202:205], v[4:7]
	v_mfma_f32_16x16x32_bf16 v[0:3], v[170:173], v[202:205], v[0:3]
	v_mfma_f32_16x16x32_bf16 v[52:55], v[166:169], v[182:185], v[52:55]
	v_mfma_f32_16x16x32_bf16 v[48:51], v[174:177], v[182:185], v[48:51]
	v_mfma_f32_16x16x32_bf16 v[36:39], v[166:169], v[190:193], v[36:39]
	v_mfma_f32_16x16x32_bf16 v[32:35], v[174:177], v[190:193], v[32:35]
	v_mfma_f32_16x16x32_bf16 v[20:23], v[166:169], v[198:201], v[20:23]
	v_mfma_f32_16x16x32_bf16 v[16:19], v[174:177], v[198:201], v[16:19]
	v_mfma_f32_16x16x32_bf16 v[4:7], v[166:169], v[206:209], v[4:7]
	v_mfma_f32_16x16x32_bf16 v[0:3], v[174:177], v[206:209], v[0:3]
	s_barrier
; #define PG8_STAGE(bufoff, soff, voff) do { _Pragma("unroll") for (int _i = 0; _i < 2; ++_i) \
;         __builtin_amdgcn_raw_ptr_buffer_load_lds(rs_##voff, (PG8_LAS unsigned*)(lds + (bufoff) + ldsw + _i * 8192), 16, (int)(voff)[_i], (int)(soff), 0, 0); } while (0)
; #define PG8_BAR __builtin_amdgcn_s_barrier()
; template <class Epi, class Sched, bool ALIGN_EPI = false, bool SP2 = false>
; __device__ __forceinline__ void gemm_phase(PG8_LAS unsigned char* lds, const Gemm g, const Sched& S, const Epi& E, const int wid  ) {
;     ...
;             PG8_LDB(B0, 1, 0); PG8_LDB(B1, 1, 1); PG8_SCHED; PG8_LDA(At, 1, 0); PG8_STAGE(PG8_SA(0, 1), a2 + hstep, voffA);
;             PG8_WAIT_V(8); PG8_WAIT_L(0); PG8_BAR; PG8_MMA(0, 0, At, B0); PG8_MMA(0, 1, At, B1); PG8_BAR; PG8_SCHED;
;             PG8_LDA(At, 1, 1); PG8_STAGE(PG8_SB(1, 0), b3, voffB); PG8_STAGE(PG8_SB(1, 1), b3 + hstep, voffB); PG8_STAGE(PG8_SA(1, 0), a3, voffA);
;             PG8_WAIT_V(8); PG8_WAIT_L(0); PG8_BAR; PG8_MMA(1, 0, At, B0); PG8_MMA(1, 1, At, B1); PG8_BAR; PG8_SCHED;
;             } else {
;             PG8_LDB(B0, 0, 0); PG8_SCHED; PG8_LDA(At, 0, 0); PG8_STAGE(PG8_SA(1, 1), a1 + hstep, voffA);
;             PG8_WAIT_L(8); PG8_BAR; PG8_WAIT_L(0); PG8_MMA(0, 0, At, B0); PG8_BAR; PG8_SCHED;
;             PG8_LDB(B1, 0, 1); PG8_STAGE(PG8_SB(0, 0), b2, voffB);
;             PG8_BAR; PG8_WAIT_L(0); PG8_MMA(0, 1, At, B1); PG8_BAR;
;             PG8_LDA(At, 0, 1); PG8_STAGE(PG8_SA(0, 0), a2, voffA);
;             PG8_BAR; PG8_WAIT_L(0); PG8_MMA(1, 0, At, B0); PG8_BAR; PG8_SCHED;
;             PG8_STAGE(PG8_SB(0, 1), b2 + hstep, voffB);
;             PG8_WAIT_V(6); PG8_BAR; PG8_MMA(1, 1, At, B1); PG8_BAR;
;             PG8_LDB(B0, 1, 0); PG8_SCHED; PG8_LDA(At, 1, 0); PG8_STAGE(PG8_SA(0, 1), a2 + hstep, voffA);
;             PG8_WAIT_L(8); PG8_BAR; PG8_WAIT_L(0); PG8_MMA(0, 0, At, B0); PG8_BAR; PG8_SCHED;
;             PG8_LDB(B1, 1, 1); PG8_STAGE(PG8_SB(1, 0), b3, voffB);
;             PG8_BAR; PG8_WAIT_L(0); PG8_MMA(0, 1, At, B1); PG8_BAR;
;             PG8_LDA(At, 1, 1); PG8_STAGE(PG8_SA(1, 0), a3, voffA);
;             PG8_BAR; PG8_WAIT_L(0); PG8_MMA(1, 0, At, B0); PG8_BAR; PG8_SCHED;
;             PG8_STAGE(PG8_SB(1, 1), b3 + hstep, voffB);
;             PG8_WAIT_V(6); PG8_BAR; PG8_MMA(1, 1, At, B1); PG8_BAR;
;             }
;         }
;         if constexpr (ALIGN_EPI) { if (wr == 0) PG8_BAR; }
	ds_read_b128 v[132:135], v155
	ds_read_b128 v[136:139], v155 offset:1024
	ds_read_b128 v[140:143], v155 offset:2048
	ds_read_b128 v[158:161], v155 offset:3072
	ds_read_b128 v[162:165], v156
	ds_read_b128 v[166:169], v156 offset:1024
	ds_read_b128 v[170:173], v156 offset:2048
	ds_read_b128 v[174:177], v156 offset:3072
	s_add_i32 s78, s78, 0x80000
	s_mov_b32 m0, s46
	ds_read_b128 v[178:181], v154 offset:32768
	ds_read_b128 v[182:185], v154 offset:33792
	ds_read_b128 v[186:189], v154 offset:34816
	ds_read_b128 v[190:193], v154 offset:35840
	ds_read_b128 v[194:197], v154 offset:36864
	ds_read_b128 v[198:201], v154 offset:37888
	ds_read_b128 v[202:205], v154 offset:38912
	ds_read_b128 v[206:209], v154 offset:39936
	buffer_load_dwordx4 v146, s[8:11], s78 offen lds
	s_mov_b32 m0, s48
	s_nop 0
	buffer_load_dwordx4 v148, s[8:11], s78 offen lds
	s_waitcnt vmcnt(8)
	s_waitcnt lgkmcnt(0)
	s_barrier
	s_waitcnt lgkmcnt(7)
	v_mfma_f32_16x16x32_bf16 v[124:127], v[132:135], v[178:181], v[124:127]
	v_mfma_f32_16x16x32_bf16 v[120:123], v[140:143], v[178:181], v[120:123]
	s_waitcnt lgkmcnt(5)
	v_mfma_f32_16x16x32_bf16 v[108:111], v[132:135], v[186:189], v[108:111]
	v_mfma_f32_16x16x32_bf16 v[104:107], v[140:143], v[186:189], v[104:107]
	s_waitcnt lgkmcnt(3)
	v_mfma_f32_16x16x32_bf16 v[92:95], v[132:135], v[194:197], v[92:95]
	v_mfma_f32_16x16x32_bf16 v[88:91], v[140:143], v[194:197], v[88:91]
	s_waitcnt lgkmcnt(1)
	v_mfma_f32_16x16x32_bf16 v[76:79], v[132:135], v[202:205], v[76:79]
	v_mfma_f32_16x16x32_bf16 v[72:75], v[140:143], v[202:205], v[72:75]
	v_mfma_f32_16x16x32_bf16 v[124:127], v[136:139], v[182:185], v[124:127]
	v_mfma_f32_16x16x32_bf16 v[120:123], v[158:161], v[182:185], v[120:123]
	v_mfma_f32_16x16x32_bf16 v[108:111], v[136:139], v[190:193], v[108:111]
	v_mfma_f32_16x16x32_bf16 v[104:107], v[158:161], v[190:193], v[104:107]
	v_mfma_f32_16x16x32_bf16 v[92:95], v[136:139], v[198:201], v[92:95]
	v_mfma_f32_16x16x32_bf16 v[88:91], v[158:161], v[198:201], v[88:91]
	s_waitcnt lgkmcnt(0)
	v_mfma_f32_16x16x32_bf16 v[76:79], v[136:139], v[206:209], v[76:79]
	v_mfma_f32_16x16x32_bf16 v[72:75], v[158:161], v[206:209], v[72:75]
	v_mfma_f32_16x16x32_bf16 v[116:119], v[162:165], v[178:181], v[116:119]
	v_mfma_f32_16x16x32_bf16 v[112:115], v[170:173], v[178:181], v[112:115]
	v_mfma_f32_16x16x32_bf16 v[100:103], v[162:165], v[186:189], v[100:103]
	v_mfma_f32_16x16x32_bf16 v[96:99], v[170:173], v[186:189], v[96:99]
	v_mfma_f32_16x16x32_bf16 v[84:87], v[162:165], v[194:197], v[84:87]
	v_mfma_f32_16x16x32_bf16 v[80:83], v[170:173], v[194:197], v[80:83]
	v_mfma_f32_16x16x32_bf16 v[68:71], v[162:165], v[202:205], v[68:71]
	v_mfma_f32_16x16x32_bf16 v[64:67], v[170:173], v[202:205], v[64:67]
	v_mfma_f32_16x16x32_bf16 v[116:119], v[166:169], v[182:185], v[116:119]
	v_mfma_f32_16x16x32_bf16 v[112:115], v[174:177], v[182:185], v[112:115]
	v_mfma_f32_16x16x32_bf16 v[100:103], v[166:169], v[190:193], v[100:103]
	v_mfma_f32_16x16x32_bf16 v[96:99], v[174:177], v[190:193], v[96:99]
	v_mfma_f32_16x16x32_bf16 v[84:87], v[166:169], v[198:201], v[84:87]
	v_mfma_f32_16x16x32_bf16 v[80:83], v[174:177], v[198:201], v[80:83]
	v_mfma_f32_16x16x32_bf16 v[68:71], v[166:169], v[206:209], v[68:71]
	v_mfma_f32_16x16x32_bf16 v[64:67], v[174:177], v[206:209], v[64:67]
	s_barrier
	s_mov_b32 m0, s50
	s_or_b32 s78, s77, 0x80
	ds_read_b128 v[178:181], v154 offset:49152
	ds_read_b128 v[182:185], v154 offset:50176
	ds_read_b128 v[186:189], v154 offset:51200
	ds_read_b128 v[190:193], v154 offset:52224
	ds_read_b128 v[194:197], v154 offset:53248
	ds_read_b128 v[198:201], v154 offset:54272
	ds_read_b128 v[202:205], v154 offset:55296
	ds_read_b128 v[206:209], v154 offset:56320
	buffer_load_dwordx4 v147, s[12:15], s78 offen lds
	s_mov_b32 m0, s51
	s_add_i32 s77, s77, 0x80080
	buffer_load_dwordx4 v149, s[12:15], s78 offen lds
	s_mov_b32 m0, s55
	s_nop 0
	buffer_load_dwordx4 v147, s[12:15], s77 offen lds
	s_mov_b32 m0, s58
	s_nop 0
	buffer_load_dwordx4 v149, s[12:15], s77 offen lds
	s_mov_b32 m0, s53
	s_nop 0
	buffer_load_dwordx4 v146, s[8:11], s76 offen lds
	s_mov_b32 m0, s54
	s_nop 0
	buffer_load_dwordx4 v148, s[8:11], s76 offen lds
	s_waitcnt vmcnt(8)
	s_waitcnt lgkmcnt(0)
	s_barrier
	s_waitcnt lgkmcnt(7)
	v_mfma_f32_16x16x32_bf16 v[60:63], v[132:135], v[178:181], v[60:63]
	v_mfma_f32_16x16x32_bf16 v[56:59], v[140:143], v[178:181], v[56:59]
	s_waitcnt lgkmcnt(5)
	v_mfma_f32_16x16x32_bf16 v[44:47], v[132:135], v[186:189], v[44:47]
	v_mfma_f32_16x16x32_bf16 v[40:43], v[140:143], v[186:189], v[40:43]
	s_waitcnt lgkmcnt(3)
	v_mfma_f32_16x16x32_bf16 v[28:31], v[132:135], v[194:197], v[28:31]
	v_mfma_f32_16x16x32_bf16 v[24:27], v[140:143], v[194:197], v[24:27]
	s_waitcnt lgkmcnt(1)
	v_mfma_f32_16x16x32_bf16 v[12:15], v[132:135], v[202:205], v[12:15]
	v_mfma_f32_16x16x32_bf16 v[8:11], v[140:143], v[202:205], v[8:11]
	v_mfma_f32_16x16x32_bf16 v[60:63], v[136:139], v[182:185], v[60:63]
	v_mfma_f32_16x16x32_bf16 v[56:59], v[158:161], v[182:185], v[56:59]
	v_mfma_f32_16x16x32_bf16 v[44:47], v[136:139], v[190:193], v[44:47]
	v_mfma_f32_16x16x32_bf16 v[40:43], v[158:161], v[190:193], v[40:43]
	v_mfma_f32_16x16x32_bf16 v[28:31], v[136:139], v[198:201], v[28:31]
	v_mfma_f32_16x16x32_bf16 v[24:27], v[158:161], v[198:201], v[24:27]
	s_waitcnt lgkmcnt(0)
	v_mfma_f32_16x16x32_bf16 v[12:15], v[136:139], v[206:209], v[12:15]
	v_mfma_f32_16x16x32_bf16 v[8:11], v[158:161], v[206:209], v[8:11]
	v_mfma_f32_16x16x32_bf16 v[52:55], v[162:165], v[178:181], v[52:55]
	v_mfma_f32_16x16x32_bf16 v[48:51], v[170:173], v[178:181], v[48:51]
	v_mfma_f32_16x16x32_bf16 v[36:39], v[162:165], v[186:189], v[36:39]
	v_mfma_f32_16x16x32_bf16 v[32:35], v[170:173], v[186:189], v[32:35]
	v_mfma_f32_16x16x32_bf16 v[20:23], v[162:165], v[194:197], v[20:23]
	v_mfma_f32_16x16x32_bf16 v[16:19], v[170:173], v[194:197], v[16:19]
	v_mfma_f32_16x16x32_bf16 v[4:7], v[162:165], v[202:205], v[4:7]
	v_mfma_f32_16x16x32_bf16 v[0:3], v[170:173], v[202:205], v[0:3]
	v_mfma_f32_16x16x32_bf16 v[52:55], v[166:169], v[182:185], v[52:55]
	v_mfma_f32_16x16x32_bf16 v[48:51], v[174:177], v[182:185], v[48:51]
	v_mfma_f32_16x16x32_bf16 v[36:39], v[166:169], v[190:193], v[36:39]
	v_mfma_f32_16x16x32_bf16 v[32:35], v[174:177], v[190:193], v[32:35]
	v_mfma_f32_16x16x32_bf16 v[20:23], v[166:169], v[198:201], v[20:23]
	v_mfma_f32_16x16x32_bf16 v[16:19], v[174:177], v[198:201], v[16:19]
	v_mfma_f32_16x16x32_bf16 v[4:7], v[166:169], v[206:209], v[4:7]
	v_mfma_f32_16x16x32_bf16 v[0:3], v[174:177], v[206:209], v[0:3]
	s_barrier
	s_add_i32 s75, s75, 2
	s_addk_i32 s41, 0x100
	s_addk_i32 s74, 0x100
	s_cmp_gt_u32 s75, 29
	s_cbranch_scc0 .LBB0_903
	s_and_b64 vcc, exec, s[26:27]
	s_cbranch_vccz .LBB0_906
	s_barrier

; __device__ __forceinline__ unsigned xb_ld(unsigned* p)              { return __hip_atomic_load(p, __ATOMIC_RELAXED, __HIP_MEMORY_SCOPE_AGENT); }
; __device__ __forceinline__ unsigned xb_add(unsigned* p, unsigned v) { return __hip_atomic_fetch_add(p, v, __ATOMIC_RELAXED, __HIP_MEMORY_SCOPE_AGENT); }
; __device__ __forceinline__ void xcd_barrier_complete(unsigned* bar, unsigned x, unsigned& nloc, unsigned& nx) {
;     const unsigned G = gridDim.x * gridDim.y * gridDim.z;
;     unsigned sum, cnt, mine, sp = 0u;
;     for (;;) {
;         sum = 0u; cnt = 0u; mine = 0u;
; #pragma unroll
;         for (unsigned j = 0; j < 16; ++j) { const unsigned c = xb_ld(&bar[XB_XCNT(j)]); sum += c; cnt += (c > 0u) ? 1u : 0u; mine = (j == x) ? c : mine; }
; __device__ __forceinline__ void xcd_barrier(const XcdBarrier& b) {
;     asm volatile("s_waitcnt vmcnt(0)" ::: "memory");
;     __syncthreads();
;     if (threadIdx.x == 0) {
;         unsigned* bar = b.bar;
;         __builtin_amdgcn_s_waitcnt(0);
;         unsigned nloc = b.st[0], nx = b.st[1];
;         if (nloc == 0u) { xcd_barrier_complete(bar, b.x, nloc, nx); b.st[0] = nloc; b.st[1] = nx; }
;         const unsigned old = xb_add(&bar[XB_XSUB(b.x)], 1u);
.LBB0_1000:
	s_cmp_lt_i32 s57, 14
	s_barrier
	s_cbranch_scc1 .LBB0_1054
	s_setprio 0
	s_add_i32 s0, 0, 0x20520
	v_mov_b32_e32 v0, s0
	ds_read_b64 v[0:1], v0
	s_getreg_b32 s3, hwreg(HW_REG_XCC_ID, 0, 4)
	s_waitcnt vmcnt(0)
	s_waitcnt lgkmcnt(0)
	s_barrier
	v_readfirstlane_b32 s4, v0
	v_readfirstlane_b32 s5, v1
	s_mov_b64 s[0:1], exec
	v_readlane_b32 s6, v246, 2
	v_readlane_b32 s7, v246, 3
	s_and_b64 s[6:7], s[0:1], s[6:7]
	s_mov_b64 exec, s[6:7]
	s_cbranch_execz .LBB0_1053
	s_add_i32 s6, 0, 0x20160
	v_mov_b32_e32 v0, s6
	s_waitcnt vmcnt(0) expcnt(0) lgkmcnt(0)
	ds_read_b32 v2, v0
	s_add_i32 s6, 0, 0x20164
	v_mov_b32_e32 v0, s6
	ds_read_b32 v0, v0
	s_and_b32 s3, s3, 15
	s_waitcnt lgkmcnt(1)
	v_cmp_ne_u32_e32 vcc, 0, v2
	s_cbranch_vccnz .LBB0_1017
	v_readlane_b32 s6, v246, 0
	v_readlane_b32 s7, v246, 1
	s_load_dwordx2 s[10:11], s[6:7], 0x4
	s_add_u32 s6, s4, 0x4200
	s_addc_u32 s7, s5, 0
	s_add_u32 s8, s4, 0x4400
	s_addc_u32 s9, s5, 0
	s_waitcnt lgkmcnt(0)
	s_mul_i32 s33, s10, s52
	s_add_u32 s10, s4, 0x4500
	s_mul_i32 s33, s33, s11
	s_addc_u32 s11, s5, 0
	s_add_u32 s12, s4, 0x4600
	s_addc_u32 s13, s5, 0
	s_add_u32 s14, s4, 0x4700
	s_addc_u32 s15, s5, 0
	s_add_u32 s16, s4, 0x4800
	s_addc_u32 s17, s5, 0
	s_add_u32 s18, s4, 0x4900
	s_addc_u32 s19, s5, 0
	s_add_u32 s20, s4, 0x4a00
	s_addc_u32 s21, s5, 0
	s_add_u32 s22, s4, 0x4b00
	s_addc_u32 s23, s5, 0
	s_add_u32 s24, s4, 0x4c00
	s_addc_u32 s25, s5, 0
	s_add_u32 s26, s4, 0x4d00
	s_addc_u32 s27, s5, 0
	s_add_u32 s28, s4, 0x4e00
	s_addc_u32 s29, s5, 0
	s_add_u32 s30, s4, 0x4f00
	s_addc_u32 s31, s5, 0
	s_add_u32 s36, s4, 0x5000
	s_addc_u32 s37, s5, 0
	s_add_u32 s38, s4, 0x5100
	s_addc_u32 s39, s5, 0
	s_add_u32 s40, s4, 0x5200
	s_addc_u32 s41, s5, 0
	s_add_u32 s42, s4, 0x5300
	s_addc_u32 s43, s5, 0
	s_mov_b32 s34, 1
	v_mov_b32_e32 v16, 0
	s_branch .LBB0_1005

; #define PG8_STAGE(bufoff, soff, voff) do { _Pragma("unroll") for (int _i = 0; _i < 2; ++_i) \
;         __builtin_amdgcn_raw_ptr_buffer_load_lds(rs_##voff, (PG8_LAS unsigned*)(lds + (bufoff) + ldsw + _i * 8192), 16, (int)(voff)[_i], (int)(soff), 0, 0); } while (0)
; #define PG8_LDA(dst, b, h) do { _Pragma("unroll") for (int m = 0; m < 4; ++m) _Pragma("unroll") for (int k = 0; k < 2; ++k) dst[m][k] = *(const PG8_LAS bf16x8*)(lds + PG8_SA(b, h) + aoff + m * 2048 + k * 1024); } while (0)
; #define PG8_LDB(dst, b, h) do { _Pragma("unroll") for (int n = 0; n < 2; ++n) _Pragma("unroll") for (int k = 0; k < 2; ++k) dst[n][k] = *(const PG8_LAS bf16x8*)(lds + PG8_SB(b, h) + boff + n * 2048 + k * 1024); } while (0)
; #define PG8_MMA(ai, bj, At, Bt) do { __builtin_amdgcn_s_setprio(1); _Pragma("unroll") for (int m = 0; m < 4; ++m) _Pragma("unroll") for (int n = 0; n < 2; ++n) _Pragma("unroll") for (int k = 0; k < 2; ++k) \
;         acc[ai][bj][m][n] = __builtin_amdgcn_mfma_f32_16x16x32_bf16(Bt[n][k], At[m][k], acc[ai][bj][m][n], 0, 0, 0); __builtin_amdgcn_s_setprio(0); } while (0)
; #define PG8_WAIT_V(n) asm volatile("s_waitcnt vmcnt(" #n ")" ::: "memory")
; #define PG8_WAIT_L(n) asm volatile("s_waitcnt lgkmcnt(" #n ")" ::: "memory")
; #define PG8_BAR __builtin_amdgcn_s_barrier()
; #define PG8_SCHED __builtin_amdgcn_sched_barrier(0)
; template <class Epi, class Sched, bool ALIGN_EPI = false, bool SP2 = false>
; __device__ __forceinline__ void gemm_phase(PG8_LAS unsigned char* lds, const Gemm g, const Sched& S, const Epi& E, const int wid  ) {
;     ...
;             PG8_LDB(B0, 0, 0); PG8_LDB(B1, 0, 1); PG8_SCHED; PG8_LDA(At, 0, 0); PG8_STAGE(PG8_SA(1, 1), a1 + hstep, voffA);
;             PG8_WAIT_V(8); PG8_WAIT_L(0); PG8_BAR; PG8_MMA(0, 0, At, B0); PG8_MMA(0, 1, At, B1); PG8_BAR; PG8_SCHED;
;             PG8_LDA(At, 0, 1); PG8_STAGE(PG8_SB(0, 0), b2, voffB); PG8_STAGE(PG8_SB(0, 1), b2 + hstep, voffB); PG8_STAGE(PG8_SA(0, 0), a2, voffA);
;             PG8_WAIT_V(8); PG8_WAIT_L(0); PG8_BAR; PG8_MMA(1, 0, At, B0); PG8_MMA(1, 1, At, B1); PG8_BAR; PG8_SCHED;
.Lprio_1076:
.LBB0_1076:
	ds_read_b128 v[142:145], v136
	ds_read_b128 v[146:149], v136 offset:1024
	ds_read_b128 v[150:153], v136 offset:2048
	ds_read_b128 v[154:157], v136 offset:3072
	ds_read_b128 v[158:161], v137
	ds_read_b128 v[162:165], v137 offset:1024
	ds_read_b128 v[166:169], v137 offset:2048
	ds_read_b128 v[170:173], v137 offset:3072
	s_add_i32 s14, s1, 0xfff80080
	s_cmp_eq_u32 s20, 28
	s_cselect_b32 s54, s55, s14
	s_cselect_b32 s35, s0, s16
	s_add_i32 s21, s54, 0x80
	s_mov_b32 m0, s45
	ds_read_b128 v[174:177], v138
	ds_read_b128 v[178:181], v138 offset:1024
	ds_read_b128 v[182:185], v138 offset:2048
	ds_read_b128 v[186:189], v138 offset:3072
	ds_read_b128 v[190:193], v138 offset:4096
	ds_read_b128 v[194:197], v138 offset:5120
	ds_read_b128 v[198:201], v138 offset:6144
	ds_read_b128 v[202:205], v138 offset:7168
	buffer_load_dwordx4 v132, s[8:11], s1 offen lds
	s_mov_b32 m0, s46
	s_nop 0
	buffer_load_dwordx4 v134, s[8:11], s1 offen lds
	s_waitcnt vmcnt(8)
	s_waitcnt lgkmcnt(0)
	s_barrier
	s_waitcnt lgkmcnt(7)
	v_mfma_f32_16x16x32_bf16 v[124:127], v[142:145], v[174:177], v[124:127]
	v_mfma_f32_16x16x32_bf16 v[120:123], v[150:153], v[174:177], v[120:123]
	s_waitcnt lgkmcnt(5)
	v_mfma_f32_16x16x32_bf16 v[108:111], v[142:145], v[182:185], v[108:111]
	v_mfma_f32_16x16x32_bf16 v[104:107], v[150:153], v[182:185], v[104:107]
	s_waitcnt lgkmcnt(3)
	v_mfma_f32_16x16x32_bf16 v[92:95], v[142:145], v[190:193], v[92:95]
	v_mfma_f32_16x16x32_bf16 v[88:91], v[150:153], v[190:193], v[88:91]
	s_waitcnt lgkmcnt(1)
	v_mfma_f32_16x16x32_bf16 v[76:79], v[142:145], v[198:201], v[76:79]
	v_mfma_f32_16x16x32_bf16 v[72:75], v[150:153], v[198:201], v[72:75]
	v_mfma_f32_16x16x32_bf16 v[124:127], v[146:149], v[178:181], v[124:127]
	v_mfma_f32_16x16x32_bf16 v[120:123], v[154:157], v[178:181], v[120:123]
	v_mfma_f32_16x16x32_bf16 v[108:111], v[146:149], v[186:189], v[108:111]
	v_mfma_f32_16x16x32_bf16 v[104:107], v[154:157], v[186:189], v[104:107]
	v_mfma_f32_16x16x32_bf16 v[92:95], v[146:149], v[194:197], v[92:95]
	v_mfma_f32_16x16x32_bf16 v[88:91], v[154:157], v[194:197], v[88:91]
	s_waitcnt lgkmcnt(0)
	v_mfma_f32_16x16x32_bf16 v[76:79], v[146:149], v[202:205], v[76:79]
	v_mfma_f32_16x16x32_bf16 v[72:75], v[154:157], v[202:205], v[72:75]
	v_mfma_f32_16x16x32_bf16 v[116:119], v[158:161], v[174:177], v[116:119]
	v_mfma_f32_16x16x32_bf16 v[112:115], v[166:169], v[174:177], v[112:115]
	v_mfma_f32_16x16x32_bf16 v[100:103], v[158:161], v[182:185], v[100:103]
	v_mfma_f32_16x16x32_bf16 v[96:99], v[166:169], v[182:185], v[96:99]
	v_mfma_f32_16x16x32_bf16 v[84:87], v[158:161], v[190:193], v[84:87]
	v_mfma_f32_16x16x32_bf16 v[80:83], v[166:169], v[190:193], v[80:83]
	v_mfma_f32_16x16x32_bf16 v[68:71], v[158:161], v[198:201], v[68:71]
	v_mfma_f32_16x16x32_bf16 v[64:67], v[166:169], v[198:201], v[64:67]
	v_mfma_f32_16x16x32_bf16 v[116:119], v[162:165], v[178:181], v[116:119]
	v_mfma_f32_16x16x32_bf16 v[112:115], v[170:173], v[178:181], v[112:115]
	v_mfma_f32_16x16x32_bf16 v[100:103], v[162:165], v[186:189], v[100:103]
	v_mfma_f32_16x16x32_bf16 v[96:99], v[170:173], v[186:189], v[96:99]
	v_mfma_f32_16x16x32_bf16 v[84:87], v[162:165], v[194:197], v[84:87]
	v_mfma_f32_16x16x32_bf16 v[80:83], v[170:173], v[194:197], v[80:83]
	v_mfma_f32_16x16x32_bf16 v[68:71], v[162:165], v[202:205], v[68:71]
	v_mfma_f32_16x16x32_bf16 v[64:67], v[170:173], v[202:205], v[64:67]
	s_barrier
	s_mov_b32 m0, s22
	s_mov_b32 s14, s10
	s_mov_b32 s15, s11
	ds_read_b128 v[174:177], v138 offset:16384
	ds_read_b128 v[178:181], v138 offset:17408
	ds_read_b128 v[182:185], v138 offset:18432
	ds_read_b128 v[186:189], v138 offset:19456
	ds_read_b128 v[190:193], v138 offset:20480
	ds_read_b128 v[194:197], v138 offset:21504
	ds_read_b128 v[198:201], v138 offset:22528
	ds_read_b128 v[202:205], v138 offset:23552
	buffer_load_dwordx4 v133, s[12:15], s35 offen lds
	s_mov_b32 m0, s23
	s_add_i32 s59, s35, 0x80000
	buffer_load_dwordx4 v135, s[12:15], s35 offen lds
	s_mov_b32 m0, s24
	s_nop 0
	buffer_load_dwordx4 v133, s[12:15], s59 offen lds
	s_mov_b32 m0, s25
	s_nop 0
	buffer_load_dwordx4 v135, s[12:15], s59 offen lds
	s_mov_b32 m0, s3
	s_nop 0
	buffer_load_dwordx4 v132, s[8:11], s54 offen lds
	s_mov_b32 m0, s26
	s_nop 0
	buffer_load_dwordx4 v134, s[8:11], s54 offen lds
	s_waitcnt vmcnt(8)
	s_waitcnt lgkmcnt(0)
	s_barrier
	s_waitcnt lgkmcnt(7)
	v_mfma_f32_16x16x32_bf16 v[60:63], v[142:145], v[174:177], v[60:63]
	v_mfma_f32_16x16x32_bf16 v[56:59], v[150:153], v[174:177], v[56:59]
	s_waitcnt lgkmcnt(5)
	v_mfma_f32_16x16x32_bf16 v[44:47], v[142:145], v[182:185], v[44:47]
	v_mfma_f32_16x16x32_bf16 v[40:43], v[150:153], v[182:185], v[40:43]
	s_waitcnt lgkmcnt(3)
	v_mfma_f32_16x16x32_bf16 v[28:31], v[142:145], v[190:193], v[28:31]
	v_mfma_f32_16x16x32_bf16 v[24:27], v[150:153], v[190:193], v[24:27]
	s_waitcnt lgkmcnt(1)
	v_mfma_f32_16x16x32_bf16 v[12:15], v[142:145], v[198:201], v[12:15]
	v_mfma_f32_16x16x32_bf16 v[8:11], v[150:153], v[198:201], v[8:11]
	v_mfma_f32_16x16x32_bf16 v[60:63], v[146:149], v[178:181], v[60:63]
	v_mfma_f32_16x16x32_bf16 v[56:59], v[154:157], v[178:181], v[56:59]
	v_mfma_f32_16x16x32_bf16 v[44:47], v[146:149], v[186:189], v[44:47]
	v_mfma_f32_16x16x32_bf16 v[40:43], v[154:157], v[186:189], v[40:43]
	v_mfma_f32_16x16x32_bf16 v[28:31], v[146:149], v[194:197], v[28:31]
	v_mfma_f32_16x16x32_bf16 v[24:27], v[154:157], v[194:197], v[24:27]
	s_waitcnt lgkmcnt(0)
	v_mfma_f32_16x16x32_bf16 v[12:15], v[146:149], v[202:205], v[12:15]
	v_mfma_f32_16x16x32_bf16 v[8:11], v[154:157], v[202:205], v[8:11]
	v_mfma_f32_16x16x32_bf16 v[52:55], v[158:161], v[174:177], v[52:55]
	v_mfma_f32_16x16x32_bf16 v[48:51], v[166:169], v[174:177], v[48:51]
	v_mfma_f32_16x16x32_bf16 v[36:39], v[158:161], v[182:185], v[36:39]
	v_mfma_f32_16x16x32_bf16 v[32:35], v[166:169], v[182:185], v[32:35]
	v_mfma_f32_16x16x32_bf16 v[20:23], v[158:161], v[190:193], v[20:23]
	v_mfma_f32_16x16x32_bf16 v[16:19], v[166:169], v[190:193], v[16:19]
	v_mfma_f32_16x16x32_bf16 v[4:7], v[158:161], v[198:201], v[4:7]
	v_mfma_f32_16x16x32_bf16 v[0:3], v[166:169], v[198:201], v[0:3]
	v_mfma_f32_16x16x32_bf16 v[52:55], v[162:165], v[178:181], v[52:55]
	v_mfma_f32_16x16x32_bf16 v[48:51], v[170:173], v[178:181], v[48:51]
	v_mfma_f32_16x16x32_bf16 v[36:39], v[162:165], v[186:189], v[36:39]
	v_mfma_f32_16x16x32_bf16 v[32:35], v[170:173], v[186:189], v[32:35]
	v_mfma_f32_16x16x32_bf16 v[20:23], v[162:165], v[194:197], v[20:23]
	v_mfma_f32_16x16x32_bf16 v[16:19], v[170:173], v[194:197], v[16:19]
	v_mfma_f32_16x16x32_bf16 v[4:7], v[162:165], v[202:205], v[4:7]
	v_mfma_f32_16x16x32_bf16 v[0:3], v[170:173], v[202:205], v[0:3]
	s_barrier
; #define PG8_STAGE(bufoff, soff, voff) do { _Pragma("unroll") for (int _i = 0; _i < 2; ++_i) \
;         __builtin_amdgcn_raw_ptr_buffer_load_lds(rs_##voff, (PG8_LAS unsigned*)(lds + (bufoff) + ldsw + _i * 8192), 16, (int)(voff)[_i], (int)(soff), 0, 0); } while (0)
; #define PG8_LDA(dst, b, h) do { _Pragma("unroll") for (int m = 0; m < 4; ++m) _Pragma("unroll") for (int k = 0; k < 2; ++k) dst[m][k] = *(const PG8_LAS bf16x8*)(lds + PG8_SA(b, h) + aoff + m * 2048 + k * 1024); } while (0)
; #define PG8_LDB(dst, b, h) do { _Pragma("unroll") for (int n = 0; n < 2; ++n) _Pragma("unroll") for (int k = 0; k < 2; ++k) dst[n][k] = *(const PG8_LAS bf16x8*)(lds + PG8_SB(b, h) + boff + n * 2048 + k * 1024); } while (0)
; #define PG8_MMA(ai, bj, At, Bt) do { __builtin_amdgcn_s_setprio(1); _Pragma("unroll") for (int m = 0; m < 4; ++m) _Pragma("unroll") for (int n = 0; n < 2; ++n) _Pragma("unroll") for (int k = 0; k < 2; ++k) \
;         acc[ai][bj][m][n] = __builtin_amdgcn_mfma_f32_16x16x32_bf16(Bt[n][k], At[m][k], acc[ai][bj][m][n], 0, 0, 0); __builtin_amdgcn_s_setprio(0); } while (0)
; #define PG8_WAIT_V(n) asm volatile("s_waitcnt vmcnt(" #n ")" ::: "memory")
; #define PG8_WAIT_L(n) asm volatile("s_waitcnt lgkmcnt(" #n ")" ::: "memory")
; #define PG8_BAR __builtin_amdgcn_s_barrier()
; #define PG8_SCHED __builtin_amdgcn_sched_barrier(0)
; template <class Epi, class Sched, bool ALIGN_EPI = false, bool SP2 = false>
; __device__ __forceinline__ void gemm_phase(PG8_LAS unsigned char* lds, const Gemm g, const Sched& S, const Epi& E, const int wid  ) {
;     ...
;             PG8_LDB(B0, 1, 0); PG8_LDB(B1, 1, 1); PG8_SCHED; PG8_LDA(At, 1, 0); PG8_STAGE(PG8_SA(0, 1), a2 + hstep, voffA);
;             PG8_WAIT_V(8); PG8_WAIT_L(0); PG8_BAR; PG8_MMA(0, 0, At, B0); PG8_MMA(0, 1, At, B1); PG8_BAR; PG8_SCHED;
;             PG8_LDA(At, 1, 1); PG8_STAGE(PG8_SB(1, 0), b3, voffB); PG8_STAGE(PG8_SB(1, 1), b3 + hstep, voffB); PG8_STAGE(PG8_SA(1, 0), a3, voffA);
;             PG8_WAIT_V(8); PG8_WAIT_L(0); PG8_BAR; PG8_MMA(1, 0, At, B0); PG8_MMA(1, 1, At, B1); PG8_BAR; PG8_SCHED;
;     ...
;         if constexpr (ALIGN_EPI) { if (wr == 0) PG8_BAR; }
	ds_read_b128 v[142:145], v139
	ds_read_b128 v[146:149], v139 offset:1024
	ds_read_b128 v[150:153], v139 offset:2048
	ds_read_b128 v[154:157], v139 offset:3072
	ds_read_b128 v[158:161], v140
	ds_read_b128 v[162:165], v140 offset:1024
	ds_read_b128 v[166:169], v140 offset:2048
	ds_read_b128 v[170:173], v140 offset:3072
	s_add_i32 s54, s54, 0x80000
	s_mov_b32 m0, s27
	ds_read_b128 v[174:177], v138 offset:32768
	ds_read_b128 v[178:181], v138 offset:33792
	ds_read_b128 v[182:185], v138 offset:34816
	ds_read_b128 v[186:189], v138 offset:35840
	ds_read_b128 v[190:193], v138 offset:36864
	ds_read_b128 v[194:197], v138 offset:37888
	ds_read_b128 v[198:201], v138 offset:38912
	ds_read_b128 v[202:205], v138 offset:39936
	buffer_load_dwordx4 v132, s[8:11], s54 offen lds
	s_mov_b32 m0, s28
	s_nop 0
	buffer_load_dwordx4 v134, s[8:11], s54 offen lds
	s_waitcnt vmcnt(8)
	s_waitcnt lgkmcnt(0)
	s_barrier
	s_waitcnt lgkmcnt(7)
	v_mfma_f32_16x16x32_bf16 v[124:127], v[142:145], v[174:177], v[124:127]
	v_mfma_f32_16x16x32_bf16 v[120:123], v[150:153], v[174:177], v[120:123]
	s_waitcnt lgkmcnt(5)
	v_mfma_f32_16x16x32_bf16 v[108:111], v[142:145], v[182:185], v[108:111]
	v_mfma_f32_16x16x32_bf16 v[104:107], v[150:153], v[182:185], v[104:107]
	s_waitcnt lgkmcnt(3)
	v_mfma_f32_16x16x32_bf16 v[92:95], v[142:145], v[190:193], v[92:95]
	v_mfma_f32_16x16x32_bf16 v[88:91], v[150:153], v[190:193], v[88:91]
	s_waitcnt lgkmcnt(1)
	v_mfma_f32_16x16x32_bf16 v[76:79], v[142:145], v[198:201], v[76:79]
	v_mfma_f32_16x16x32_bf16 v[72:75], v[150:153], v[198:201], v[72:75]
	v_mfma_f32_16x16x32_bf16 v[124:127], v[146:149], v[178:181], v[124:127]
	v_mfma_f32_16x16x32_bf16 v[120:123], v[154:157], v[178:181], v[120:123]
	v_mfma_f32_16x16x32_bf16 v[108:111], v[146:149], v[186:189], v[108:111]
	v_mfma_f32_16x16x32_bf16 v[104:107], v[154:157], v[186:189], v[104:107]
	v_mfma_f32_16x16x32_bf16 v[92:95], v[146:149], v[194:197], v[92:95]
	v_mfma_f32_16x16x32_bf16 v[88:91], v[154:157], v[194:197], v[88:91]
	s_waitcnt lgkmcnt(0)
	v_mfma_f32_16x16x32_bf16 v[76:79], v[146:149], v[202:205], v[76:79]
	v_mfma_f32_16x16x32_bf16 v[72:75], v[154:157], v[202:205], v[72:75]
	v_mfma_f32_16x16x32_bf16 v[116:119], v[158:161], v[174:177], v[116:119]
	v_mfma_f32_16x16x32_bf16 v[112:115], v[166:169], v[174:177], v[112:115]
	v_mfma_f32_16x16x32_bf16 v[100:103], v[158:161], v[182:185], v[100:103]
	v_mfma_f32_16x16x32_bf16 v[96:99], v[166:169], v[182:185], v[96:99]
	v_mfma_f32_16x16x32_bf16 v[84:87], v[158:161], v[190:193], v[84:87]
	v_mfma_f32_16x16x32_bf16 v[80:83], v[166:169], v[190:193], v[80:83]
	v_mfma_f32_16x16x32_bf16 v[68:71], v[158:161], v[198:201], v[68:71]
	v_mfma_f32_16x16x32_bf16 v[64:67], v[166:169], v[198:201], v[64:67]
	v_mfma_f32_16x16x32_bf16 v[116:119], v[162:165], v[178:181], v[116:119]
	v_mfma_f32_16x16x32_bf16 v[112:115], v[170:173], v[178:181], v[112:115]
	v_mfma_f32_16x16x32_bf16 v[100:103], v[162:165], v[186:189], v[100:103]
	v_mfma_f32_16x16x32_bf16 v[96:99], v[170:173], v[186:189], v[96:99]
	v_mfma_f32_16x16x32_bf16 v[84:87], v[162:165], v[194:197], v[84:87]
	v_mfma_f32_16x16x32_bf16 v[80:83], v[170:173], v[194:197], v[80:83]
	v_mfma_f32_16x16x32_bf16 v[68:71], v[162:165], v[202:205], v[68:71]
	v_mfma_f32_16x16x32_bf16 v[64:67], v[170:173], v[202:205], v[64:67]
	s_barrier
	s_mov_b32 m0, s37
	s_or_b32 s54, s35, 0x80
	ds_read_b128 v[174:177], v138 offset:49152
	ds_read_b128 v[178:181], v138 offset:50176
	ds_read_b128 v[182:185], v138 offset:51200
	ds_read_b128 v[186:189], v138 offset:52224
	ds_read_b128 v[190:193], v138 offset:53248
	ds_read_b128 v[194:197], v138 offset:54272
	ds_read_b128 v[198:201], v138 offset:55296
	ds_read_b128 v[202:205], v138 offset:56320
	buffer_load_dwordx4 v133, s[12:15], s54 offen lds
	s_mov_b32 m0, s38
	s_add_i32 s35, s35, 0x80080
	buffer_load_dwordx4 v135, s[12:15], s54 offen lds
	s_mov_b32 m0, s41
	s_nop 0
	buffer_load_dwordx4 v133, s[12:15], s35 offen lds
	s_mov_b32 m0, s42
	s_nop 0
	buffer_load_dwordx4 v135, s[12:15], s35 offen lds
	s_mov_b32 m0, s39
	s_nop 0
	buffer_load_dwordx4 v132, s[8:11], s21 offen lds
	s_mov_b32 m0, s40
	s_nop 0
	buffer_load_dwordx4 v134, s[8:11], s21 offen lds
	s_waitcnt vmcnt(8)
	s_waitcnt lgkmcnt(0)
	s_barrier
	s_waitcnt lgkmcnt(7)
	v_mfma_f32_16x16x32_bf16 v[60:63], v[142:145], v[174:177], v[60:63]
	v_mfma_f32_16x16x32_bf16 v[56:59], v[150:153], v[174:177], v[56:59]
	s_waitcnt lgkmcnt(5)
	v_mfma_f32_16x16x32_bf16 v[44:47], v[142:145], v[182:185], v[44:47]
	v_mfma_f32_16x16x32_bf16 v[40:43], v[150:153], v[182:185], v[40:43]
	s_waitcnt lgkmcnt(3)
	v_mfma_f32_16x16x32_bf16 v[28:31], v[142:145], v[190:193], v[28:31]
	v_mfma_f32_16x16x32_bf16 v[24:27], v[150:153], v[190:193], v[24:27]
	s_waitcnt lgkmcnt(1)
	v_mfma_f32_16x16x32_bf16 v[12:15], v[142:145], v[198:201], v[12:15]
	v_mfma_f32_16x16x32_bf16 v[8:11], v[150:153], v[198:201], v[8:11]
	v_mfma_f32_16x16x32_bf16 v[60:63], v[146:149], v[178:181], v[60:63]
	v_mfma_f32_16x16x32_bf16 v[56:59], v[154:157], v[178:181], v[56:59]
	v_mfma_f32_16x16x32_bf16 v[44:47], v[146:149], v[186:189], v[44:47]
	v_mfma_f32_16x16x32_bf16 v[40:43], v[154:157], v[186:189], v[40:43]
	v_mfma_f32_16x16x32_bf16 v[28:31], v[146:149], v[194:197], v[28:31]
	v_mfma_f32_16x16x32_bf16 v[24:27], v[154:157], v[194:197], v[24:27]
	s_waitcnt lgkmcnt(0)
	v_mfma_f32_16x16x32_bf16 v[12:15], v[146:149], v[202:205], v[12:15]
	v_mfma_f32_16x16x32_bf16 v[8:11], v[154:157], v[202:205], v[8:11]
	v_mfma_f32_16x16x32_bf16 v[52:55], v[158:161], v[174:177], v[52:55]
	v_mfma_f32_16x16x32_bf16 v[48:51], v[166:169], v[174:177], v[48:51]
	v_mfma_f32_16x16x32_bf16 v[36:39], v[158:161], v[182:185], v[36:39]
	v_mfma_f32_16x16x32_bf16 v[32:35], v[166:169], v[182:185], v[32:35]
	v_mfma_f32_16x16x32_bf16 v[20:23], v[158:161], v[190:193], v[20:23]
	v_mfma_f32_16x16x32_bf16 v[16:19], v[166:169], v[190:193], v[16:19]
	v_mfma_f32_16x16x32_bf16 v[4:7], v[158:161], v[198:201], v[4:7]
	v_mfma_f32_16x16x32_bf16 v[0:3], v[166:169], v[198:201], v[0:3]
	v_mfma_f32_16x16x32_bf16 v[52:55], v[162:165], v[178:181], v[52:55]
	v_mfma_f32_16x16x32_bf16 v[48:51], v[170:173], v[178:181], v[48:51]
	v_mfma_f32_16x16x32_bf16 v[36:39], v[162:165], v[186:189], v[36:39]
	v_mfma_f32_16x16x32_bf16 v[32:35], v[170:173], v[186:189], v[32:35]
	v_mfma_f32_16x16x32_bf16 v[20:23], v[162:165], v[194:197], v[20:23]
	v_mfma_f32_16x16x32_bf16 v[16:19], v[170:173], v[194:197], v[16:19]
	v_mfma_f32_16x16x32_bf16 v[4:7], v[162:165], v[202:205], v[4:7]
	v_mfma_f32_16x16x32_bf16 v[0:3], v[170:173], v[202:205], v[0:3]
	s_barrier
	s_add_i32 s20, s20, 2
	s_addk_i32 s1, 0x100
	s_addk_i32 s16, 0x100
	s_cmp_gt_u32 s20, 29
	s_cbranch_scc0 .LBB0_1076
	s_and_b64 vcc, exec, s[18:19]
	s_cbranch_vccz .LBB0_1079
	s_barrier

; __device__ __forceinline__ unsigned xb_ld(unsigned* p)              { return __hip_atomic_load(p, __ATOMIC_RELAXED, __HIP_MEMORY_SCOPE_AGENT); }
; __device__ __forceinline__ void xcd_barrier_complete(unsigned* bar, unsigned x, unsigned& nloc, unsigned& nx) {
;     const unsigned G = gridDim.x * gridDim.y * gridDim.z;
;     unsigned sum, cnt, mine, sp = 0u;
;     for (;;) {
;         sum = 0u; cnt = 0u; mine = 0u;
; #pragma unroll
;         for (unsigned j = 0; j < 16; ++j) { const unsigned c = xb_ld(&bar[XB_XCNT(j)]); sum += c; cnt += (c > 0u) ? 1u : 0u; mine = (j == x) ? c : mine; }
; __device__ __forceinline__ void xcd_barrier(const XcdBarrier& b) {
;     asm volatile("s_waitcnt vmcnt(0)" ::: "memory");
;     __syncthreads();
;     if (threadIdx.x == 0) {
;         unsigned* bar = b.bar;
;         __builtin_amdgcn_s_waitcnt(0);
;         unsigned nloc = b.st[0], nx = b.st[1];
;         if (nloc == 0u) { xcd_barrier_complete(bar, b.x, nloc, nx); b.st[0] = nloc; b.st[1] = nx; }
.LBB0_1449:
	s_cmp_lt_i32 s57, 15
	s_cbranch_scc1 .LBB0_1503
	s_setprio 0
	s_add_i32 s0, 0, 0x20520
	v_mov_b32_e32 v0, s0
	ds_read_b64 v[0:1], v0
	s_getreg_b32 s3, hwreg(HW_REG_XCC_ID, 0, 4)
	s_waitcnt vmcnt(0)
	s_waitcnt vmcnt(16) lgkmcnt(0)
	s_barrier
	v_readfirstlane_b32 s4, v0
	v_readfirstlane_b32 s5, v1
	s_mov_b64 s[0:1], exec
	v_readlane_b32 s6, v246, 2
	v_readlane_b32 s7, v246, 3
	s_and_b64 s[6:7], s[0:1], s[6:7]
	s_mov_b64 exec, s[6:7]
	s_cbranch_execz .LBB0_1502
	s_add_i32 s6, 0, 0x20160
	v_mov_b32_e32 v0, s6
	s_waitcnt vmcnt(0) expcnt(0) lgkmcnt(0)
	ds_read_b32 v2, v0
	s_add_i32 s6, 0, 0x20164
	v_mov_b32_e32 v0, s6
	ds_read_b32 v0, v0
	s_and_b32 s3, s3, 15
	s_waitcnt lgkmcnt(1)
	v_cmp_ne_u32_e32 vcc, 0, v2
	s_cbranch_vccnz .LBB0_1466
	v_readlane_b32 s6, v246, 0
	v_readlane_b32 s7, v246, 1
	s_load_dwordx2 s[10:11], s[6:7], 0x4
	s_add_u32 s6, s4, 0x4200
	s_addc_u32 s7, s5, 0
	s_add_u32 s8, s4, 0x4400
	s_addc_u32 s9, s5, 0
	s_waitcnt lgkmcnt(0)
	s_mul_i32 s33, s10, s52
	s_add_u32 s10, s4, 0x4500
	s_mul_i32 s33, s33, s11
	s_addc_u32 s11, s5, 0
	s_add_u32 s12, s4, 0x4600
	s_addc_u32 s13, s5, 0
	s_add_u32 s14, s4, 0x4700
	s_addc_u32 s15, s5, 0
	s_add_u32 s16, s4, 0x4800
	s_addc_u32 s17, s5, 0
	s_add_u32 s18, s4, 0x4900
	s_addc_u32 s19, s5, 0
	s_add_u32 s20, s4, 0x4a00
	s_addc_u32 s21, s5, 0
	s_add_u32 s22, s4, 0x4b00
	s_addc_u32 s23, s5, 0
	s_add_u32 s24, s4, 0x4c00
	s_addc_u32 s25, s5, 0
	s_add_u32 s26, s4, 0x4d00
	s_addc_u32 s27, s5, 0
	s_add_u32 s28, s4, 0x4e00
	s_addc_u32 s29, s5, 0
	s_add_u32 s30, s4, 0x4f00
	s_addc_u32 s31, s5, 0
	s_add_u32 s36, s4, 0x5000
	s_addc_u32 s37, s5, 0
	s_add_u32 s38, s4, 0x5100
	s_addc_u32 s39, s5, 0
	s_add_u32 s40, s4, 0x5200
	s_addc_u32 s41, s5, 0
	s_add_u32 s42, s4, 0x5300
	s_addc_u32 s43, s5, 0
	s_mov_b32 s34, 1
	v_mov_b32_e32 v16, 0
	s_branch .LBB0_1454

; __device__ __forceinline__ unsigned xb_ld(unsigned* p)              { return __hip_atomic_load(p, __ATOMIC_RELAXED, __HIP_MEMORY_SCOPE_AGENT); }
; __device__ __forceinline__ void xcd_barrier_complete(unsigned* bar, unsigned x, unsigned& nloc, unsigned& nx) {
;     const unsigned G = gridDim.x * gridDim.y * gridDim.z;
;     unsigned sum, cnt, mine, sp = 0u;
;     for (;;) {
;         sum = 0u; cnt = 0u; mine = 0u;
; #pragma unroll
;         for (unsigned j = 0; j < 16; ++j) { const unsigned c = xb_ld(&bar[XB_XCNT(j)]); sum += c; cnt += (c > 0u) ? 1u : 0u; mine = (j == x) ? c : mine; }
; __device__ __forceinline__ void xcd_barrier(const XcdBarrier& b) {
;     asm volatile("s_waitcnt vmcnt(0)" ::: "memory");
;     __syncthreads();
;     if (threadIdx.x == 0) {
;         unsigned* bar = b.bar;
;         __builtin_amdgcn_s_waitcnt(0);
;         unsigned nloc = b.st[0], nx = b.st[1];
;         if (nloc == 0u) { xcd_barrier_complete(bar, b.x, nloc, nx); b.st[0] = nloc; b.st[1] = nx; }
.LBB0_1631:
	s_setprio 0
	s_add_i32 s0, 0, 0x20520
	v_mov_b32_e32 v0, s0
	ds_read_b64 v[0:1], v0
	s_getreg_b32 s3, hwreg(HW_REG_XCC_ID, 0, 4)
	s_waitcnt vmcnt(0)
	s_waitcnt vmcnt(16) lgkmcnt(0)
	s_barrier
	v_readfirstlane_b32 s4, v0
	v_readfirstlane_b32 s5, v1
	s_mov_b64 s[0:1], exec
	v_readlane_b32 s6, v246, 2
	v_readlane_b32 s7, v246, 3
	s_and_b64 s[6:7], s[0:1], s[6:7]
	s_mov_b64 exec, s[6:7]
	s_cbranch_execz .LBB0_1683
	s_add_i32 s6, 0, 0x20160
	v_mov_b32_e32 v0, s6
	s_waitcnt vmcnt(0) expcnt(0) lgkmcnt(0)
	ds_read_b32 v2, v0
	s_add_i32 s6, 0, 0x20164
	v_mov_b32_e32 v0, s6
	ds_read_b32 v0, v0
	s_and_b32 s3, s3, 15
	s_waitcnt lgkmcnt(1)
	v_cmp_ne_u32_e32 vcc, 0, v2
	s_cbranch_vccnz .LBB0_1647
	v_readlane_b32 s6, v246, 0
	v_readlane_b32 s7, v246, 1
	s_load_dwordx2 s[10:11], s[6:7], 0x4
	s_add_u32 s6, s4, 0x4200
	s_addc_u32 s7, s5, 0
	s_add_u32 s8, s4, 0x4400
	s_addc_u32 s9, s5, 0
	s_waitcnt lgkmcnt(0)
	s_mul_i32 s33, s10, s52
	s_add_u32 s10, s4, 0x4500
	s_mul_i32 s33, s33, s11
	s_addc_u32 s11, s5, 0
	s_add_u32 s12, s4, 0x4600
	s_addc_u32 s13, s5, 0
	s_add_u32 s14, s4, 0x4700
	s_addc_u32 s15, s5, 0
	s_add_u32 s16, s4, 0x4800
	s_addc_u32 s17, s5, 0
	s_add_u32 s18, s4, 0x4900
	s_addc_u32 s19, s5, 0
	s_add_u32 s20, s4, 0x4a00
	s_addc_u32 s21, s5, 0
	s_add_u32 s22, s4, 0x4b00
	s_addc_u32 s23, s5, 0
	s_add_u32 s24, s4, 0x4c00
	s_addc_u32 s25, s5, 0
	s_add_u32 s26, s4, 0x4d00
	s_addc_u32 s27, s5, 0
	s_add_u32 s28, s4, 0x4e00
	s_addc_u32 s29, s5, 0
	s_add_u32 s30, s4, 0x4f00
	s_addc_u32 s31, s5, 0
	s_add_u32 s36, s4, 0x5000
	s_addc_u32 s37, s5, 0
	s_add_u32 s38, s4, 0x5100
	s_addc_u32 s39, s5, 0
	s_add_u32 s40, s4, 0x5200
	s_addc_u32 s41, s5, 0
	s_add_u32 s42, s4, 0x5300
	s_addc_u32 s43, s5, 0
	s_mov_b32 s34, 1
	v_mov_b32_e32 v16, 0
	s_branch .LBB0_1635

; __device__ __forceinline__ unsigned xb_ld(unsigned* p)              { return __hip_atomic_load(p, __ATOMIC_RELAXED, __HIP_MEMORY_SCOPE_AGENT); }
; __device__ __forceinline__ void xcd_barrier_complete(unsigned* bar, unsigned x, unsigned& nloc, unsigned& nx) {
;     const unsigned G = gridDim.x * gridDim.y * gridDim.z;
;     unsigned sum, cnt, mine, sp = 0u;
;     for (;;) {
;         sum = 0u; cnt = 0u; mine = 0u;
; #pragma unroll
;         for (unsigned j = 0; j < 16; ++j) { const unsigned c = xb_ld(&bar[XB_XCNT(j)]); sum += c; cnt += (c > 0u) ? 1u : 0u; mine = (j == x) ? c : mine; }
; __device__ __forceinline__ void xcd_barrier(const XcdBarrier& b) {
;     asm volatile("s_waitcnt vmcnt(0)" ::: "memory");
;     __syncthreads();
;     if (threadIdx.x == 0) {
;         unsigned* bar = b.bar;
;         __builtin_amdgcn_s_waitcnt(0);
;         unsigned nloc = b.st[0], nx = b.st[1];
;         if (nloc == 0u) { xcd_barrier_complete(bar, b.x, nloc, nx); b.st[0] = nloc; b.st[1] = nx; }
.LBB0_1814:
	s_cmp_lt_i32 s57, 17
	s_waitcnt vmcnt(16)
	s_barrier
	s_cbranch_scc1 .LBB0_1868
	s_setprio 0
	s_add_i32 s0, 0, 0x20520
	v_mov_b32_e32 v0, s0
	ds_read_b64 v[0:1], v0
	s_getreg_b32 s3, hwreg(HW_REG_XCC_ID, 0, 4)
	s_waitcnt vmcnt(0)
	s_waitcnt lgkmcnt(0)
	s_barrier
	v_readfirstlane_b32 s4, v0
	v_readfirstlane_b32 s5, v1
	s_mov_b64 s[0:1], exec
	v_readlane_b32 s6, v246, 2
	v_readlane_b32 s7, v246, 3
	s_and_b64 s[6:7], s[0:1], s[6:7]
	s_mov_b64 exec, s[6:7]
	s_cbranch_execz .LBB0_1867
	s_add_i32 s6, 0, 0x20160
	v_mov_b32_e32 v0, s6
	s_waitcnt vmcnt(0) expcnt(0) lgkmcnt(0)
	ds_read_b32 v2, v0
	s_add_i32 s6, 0, 0x20164
	v_mov_b32_e32 v0, s6
	ds_read_b32 v0, v0
	s_and_b32 s3, s3, 15
	s_waitcnt lgkmcnt(1)
	v_cmp_ne_u32_e32 vcc, 0, v2
	s_cbranch_vccnz .LBB0_1831
	v_readlane_b32 s6, v246, 0
	v_readlane_b32 s7, v246, 1
	s_load_dwordx2 s[10:11], s[6:7], 0x4
	s_add_u32 s6, s4, 0x4200
	s_addc_u32 s7, s5, 0
	s_add_u32 s8, s4, 0x4400
	s_addc_u32 s9, s5, 0
	s_waitcnt lgkmcnt(0)
	s_mul_i32 s33, s10, s52
	s_add_u32 s10, s4, 0x4500
	s_mul_i32 s33, s33, s11
	s_addc_u32 s11, s5, 0
	s_add_u32 s12, s4, 0x4600
	s_addc_u32 s13, s5, 0
	s_add_u32 s14, s4, 0x4700
	s_addc_u32 s15, s5, 0
	s_add_u32 s16, s4, 0x4800
	s_addc_u32 s17, s5, 0
	s_add_u32 s18, s4, 0x4900
	s_addc_u32 s19, s5, 0
	s_add_u32 s20, s4, 0x4a00
	s_addc_u32 s21, s5, 0
	s_add_u32 s22, s4, 0x4b00
	s_addc_u32 s23, s5, 0
	s_add_u32 s24, s4, 0x4c00
	s_addc_u32 s25, s5, 0
	s_add_u32 s26, s4, 0x4d00
	s_addc_u32 s27, s5, 0
	s_add_u32 s28, s4, 0x4e00
	s_addc_u32 s29, s5, 0
	s_add_u32 s30, s4, 0x4f00
	s_addc_u32 s31, s5, 0
	s_add_u32 s36, s4, 0x5000
	s_addc_u32 s37, s5, 0
	s_add_u32 s38, s4, 0x5100
	s_addc_u32 s39, s5, 0
	s_add_u32 s40, s4, 0x5200
	s_addc_u32 s41, s5, 0
	s_add_u32 s42, s4, 0x5300
	s_addc_u32 s43, s5, 0
	s_mov_b32 s34, 1
	v_mov_b32_e32 v16, 0
	s_branch .LBB0_1819

; __device__ __forceinline__ unsigned xb_ld(unsigned* p)              { return __hip_atomic_load(p, __ATOMIC_RELAXED, __HIP_MEMORY_SCOPE_AGENT); }
; __device__ __forceinline__ void xcd_barrier_complete(unsigned* bar, unsigned x, unsigned& nloc, unsigned& nx) {
;     const unsigned G = gridDim.x * gridDim.y * gridDim.z;
;     unsigned sum, cnt, mine, sp = 0u;
;     for (;;) {
;         sum = 0u; cnt = 0u; mine = 0u;
; #pragma unroll
;         for (unsigned j = 0; j < 16; ++j) { const unsigned c = xb_ld(&bar[XB_XCNT(j)]); sum += c; cnt += (c > 0u) ? 1u : 0u; mine = (j == x) ? c : mine; }
; __device__ __forceinline__ void xcd_barrier(const XcdBarrier& b) {
;     asm volatile("s_waitcnt vmcnt(0)" ::: "memory");
;     __syncthreads();
;     if (threadIdx.x == 0) {
;         unsigned* bar = b.bar;
;         __builtin_amdgcn_s_waitcnt(0);
;         unsigned nloc = b.st[0], nx = b.st[1];
;         if (nloc == 0u) { xcd_barrier_complete(bar, b.x, nloc, nx); b.st[0] = nloc; b.st[1] = nx; }
.LBB0_1872:
	s_cmp_lt_u32 s57, 18
	s_cbranch_scc1 .LBB0_1926
	s_setprio 0
	s_add_i32 s0, 0, 0x20520
	v_mov_b32_e32 v0, s0
	ds_read_b64 v[0:1], v0
	s_getreg_b32 s3, hwreg(HW_REG_XCC_ID, 0, 4)
	s_waitcnt vmcnt(0)
	s_waitcnt vmcnt(16) lgkmcnt(0)
	s_barrier
	v_readfirstlane_b32 s4, v0
	v_readfirstlane_b32 s5, v1
	s_mov_b64 s[0:1], exec
	v_readlane_b32 s6, v246, 2
	v_readlane_b32 s7, v246, 3
	s_and_b64 s[6:7], s[0:1], s[6:7]
	s_mov_b64 exec, s[6:7]
	s_cbranch_execz .LBB0_1925
	s_add_i32 s6, 0, 0x20160
	v_mov_b32_e32 v0, s6
	s_waitcnt vmcnt(0) expcnt(0) lgkmcnt(0)
	ds_read_b32 v2, v0
	s_add_i32 s6, 0, 0x20164
	v_mov_b32_e32 v0, s6
	ds_read_b32 v0, v0
	s_and_b32 s3, s3, 15
	s_waitcnt lgkmcnt(1)
	v_cmp_ne_u32_e32 vcc, 0, v2
	s_cbranch_vccnz .LBB0_1889
	v_readlane_b32 s6, v246, 0
	v_readlane_b32 s7, v246, 1
	s_load_dwordx2 s[10:11], s[6:7], 0x4
	s_add_u32 s6, s4, 0x4200
	s_addc_u32 s7, s5, 0
	s_add_u32 s8, s4, 0x4400
	s_addc_u32 s9, s5, 0
	s_waitcnt lgkmcnt(0)
	s_mul_i32 s33, s10, s52
	s_add_u32 s10, s4, 0x4500
	s_mul_i32 s33, s33, s11
	s_addc_u32 s11, s5, 0
	s_add_u32 s12, s4, 0x4600
	s_addc_u32 s13, s5, 0
	s_add_u32 s14, s4, 0x4700
	s_addc_u32 s15, s5, 0
	s_add_u32 s16, s4, 0x4800
	s_addc_u32 s17, s5, 0
	s_add_u32 s18, s4, 0x4900
	s_addc_u32 s19, s5, 0
	s_add_u32 s20, s4, 0x4a00
	s_addc_u32 s21, s5, 0
	s_add_u32 s22, s4, 0x4b00
	s_addc_u32 s23, s5, 0
	s_add_u32 s24, s4, 0x4c00
	s_addc_u32 s25, s5, 0
	s_add_u32 s26, s4, 0x4d00
	s_addc_u32 s27, s5, 0
	s_add_u32 s28, s4, 0x4e00
	s_addc_u32 s29, s5, 0
	s_add_u32 s30, s4, 0x4f00
	s_addc_u32 s31, s5, 0
	s_add_u32 s36, s4, 0x5000
	s_addc_u32 s37, s5, 0
	s_add_u32 s38, s4, 0x5100
	s_addc_u32 s39, s5, 0
	s_add_u32 s40, s4, 0x5200
	s_addc_u32 s41, s5, 0
	s_add_u32 s42, s4, 0x5300
	s_addc_u32 s43, s5, 0
	s_mov_b32 s34, 1
	v_mov_b32_e32 v16, 0
	s_branch .LBB0_1877

; #define PG8_STAGE(bufoff, soff, voff) do { _Pragma("unroll") for (int _i = 0; _i < 2; ++_i) \
;         __builtin_amdgcn_raw_ptr_buffer_load_lds(rs_##voff, (PG8_LAS unsigned*)(lds + (bufoff) + ldsw + _i * 8192), 16, (int)(voff)[_i], (int)(soff), 0, 0); } while (0)
; #define PG8_LDA(dst, b, h) do { _Pragma("unroll") for (int m = 0; m < 4; ++m) _Pragma("unroll") for (int k = 0; k < 2; ++k) dst[m][k] = *(const PG8_LAS bf16x8*)(lds + PG8_SA(b, h) + aoff + m * 2048 + k * 1024); } while (0)
; #define PG8_LDB(dst, b, h) do { _Pragma("unroll") for (int n = 0; n < 2; ++n) _Pragma("unroll") for (int k = 0; k < 2; ++k) dst[n][k] = *(const PG8_LAS bf16x8*)(lds + PG8_SB(b, h) + boff + n * 2048 + k * 1024); } while (0)
; #define PG8_MMA(ai, bj, At, Bt) do { __builtin_amdgcn_s_setprio(1); _Pragma("unroll") for (int m = 0; m < 4; ++m) _Pragma("unroll") for (int n = 0; n < 2; ++n) _Pragma("unroll") for (int k = 0; k < 2; ++k) \
;         acc[ai][bj][m][n] = __builtin_amdgcn_mfma_f32_16x16x32_bf16(Bt[n][k], At[m][k], acc[ai][bj][m][n], 0, 0, 0); __builtin_amdgcn_s_setprio(0); } while (0)
; #define PG8_WAIT_V(n) asm volatile("s_waitcnt vmcnt(" #n ")" ::: "memory")
; #define PG8_WAIT_L(n) asm volatile("s_waitcnt lgkmcnt(" #n ")" ::: "memory")
; #define PG8_BAR __builtin_amdgcn_s_barrier()
; #define PG8_SCHED __builtin_amdgcn_sched_barrier(0)
; template <class Epi, class Sched, bool ALIGN_EPI = false, bool SP2 = false>
; __device__ __forceinline__ void gemm_phase(PG8_LAS unsigned char* lds, const Gemm g, const Sched& S, const Epi& E, const int wid  ) {
;     ...
;             PG8_LDB(B0, 0, 0); PG8_LDB(B1, 0, 1); PG8_SCHED; PG8_LDA(At, 0, 0); PG8_STAGE(PG8_SA(1, 1), a1 + hstep, voffA);
;             PG8_WAIT_V(8); PG8_WAIT_L(0); PG8_BAR; PG8_MMA(0, 0, At, B0); PG8_MMA(0, 1, At, B1); PG8_BAR; PG8_SCHED;
;             PG8_LDA(At, 0, 1); PG8_STAGE(PG8_SB(0, 0), b2, voffB); PG8_STAGE(PG8_SB(0, 1), b2 + hstep, voffB); PG8_STAGE(PG8_SA(0, 0), a2, voffA);
;             PG8_WAIT_V(8); PG8_WAIT_L(0); PG8_BAR; PG8_MMA(1, 0, At, B0); PG8_MMA(1, 1, At, B1); PG8_BAR; PG8_SCHED;
.Lprio_2037:
.LBB0_2037:
	s_waitcnt lgkmcnt(0)
	ds_read_b128 v[16:19], v188
	ds_read_b128 v[20:23], v188 offset:1024
	ds_read_b128 v[24:27], v188 offset:2048
	ds_read_b128 v[28:31], v188 offset:3072
	ds_read_b128 v[32:35], v189
	ds_read_b128 v[36:39], v189 offset:1024
	ds_read_b128 v[40:43], v189 offset:2048
	ds_read_b128 v[44:47], v189 offset:3072
	s_add_i32 s18, s8, 0xfff80080
	s_cmp_eq_u32 s48, 28
	s_cselect_b32 s93, s6, s18
	s_cselect_b32 s92, s7, s9
	s_or_b32 s49, s93, 0x80
	s_mov_b32 m0, s74
	ds_read_b128 v[160:163], v190
	ds_read_b128 v[170:173], v190 offset:1024
	ds_read_b128 v[174:177], v190 offset:2048
	ds_read_b128 v[178:181], v190 offset:3072
	ds_read_b128 v[194:197], v190 offset:4096
	ds_read_b128 v[198:201], v190 offset:5120
	ds_read_b128 v[202:205], v190 offset:6144
	ds_read_b128 v[206:209], v190 offset:7168
	buffer_load_dwordx4 v182, s[12:15], s8 offen lds
	s_mov_b32 m0, s76
	s_nop 0
	buffer_load_dwordx4 v184, s[12:15], s8 offen lds
	s_waitcnt vmcnt(8)
	s_waitcnt lgkmcnt(0)
	s_barrier
	s_waitcnt lgkmcnt(7)
	v_mfma_f32_16x16x32_bf16 v[152:155], v[16:19], v[160:163], v[152:155]
	v_mfma_f32_16x16x32_bf16 v[52:55], v[24:27], v[160:163], v[52:55]
	s_waitcnt lgkmcnt(5)
	v_mfma_f32_16x16x32_bf16 v[148:151], v[16:19], v[174:177], v[148:151]
	v_mfma_f32_16x16x32_bf16 v[144:147], v[24:27], v[174:177], v[144:147]
	s_waitcnt lgkmcnt(3)
	v_mfma_f32_16x16x32_bf16 v[140:143], v[16:19], v[194:197], v[140:143]
	v_mfma_f32_16x16x32_bf16 v[132:135], v[24:27], v[194:197], v[132:135]
	s_waitcnt lgkmcnt(1)
	v_mfma_f32_16x16x32_bf16 v[156:159], v[16:19], v[202:205], v[156:159]
	v_mfma_f32_16x16x32_bf16 v[120:123], v[24:27], v[202:205], v[120:123]
	v_mfma_f32_16x16x32_bf16 v[152:155], v[20:23], v[170:173], v[152:155]
	v_mfma_f32_16x16x32_bf16 v[52:55], v[28:31], v[170:173], v[52:55]
	v_mfma_f32_16x16x32_bf16 v[148:151], v[20:23], v[178:181], v[148:151]
	v_mfma_f32_16x16x32_bf16 v[144:147], v[28:31], v[178:181], v[144:147]
	v_mfma_f32_16x16x32_bf16 v[140:143], v[20:23], v[198:201], v[140:143]
	v_mfma_f32_16x16x32_bf16 v[132:135], v[28:31], v[198:201], v[132:135]
	s_waitcnt lgkmcnt(0)
	v_mfma_f32_16x16x32_bf16 v[156:159], v[20:23], v[206:209], v[156:159]
	v_mfma_f32_16x16x32_bf16 v[120:123], v[28:31], v[206:209], v[120:123]
	v_mfma_f32_16x16x32_bf16 v[12:15], v[32:35], v[160:163], v[12:15]
	v_mfma_f32_16x16x32_bf16 v[8:11], v[40:43], v[160:163], v[8:11]
	v_mfma_f32_16x16x32_bf16 v[136:139], v[32:35], v[174:177], v[136:139]
	v_mfma_f32_16x16x32_bf16 v[128:131], v[40:43], v[174:177], v[128:131]
	v_mfma_f32_16x16x32_bf16 v[124:127], v[32:35], v[194:197], v[124:127]
	v_mfma_f32_16x16x32_bf16 v[116:119], v[40:43], v[194:197], v[116:119]
	v_mfma_f32_16x16x32_bf16 v[112:115], v[32:35], v[202:205], v[112:115]
	v_mfma_f32_16x16x32_bf16 v[108:111], v[40:43], v[202:205], v[108:111]
	v_mfma_f32_16x16x32_bf16 v[12:15], v[36:39], v[170:173], v[12:15]
	v_mfma_f32_16x16x32_bf16 v[8:11], v[44:47], v[170:173], v[8:11]
	v_mfma_f32_16x16x32_bf16 v[136:139], v[36:39], v[178:181], v[136:139]
	v_mfma_f32_16x16x32_bf16 v[128:131], v[44:47], v[178:181], v[128:131]
	v_mfma_f32_16x16x32_bf16 v[124:127], v[36:39], v[198:201], v[124:127]
	v_mfma_f32_16x16x32_bf16 v[116:119], v[44:47], v[198:201], v[116:119]
	v_mfma_f32_16x16x32_bf16 v[112:115], v[36:39], v[206:209], v[112:115]
	v_mfma_f32_16x16x32_bf16 v[108:111], v[44:47], v[206:209], v[108:111]
	s_barrier
	s_mov_b32 m0, s34
	s_mov_b32 s18, s14
	s_mov_b32 s19, s15
	ds_read_b128 v[160:163], v190 offset:16384
	ds_read_b128 v[170:173], v190 offset:17408
	ds_read_b128 v[174:177], v190 offset:18432
	ds_read_b128 v[178:181], v190 offset:19456
	ds_read_b128 v[194:197], v190 offset:20480
	ds_read_b128 v[198:201], v190 offset:21504
	ds_read_b128 v[202:205], v190 offset:22528
	ds_read_b128 v[206:209], v190 offset:23552
	buffer_load_dwordx4 v183, s[16:19], s92 offen lds
	s_mov_b32 m0, s35
	s_add_i32 s94, s92, 0x80000
	buffer_load_dwordx4 v185, s[16:19], s92 offen lds
	s_mov_b32 m0, s50
	s_nop 0
	buffer_load_dwordx4 v183, s[16:19], s94 offen lds
	s_mov_b32 m0, s51
	s_nop 0
	buffer_load_dwordx4 v185, s[16:19], s94 offen lds
	s_mov_b32 m0, s33
	s_nop 0
	buffer_load_dwordx4 v182, s[12:15], s93 offen lds
	s_mov_b32 m0, s53
	s_nop 0
	buffer_load_dwordx4 v184, s[12:15], s93 offen lds
	s_waitcnt vmcnt(8)
	s_waitcnt lgkmcnt(0)
	s_barrier
	s_waitcnt lgkmcnt(7)
	v_mfma_f32_16x16x32_bf16 v[104:107], v[16:19], v[160:163], v[104:107]
	v_mfma_f32_16x16x32_bf16 v[100:103], v[24:27], v[160:163], v[100:103]
	s_waitcnt lgkmcnt(5)
	v_mfma_f32_16x16x32_bf16 v[96:99], v[16:19], v[174:177], v[96:99]
	v_mfma_f32_16x16x32_bf16 v[88:91], v[24:27], v[174:177], v[88:91]
	s_waitcnt lgkmcnt(3)
	v_mfma_f32_16x16x32_bf16 v[84:87], v[16:19], v[194:197], v[84:87]
	v_mfma_f32_16x16x32_bf16 v[76:79], v[24:27], v[194:197], v[76:79]
	s_waitcnt lgkmcnt(1)
	v_mfma_f32_16x16x32_bf16 v[16:19], v[16:19], v[202:205], v[92:95]
	v_mfma_f32_16x16x32_bf16 v[104:107], v[20:23], v[170:173], v[104:107]
	v_mfma_f32_16x16x32_bf16 v[100:103], v[28:31], v[170:173], v[100:103]
	v_mfma_f32_16x16x32_bf16 v[96:99], v[20:23], v[178:181], v[96:99]
	v_mfma_f32_16x16x32_bf16 v[88:91], v[28:31], v[178:181], v[88:91]
	v_mfma_f32_16x16x32_bf16 v[84:87], v[20:23], v[198:201], v[84:87]
	v_mfma_f32_16x16x32_bf16 v[76:79], v[28:31], v[198:201], v[76:79]
	s_waitcnt lgkmcnt(0)
	v_mfma_f32_16x16x32_bf16 v[16:19], v[20:23], v[206:209], v[16:19]
	v_mfma_f32_16x16x32_bf16 v[20:23], v[24:27], v[202:205], v[48:51]
	v_mfma_f32_16x16x32_bf16 v[20:23], v[28:31], v[206:209], v[20:23]
	v_mfma_f32_16x16x32_bf16 v[48:51], v[32:35], v[194:197], v[68:71]
	v_mfma_f32_16x16x32_bf16 v[4:7], v[32:35], v[160:163], v[4:7]
	v_mfma_f32_16x16x32_bf16 v[0:3], v[40:43], v[160:163], v[0:3]
	v_mfma_f32_16x16x32_bf16 v[24:27], v[32:35], v[174:177], v[80:83]
	v_mfma_f32_16x16x32_bf16 v[68:71], v[36:39], v[198:201], v[48:51]
	v_mfma_f32_16x16x32_bf16 v[48:51], v[40:43], v[194:197], v[64:67]
	v_mfma_f32_16x16x32_bf16 v[32:35], v[32:35], v[202:205], v[60:63]
	v_mfma_f32_16x16x32_bf16 v[4:7], v[36:39], v[170:173], v[4:7]
	v_mfma_f32_16x16x32_bf16 v[0:3], v[44:47], v[170:173], v[0:3]
	v_mfma_f32_16x16x32_bf16 v[24:27], v[36:39], v[178:181], v[24:27]
	v_mfma_f32_16x16x32_bf16 v[28:31], v[40:43], v[174:177], v[72:75]
	v_mfma_f32_16x16x32_bf16 v[64:67], v[44:47], v[198:201], v[48:51]
	v_mfma_f32_16x16x32_bf16 v[32:35], v[36:39], v[206:209], v[32:35]
	v_mfma_f32_16x16x32_bf16 v[36:39], v[40:43], v[202:205], v[56:59]
	v_mfma_f32_16x16x32_bf16 v[28:31], v[44:47], v[178:181], v[28:31]
	v_mfma_f32_16x16x32_bf16 v[36:39], v[44:47], v[206:209], v[36:39]
	s_barrier
; #define PG8_STAGE(bufoff, soff, voff) do { _Pragma("unroll") for (int _i = 0; _i < 2; ++_i) \
;         __builtin_amdgcn_raw_ptr_buffer_load_lds(rs_##voff, (PG8_LAS unsigned*)(lds + (bufoff) + ldsw + _i * 8192), 16, (int)(voff)[_i], (int)(soff), 0, 0); } while (0)
; #define PG8_LDA(dst, b, h) do { _Pragma("unroll") for (int m = 0; m < 4; ++m) _Pragma("unroll") for (int k = 0; k < 2; ++k) dst[m][k] = *(const PG8_LAS bf16x8*)(lds + PG8_SA(b, h) + aoff + m * 2048 + k * 1024); } while (0)
; #define PG8_LDB(dst, b, h) do { _Pragma("unroll") for (int n = 0; n < 2; ++n) _Pragma("unroll") for (int k = 0; k < 2; ++k) dst[n][k] = *(const PG8_LAS bf16x8*)(lds + PG8_SB(b, h) + boff + n * 2048 + k * 1024); } while (0)
; #define PG8_MMA(ai, bj, At, Bt) do { __builtin_amdgcn_s_setprio(1); _Pragma("unroll") for (int m = 0; m < 4; ++m) _Pragma("unroll") for (int n = 0; n < 2; ++n) _Pragma("unroll") for (int k = 0; k < 2; ++k) \
;         acc[ai][bj][m][n] = __builtin_amdgcn_mfma_f32_16x16x32_bf16(Bt[n][k], At[m][k], acc[ai][bj][m][n], 0, 0, 0); __builtin_amdgcn_s_setprio(0); } while (0)
; #define PG8_WAIT_V(n) asm volatile("s_waitcnt vmcnt(" #n ")" ::: "memory")
; #define PG8_WAIT_L(n) asm volatile("s_waitcnt lgkmcnt(" #n ")" ::: "memory")
; #define PG8_BAR __builtin_amdgcn_s_barrier()
; #define PG8_SCHED __builtin_amdgcn_sched_barrier(0)
; template <class Epi, class Sched, bool ALIGN_EPI = false, bool SP2 = false>
; __device__ __forceinline__ void gemm_phase(PG8_LAS unsigned char* lds, const Gemm g, const Sched& S, const Epi& E, const int wid  ) {
;     ...
;             PG8_LDB(B0, 1, 0); PG8_LDB(B1, 1, 1); PG8_SCHED; PG8_LDA(At, 1, 0); PG8_STAGE(PG8_SA(0, 1), a2 + hstep, voffA);
;             PG8_WAIT_V(8); PG8_WAIT_L(0); PG8_BAR; PG8_MMA(0, 0, At, B0); PG8_MMA(0, 1, At, B1); PG8_BAR; PG8_SCHED;
;             PG8_LDA(At, 1, 1); PG8_STAGE(PG8_SB(1, 0), b3, voffB); PG8_STAGE(PG8_SB(1, 1), b3 + hstep, voffB); PG8_STAGE(PG8_SA(1, 0), a3, voffA);
;             PG8_WAIT_V(8); PG8_WAIT_L(0); PG8_BAR; PG8_MMA(1, 0, At, B0); PG8_MMA(1, 1, At, B1); PG8_BAR; PG8_SCHED;
;     ...
;         if constexpr (ALIGN_EPI) { if (wr == 0) PG8_BAR; }
	ds_read_b128 v[40:43], v191
	ds_read_b128 v[44:47], v191 offset:1024
	ds_read_b128 v[48:51], v191 offset:2048
	ds_read_b128 v[56:59], v191 offset:3072
	ds_read_b128 v[60:63], v192
	ds_read_b128 v[160:163], v192 offset:1024
	ds_read_b128 v[170:173], v192 offset:2048
	ds_read_b128 v[174:177], v192 offset:3072
	s_add_i32 s93, s93, 0x80000
	s_mov_b32 m0, s54
	ds_read_b128 v[72:75], v190 offset:32768
	ds_read_b128 v[80:83], v190 offset:33792
	ds_read_b128 v[92:95], v190 offset:34816
	ds_read_b128 v[178:181], v190 offset:35840
	ds_read_b128 v[194:197], v190 offset:36864
	ds_read_b128 v[198:201], v190 offset:37888
	ds_read_b128 v[202:205], v190 offset:38912
	ds_read_b128 v[206:209], v190 offset:39936
	buffer_load_dwordx4 v182, s[12:15], s93 offen lds
	s_mov_b32 m0, s58
	s_nop 0
	buffer_load_dwordx4 v184, s[12:15], s93 offen lds
	s_waitcnt vmcnt(8)
	s_waitcnt lgkmcnt(0)
	s_barrier
	s_waitcnt lgkmcnt(7)
	v_mfma_f32_16x16x32_bf16 v[152:155], v[40:43], v[72:75], v[152:155]
	v_mfma_f32_16x16x32_bf16 v[52:55], v[48:51], v[72:75], v[52:55]
	s_waitcnt lgkmcnt(5)
	v_mfma_f32_16x16x32_bf16 v[148:151], v[40:43], v[92:95], v[148:151]
	v_mfma_f32_16x16x32_bf16 v[144:147], v[48:51], v[92:95], v[144:147]
	s_waitcnt lgkmcnt(3)
	v_mfma_f32_16x16x32_bf16 v[140:143], v[40:43], v[194:197], v[140:143]
	v_mfma_f32_16x16x32_bf16 v[132:135], v[48:51], v[194:197], v[132:135]
	s_waitcnt lgkmcnt(1)
	v_mfma_f32_16x16x32_bf16 v[156:159], v[40:43], v[202:205], v[156:159]
	v_mfma_f32_16x16x32_bf16 v[120:123], v[48:51], v[202:205], v[120:123]
	v_mfma_f32_16x16x32_bf16 v[152:155], v[44:47], v[80:83], v[152:155]
	v_mfma_f32_16x16x32_bf16 v[52:55], v[56:59], v[80:83], v[52:55]
	v_mfma_f32_16x16x32_bf16 v[148:151], v[44:47], v[178:181], v[148:151]
	v_mfma_f32_16x16x32_bf16 v[144:147], v[56:59], v[178:181], v[144:147]
	v_mfma_f32_16x16x32_bf16 v[140:143], v[44:47], v[198:201], v[140:143]
	v_mfma_f32_16x16x32_bf16 v[132:135], v[56:59], v[198:201], v[132:135]
	s_waitcnt lgkmcnt(0)
	v_mfma_f32_16x16x32_bf16 v[156:159], v[44:47], v[206:209], v[156:159]
	v_mfma_f32_16x16x32_bf16 v[120:123], v[56:59], v[206:209], v[120:123]
	v_mfma_f32_16x16x32_bf16 v[12:15], v[60:63], v[72:75], v[12:15]
	v_mfma_f32_16x16x32_bf16 v[8:11], v[170:173], v[72:75], v[8:11]
	v_mfma_f32_16x16x32_bf16 v[72:75], v[60:63], v[92:95], v[136:139]
	v_mfma_f32_16x16x32_bf16 v[136:139], v[160:163], v[178:181], v[72:75]
	v_mfma_f32_16x16x32_bf16 v[72:75], v[170:173], v[92:95], v[128:131]
	v_mfma_f32_16x16x32_bf16 v[128:131], v[174:177], v[178:181], v[72:75]
	v_mfma_f32_16x16x32_bf16 v[72:75], v[60:63], v[194:197], v[124:127]
	v_mfma_f32_16x16x32_bf16 v[124:127], v[160:163], v[198:201], v[72:75]
	v_mfma_f32_16x16x32_bf16 v[72:75], v[170:173], v[194:197], v[116:119]
	v_mfma_f32_16x16x32_bf16 v[116:119], v[174:177], v[198:201], v[72:75]
	v_mfma_f32_16x16x32_bf16 v[72:75], v[60:63], v[202:205], v[112:115]
	v_mfma_f32_16x16x32_bf16 v[112:115], v[160:163], v[206:209], v[72:75]
	v_mfma_f32_16x16x32_bf16 v[72:75], v[170:173], v[202:205], v[108:111]
	v_mfma_f32_16x16x32_bf16 v[12:15], v[160:163], v[80:83], v[12:15]
	v_mfma_f32_16x16x32_bf16 v[8:11], v[174:177], v[80:83], v[8:11]
	v_mfma_f32_16x16x32_bf16 v[108:111], v[174:177], v[206:209], v[72:75]
	s_barrier
	s_mov_b32 m0, s63
	s_or_b32 s93, s92, 0x80
	s_nop 0
	ds_read_b128 v[72:75], v190 offset:49152
	ds_read_b128 v[80:83], v190 offset:50176
	ds_read_b128 v[178:181], v190 offset:51200
	ds_read_b128 v[194:197], v190 offset:52224
	ds_read_b128 v[198:201], v190 offset:53248
	ds_read_b128 v[202:205], v190 offset:54272
	ds_read_b128 v[206:209], v190 offset:55296
	ds_read_b128 v[210:213], v190 offset:56320
	buffer_load_dwordx4 v183, s[16:19], s93 offen lds
	s_mov_b32 m0, s65
	s_add_i32 s92, s92, 0x80080
	buffer_load_dwordx4 v185, s[16:19], s93 offen lds
	s_mov_b32 m0, s68
	s_nop 0
	buffer_load_dwordx4 v183, s[16:19], s92 offen lds
	s_mov_b32 m0, s69
	s_nop 0
	buffer_load_dwordx4 v185, s[16:19], s92 offen lds
	s_mov_b32 m0, s66
	s_nop 0
	buffer_load_dwordx4 v182, s[12:15], s49 offen lds
	s_mov_b32 m0, s67
	s_nop 0
	buffer_load_dwordx4 v184, s[12:15], s49 offen lds
	s_waitcnt vmcnt(8)
	s_waitcnt lgkmcnt(0)
	s_barrier
	s_waitcnt lgkmcnt(7)
	v_mfma_f32_16x16x32_bf16 v[92:95], v[40:43], v[72:75], v[104:107]
	s_waitcnt lgkmcnt(6)
	v_mfma_f32_16x16x32_bf16 v[104:107], v[44:47], v[80:83], v[92:95]
	v_mfma_f32_16x16x32_bf16 v[92:95], v[48:51], v[72:75], v[100:103]
	v_mfma_f32_16x16x32_bf16 v[100:103], v[56:59], v[80:83], v[92:95]
	s_waitcnt lgkmcnt(5)
	v_mfma_f32_16x16x32_bf16 v[92:95], v[40:43], v[178:181], v[96:99]
	s_waitcnt lgkmcnt(1)
	v_mfma_f32_16x16x32_bf16 v[16:19], v[40:43], v[206:209], v[16:19]
	v_mfma_f32_16x16x32_bf16 v[96:99], v[44:47], v[194:197], v[92:95]
	v_mfma_f32_16x16x32_bf16 v[88:91], v[48:51], v[178:181], v[88:91]
	v_mfma_f32_16x16x32_bf16 v[84:87], v[40:43], v[198:201], v[84:87]
	v_mfma_f32_16x16x32_bf16 v[76:79], v[48:51], v[198:201], v[76:79]
	s_waitcnt lgkmcnt(0)
	v_mfma_f32_16x16x32_bf16 v[92:95], v[44:47], v[210:213], v[16:19]
	v_mfma_f32_16x16x32_bf16 v[16:19], v[48:51], v[206:209], v[20:23]
	v_mfma_f32_16x16x32_bf16 v[88:91], v[56:59], v[194:197], v[88:91]
	v_mfma_f32_16x16x32_bf16 v[84:87], v[44:47], v[202:205], v[84:87]
	v_mfma_f32_16x16x32_bf16 v[76:79], v[56:59], v[202:205], v[76:79]
	v_mfma_f32_16x16x32_bf16 v[48:51], v[56:59], v[210:213], v[16:19]
	v_mfma_f32_16x16x32_bf16 v[4:7], v[60:63], v[72:75], v[4:7]
	v_mfma_f32_16x16x32_bf16 v[0:3], v[170:173], v[72:75], v[0:3]
	v_mfma_f32_16x16x32_bf16 v[16:19], v[60:63], v[178:181], v[24:27]
	v_mfma_f32_16x16x32_bf16 v[4:7], v[160:163], v[80:83], v[4:7]
	v_mfma_f32_16x16x32_bf16 v[0:3], v[174:177], v[80:83], v[0:3]
	v_mfma_f32_16x16x32_bf16 v[80:83], v[160:163], v[194:197], v[16:19]
	v_mfma_f32_16x16x32_bf16 v[16:19], v[170:173], v[178:181], v[28:31]
	v_mfma_f32_16x16x32_bf16 v[72:75], v[174:177], v[194:197], v[16:19]
	v_mfma_f32_16x16x32_bf16 v[16:19], v[60:63], v[198:201], v[68:71]
	v_mfma_f32_16x16x32_bf16 v[68:71], v[160:163], v[202:205], v[16:19]
	v_mfma_f32_16x16x32_bf16 v[16:19], v[170:173], v[198:201], v[64:67]
	v_mfma_f32_16x16x32_bf16 v[64:67], v[174:177], v[202:205], v[16:19]
	v_mfma_f32_16x16x32_bf16 v[16:19], v[60:63], v[206:209], v[32:35]
	v_mfma_f32_16x16x32_bf16 v[60:63], v[160:163], v[210:213], v[16:19]
	v_mfma_f32_16x16x32_bf16 v[16:19], v[170:173], v[206:209], v[36:39]
	v_mfma_f32_16x16x32_bf16 v[56:59], v[174:177], v[210:213], v[16:19]
	s_barrier
	s_add_i32 s48, s48, 2
	s_addk_i32 s8, 0x100
	s_addk_i32 s9, 0x100
	s_cmp_gt_u32 s48, 29
	s_cbranch_scc0 .LBB0_2037
	s_and_b64 vcc, exec, s[28:29]
	s_cbranch_vccz .LBB0_2040
	s_barrier

; __device__ __forceinline__ unsigned xb_ld(unsigned* p)              { return __hip_atomic_load(p, __ATOMIC_RELAXED, __HIP_MEMORY_SCOPE_AGENT); }
; __device__ __forceinline__ void xcd_barrier_complete(unsigned* bar, unsigned x, unsigned& nloc, unsigned& nx) {
;     const unsigned G = gridDim.x * gridDim.y * gridDim.z;
;     unsigned sum, cnt, mine, sp = 0u;
;     for (;;) {
;         sum = 0u; cnt = 0u; mine = 0u;
; #pragma unroll
;         for (unsigned j = 0; j < 16; ++j) { const unsigned c = xb_ld(&bar[XB_XCNT(j)]); sum += c; cnt += (c > 0u) ? 1u : 0u; mine = (j == x) ? c : mine; }
; __device__ __forceinline__ void xcd_barrier(const XcdBarrier& b) {
;     asm volatile("s_waitcnt vmcnt(0)" ::: "memory");
;     __syncthreads();
;     if (threadIdx.x == 0) {
;         unsigned* bar = b.bar;
;         __builtin_amdgcn_s_waitcnt(0);
;         unsigned nloc = b.st[0], nx = b.st[1];
;         if (nloc == 0u) { xcd_barrier_complete(bar, b.x, nloc, nx); b.st[0] = nloc; b.st[1] = nx; }
.LBB0_2182:
	s_cmp_lt_i32 s57, 20
	s_cbranch_scc1 .LBB0_2351
	s_setprio 0
	s_add_i32 s0, 0, 0x20520
	v_mov_b32_e32 v0, s0
	ds_read_b64 v[0:1], v0
	s_getreg_b32 s3, hwreg(HW_REG_XCC_ID, 0, 4)
	s_waitcnt vmcnt(0)
	s_waitcnt vmcnt(16) lgkmcnt(0)
	s_barrier
	v_readfirstlane_b32 s4, v0
	v_readfirstlane_b32 s5, v1
	s_mov_b64 s[0:1], exec
	v_readlane_b32 s6, v246, 2
	v_readlane_b32 s7, v246, 3
	s_and_b64 s[6:7], s[0:1], s[6:7]
	s_mov_b64 exec, s[6:7]
	s_cbranch_execz .LBB0_2350
	s_add_i32 s6, 0, 0x20160
	v_mov_b32_e32 v0, s6
	s_waitcnt vmcnt(0) expcnt(0) lgkmcnt(0)
	ds_read_b32 v2, v0
	s_add_i32 s6, 0, 0x20164
	v_mov_b32_e32 v0, s6
	ds_read_b32 v0, v0
	s_and_b32 s3, s3, 15
	s_waitcnt lgkmcnt(1)
	v_cmp_ne_u32_e32 vcc, 0, v2
	s_cbranch_vccnz .LBB0_2314
	v_readlane_b32 s6, v246, 0
	v_readlane_b32 s7, v246, 1
	s_load_dwordx2 s[10:11], s[6:7], 0x4
	s_add_u32 s6, s4, 0x4200
	s_addc_u32 s7, s5, 0
	s_add_u32 s8, s4, 0x4400
	s_addc_u32 s9, s5, 0
	s_waitcnt lgkmcnt(0)
	s_mul_i32 s33, s10, s52
	s_add_u32 s10, s4, 0x4500
	s_mul_i32 s33, s33, s11
	s_addc_u32 s11, s5, 0
	s_add_u32 s12, s4, 0x4600
	s_addc_u32 s13, s5, 0
	s_add_u32 s14, s4, 0x4700
	s_addc_u32 s15, s5, 0
	s_add_u32 s16, s4, 0x4800
	s_addc_u32 s17, s5, 0
	s_add_u32 s18, s4, 0x4900
	s_addc_u32 s19, s5, 0
	s_add_u32 s20, s4, 0x4a00
	s_addc_u32 s21, s5, 0
	s_add_u32 s22, s4, 0x4b00
	s_addc_u32 s23, s5, 0
	s_add_u32 s24, s4, 0x4c00
	s_addc_u32 s25, s5, 0
	s_add_u32 s26, s4, 0x4d00
	s_addc_u32 s27, s5, 0
	s_add_u32 s28, s4, 0x4e00
	s_addc_u32 s29, s5, 0
	s_add_u32 s30, s4, 0x4f00
	s_addc_u32 s31, s5, 0
	s_add_u32 s36, s4, 0x5000
	s_addc_u32 s37, s5, 0
	s_add_u32 s38, s4, 0x5100
	s_addc_u32 s39, s5, 0
	s_add_u32 s40, s4, 0x5200
	s_addc_u32 s41, s5, 0
	s_add_u32 s42, s4, 0x5300
	s_addc_u32 s43, s5, 0
	s_mov_b32 s34, 1
	v_mov_b32_e32 v16, 0
	s_branch .LBB0_2187

; #define PG8_STAGE(bufoff, soff, voff) do { _Pragma("unroll") for (int _i = 0; _i < 2; ++_i) \
;         __builtin_amdgcn_raw_ptr_buffer_load_lds(rs_##voff, (PG8_LAS unsigned*)(lds + (bufoff) + ldsw + _i * 8192), 16, (int)(voff)[_i], (int)(soff), 0, 0); } while (0)
; #define PG8_LDA(dst, b, h) do { _Pragma("unroll") for (int m = 0; m < 4; ++m) _Pragma("unroll") for (int k = 0; k < 2; ++k) dst[m][k] = *(const PG8_LAS bf16x8*)(lds + PG8_SA(b, h) + aoff + m * 2048 + k * 1024); } while (0)
; #define PG8_LDB(dst, b, h) do { _Pragma("unroll") for (int n = 0; n < 2; ++n) _Pragma("unroll") for (int k = 0; k < 2; ++k) dst[n][k] = *(const PG8_LAS bf16x8*)(lds + PG8_SB(b, h) + boff + n * 2048 + k * 1024); } while (0)
; #define PG8_MMA(ai, bj, At, Bt) do { __builtin_amdgcn_s_setprio(1); _Pragma("unroll") for (int m = 0; m < 4; ++m) _Pragma("unroll") for (int n = 0; n < 2; ++n) _Pragma("unroll") for (int k = 0; k < 2; ++k) \
;         acc[ai][bj][m][n] = __builtin_amdgcn_mfma_f32_16x16x32_bf16(Bt[n][k], At[m][k], acc[ai][bj][m][n], 0, 0, 0); __builtin_amdgcn_s_setprio(0); } while (0)
; #define PG8_WAIT_V(n) asm volatile("s_waitcnt vmcnt(" #n ")" ::: "memory")
; #define PG8_WAIT_L(n) asm volatile("s_waitcnt lgkmcnt(" #n ")" ::: "memory")
; #define PG8_BAR __builtin_amdgcn_s_barrier()
; #define PG8_SCHED __builtin_amdgcn_sched_barrier(0)
; template <class Epi, class Sched, bool ALIGN_EPI = false, bool SP2 = false>
; __device__ __forceinline__ void gemm_phase(PG8_LAS unsigned char* lds, const Gemm g, const Sched& S, const Epi& E, const int wid  ) {
;     ...
;             PG8_LDB(B0, 0, 0); PG8_LDB(B1, 0, 1); PG8_SCHED; PG8_LDA(At, 0, 0); PG8_STAGE(PG8_SA(1, 1), a1 + hstep, voffA);
;             PG8_WAIT_V(8); PG8_WAIT_L(0); PG8_BAR; PG8_MMA(0, 0, At, B0); PG8_MMA(0, 1, At, B1); PG8_BAR; PG8_SCHED;
;             PG8_LDA(At, 0, 1); PG8_STAGE(PG8_SB(0, 0), b2, voffB); PG8_STAGE(PG8_SB(0, 1), b2 + hstep, voffB); PG8_STAGE(PG8_SA(0, 0), a2, voffA);
;             PG8_WAIT_V(8); PG8_WAIT_L(0); PG8_BAR; PG8_MMA(1, 0, At, B0); PG8_MMA(1, 1, At, B1); PG8_BAR; PG8_SCHED;
.Lprio_2380:
.LBB0_2380:
	ds_read_b128 v[132:135], v140
	ds_read_b128 v[146:149], v140 offset:1024
	ds_read_b128 v[150:153], v140 offset:2048
	ds_read_b128 v[154:157], v140 offset:3072
	ds_read_b128 v[158:161], v141
	ds_read_b128 v[162:165], v141 offset:1024
	ds_read_b128 v[166:169], v141 offset:2048
	ds_read_b128 v[170:173], v141 offset:3072
	s_add_i32 s14, s16, 0xffea0080
	s_cmpk_eq_i32 s58, 0x54
	s_cselect_b32 s61, s0, s14
	s_cselect_b32 s60, s1, s55
	s_or_b32 s59, s61, 0x80
	s_mov_b32 m0, s45
	ds_read_b128 v[174:177], v142
	ds_read_b128 v[178:181], v142 offset:1024
	ds_read_b128 v[182:185], v142 offset:2048
	ds_read_b128 v[186:189], v142 offset:3072
	ds_read_b128 v[190:193], v142 offset:4096
	ds_read_b128 v[194:197], v142 offset:5120
	ds_read_b128 v[198:201], v142 offset:6144
	ds_read_b128 v[202:205], v142 offset:7168
	buffer_load_dwordx4 v136, s[8:11], s16 offen lds
	s_mov_b32 m0, s46
	s_nop 0
	buffer_load_dwordx4 v138, s[8:11], s16 offen lds
	s_waitcnt vmcnt(8)
	s_waitcnt lgkmcnt(0)
	s_barrier
	s_waitcnt lgkmcnt(7)
	v_mfma_f32_16x16x32_bf16 v[124:127], v[132:135], v[174:177], v[124:127]
	v_mfma_f32_16x16x32_bf16 v[120:123], v[150:153], v[174:177], v[120:123]
	s_waitcnt lgkmcnt(5)
	v_mfma_f32_16x16x32_bf16 v[108:111], v[132:135], v[182:185], v[108:111]
	v_mfma_f32_16x16x32_bf16 v[104:107], v[150:153], v[182:185], v[104:107]
	s_waitcnt lgkmcnt(3)
	v_mfma_f32_16x16x32_bf16 v[92:95], v[132:135], v[190:193], v[92:95]
	v_mfma_f32_16x16x32_bf16 v[88:91], v[150:153], v[190:193], v[88:91]
	s_waitcnt lgkmcnt(1)
	v_mfma_f32_16x16x32_bf16 v[76:79], v[132:135], v[198:201], v[76:79]
	v_mfma_f32_16x16x32_bf16 v[72:75], v[150:153], v[198:201], v[72:75]
	v_mfma_f32_16x16x32_bf16 v[124:127], v[146:149], v[178:181], v[124:127]
	v_mfma_f32_16x16x32_bf16 v[120:123], v[154:157], v[178:181], v[120:123]
	v_mfma_f32_16x16x32_bf16 v[108:111], v[146:149], v[186:189], v[108:111]
	v_mfma_f32_16x16x32_bf16 v[104:107], v[154:157], v[186:189], v[104:107]
	v_mfma_f32_16x16x32_bf16 v[92:95], v[146:149], v[194:197], v[92:95]
	v_mfma_f32_16x16x32_bf16 v[88:91], v[154:157], v[194:197], v[88:91]
	s_waitcnt lgkmcnt(0)
	v_mfma_f32_16x16x32_bf16 v[76:79], v[146:149], v[202:205], v[76:79]
	v_mfma_f32_16x16x32_bf16 v[72:75], v[154:157], v[202:205], v[72:75]
	v_mfma_f32_16x16x32_bf16 v[116:119], v[158:161], v[174:177], v[116:119]
	v_mfma_f32_16x16x32_bf16 v[112:115], v[166:169], v[174:177], v[112:115]
	v_mfma_f32_16x16x32_bf16 v[100:103], v[158:161], v[182:185], v[100:103]
	v_mfma_f32_16x16x32_bf16 v[96:99], v[166:169], v[182:185], v[96:99]
	v_mfma_f32_16x16x32_bf16 v[84:87], v[158:161], v[190:193], v[84:87]
	v_mfma_f32_16x16x32_bf16 v[80:83], v[166:169], v[190:193], v[80:83]
	v_mfma_f32_16x16x32_bf16 v[68:71], v[158:161], v[198:201], v[68:71]
	v_mfma_f32_16x16x32_bf16 v[64:67], v[166:169], v[198:201], v[64:67]
	v_mfma_f32_16x16x32_bf16 v[116:119], v[162:165], v[178:181], v[116:119]
	v_mfma_f32_16x16x32_bf16 v[112:115], v[170:173], v[178:181], v[112:115]
	v_mfma_f32_16x16x32_bf16 v[100:103], v[162:165], v[186:189], v[100:103]
	v_mfma_f32_16x16x32_bf16 v[96:99], v[170:173], v[186:189], v[96:99]
	v_mfma_f32_16x16x32_bf16 v[84:87], v[162:165], v[194:197], v[84:87]
	v_mfma_f32_16x16x32_bf16 v[80:83], v[170:173], v[194:197], v[80:83]
	v_mfma_f32_16x16x32_bf16 v[68:71], v[162:165], v[202:205], v[68:71]
	v_mfma_f32_16x16x32_bf16 v[64:67], v[170:173], v[202:205], v[64:67]
	s_barrier
	s_mov_b32 m0, s28
	s_mov_b32 s14, s10
	s_mov_b32 s15, s11
	ds_read_b128 v[174:177], v142 offset:16384
	ds_read_b128 v[178:181], v142 offset:17408
	ds_read_b128 v[182:185], v142 offset:18432
	ds_read_b128 v[186:189], v142 offset:19456
	ds_read_b128 v[190:193], v142 offset:20480
	ds_read_b128 v[194:197], v142 offset:21504
	ds_read_b128 v[198:201], v142 offset:22528
	ds_read_b128 v[202:205], v142 offset:23552
	buffer_load_dwordx4 v137, s[12:15], s60 offen lds
	s_mov_b32 m0, s29
	s_add_i32 s62, s60, 0x160000
	buffer_load_dwordx4 v139, s[12:15], s60 offen lds
	s_mov_b32 m0, s30
	s_nop 0
	buffer_load_dwordx4 v137, s[12:15], s62 offen lds
	s_mov_b32 m0, s31
	s_nop 0
	buffer_load_dwordx4 v139, s[12:15], s62 offen lds
	s_mov_b32 m0, s27
	s_nop 0
	buffer_load_dwordx4 v136, s[8:11], s61 offen lds
	s_mov_b32 m0, s33
	s_nop 0
	buffer_load_dwordx4 v138, s[8:11], s61 offen lds
	s_waitcnt vmcnt(8)
	s_waitcnt lgkmcnt(0)
	s_barrier
	s_waitcnt lgkmcnt(7)
	v_mfma_f32_16x16x32_bf16 v[60:63], v[132:135], v[174:177], v[60:63]
	v_mfma_f32_16x16x32_bf16 v[56:59], v[150:153], v[174:177], v[56:59]
	s_waitcnt lgkmcnt(5)
	v_mfma_f32_16x16x32_bf16 v[44:47], v[132:135], v[182:185], v[44:47]
	v_mfma_f32_16x16x32_bf16 v[40:43], v[150:153], v[182:185], v[40:43]
	s_waitcnt lgkmcnt(3)
	v_mfma_f32_16x16x32_bf16 v[28:31], v[132:135], v[190:193], v[28:31]
	v_mfma_f32_16x16x32_bf16 v[24:27], v[150:153], v[190:193], v[24:27]
	s_waitcnt lgkmcnt(1)
	v_mfma_f32_16x16x32_bf16 v[12:15], v[132:135], v[198:201], v[12:15]
	v_mfma_f32_16x16x32_bf16 v[8:11], v[150:153], v[198:201], v[8:11]
	v_mfma_f32_16x16x32_bf16 v[60:63], v[146:149], v[178:181], v[60:63]
	v_mfma_f32_16x16x32_bf16 v[56:59], v[154:157], v[178:181], v[56:59]
	v_mfma_f32_16x16x32_bf16 v[44:47], v[146:149], v[186:189], v[44:47]
	v_mfma_f32_16x16x32_bf16 v[40:43], v[154:157], v[186:189], v[40:43]
	v_mfma_f32_16x16x32_bf16 v[28:31], v[146:149], v[194:197], v[28:31]
	v_mfma_f32_16x16x32_bf16 v[24:27], v[154:157], v[194:197], v[24:27]
	s_waitcnt lgkmcnt(0)
	v_mfma_f32_16x16x32_bf16 v[12:15], v[146:149], v[202:205], v[12:15]
	v_mfma_f32_16x16x32_bf16 v[8:11], v[154:157], v[202:205], v[8:11]
	v_mfma_f32_16x16x32_bf16 v[52:55], v[158:161], v[174:177], v[52:55]
	v_mfma_f32_16x16x32_bf16 v[48:51], v[166:169], v[174:177], v[48:51]
	v_mfma_f32_16x16x32_bf16 v[36:39], v[158:161], v[182:185], v[36:39]
	v_mfma_f32_16x16x32_bf16 v[32:35], v[166:169], v[182:185], v[32:35]
	v_mfma_f32_16x16x32_bf16 v[20:23], v[158:161], v[190:193], v[20:23]
	v_mfma_f32_16x16x32_bf16 v[16:19], v[166:169], v[190:193], v[16:19]
	v_mfma_f32_16x16x32_bf16 v[4:7], v[158:161], v[198:201], v[4:7]
	v_mfma_f32_16x16x32_bf16 v[0:3], v[166:169], v[198:201], v[0:3]
	v_mfma_f32_16x16x32_bf16 v[52:55], v[162:165], v[178:181], v[52:55]
	v_mfma_f32_16x16x32_bf16 v[48:51], v[170:173], v[178:181], v[48:51]
	v_mfma_f32_16x16x32_bf16 v[36:39], v[162:165], v[186:189], v[36:39]
	v_mfma_f32_16x16x32_bf16 v[32:35], v[170:173], v[186:189], v[32:35]
	v_mfma_f32_16x16x32_bf16 v[20:23], v[162:165], v[194:197], v[20:23]
	v_mfma_f32_16x16x32_bf16 v[16:19], v[170:173], v[194:197], v[16:19]
	v_mfma_f32_16x16x32_bf16 v[4:7], v[162:165], v[202:205], v[4:7]
	v_mfma_f32_16x16x32_bf16 v[0:3], v[170:173], v[202:205], v[0:3]
	s_barrier
; #define PG8_STAGE(bufoff, soff, voff) do { _Pragma("unroll") for (int _i = 0; _i < 2; ++_i) \
;         __builtin_amdgcn_raw_ptr_buffer_load_lds(rs_##voff, (PG8_LAS unsigned*)(lds + (bufoff) + ldsw + _i * 8192), 16, (int)(voff)[_i], (int)(soff), 0, 0); } while (0)
; #define PG8_LDA(dst, b, h) do { _Pragma("unroll") for (int m = 0; m < 4; ++m) _Pragma("unroll") for (int k = 0; k < 2; ++k) dst[m][k] = *(const PG8_LAS bf16x8*)(lds + PG8_SA(b, h) + aoff + m * 2048 + k * 1024); } while (0)
; #define PG8_LDB(dst, b, h) do { _Pragma("unroll") for (int n = 0; n < 2; ++n) _Pragma("unroll") for (int k = 0; k < 2; ++k) dst[n][k] = *(const PG8_LAS bf16x8*)(lds + PG8_SB(b, h) + boff + n * 2048 + k * 1024); } while (0)
; #define PG8_MMA(ai, bj, At, Bt) do { __builtin_amdgcn_s_setprio(1); _Pragma("unroll") for (int m = 0; m < 4; ++m) _Pragma("unroll") for (int n = 0; n < 2; ++n) _Pragma("unroll") for (int k = 0; k < 2; ++k) \
;         acc[ai][bj][m][n] = __builtin_amdgcn_mfma_f32_16x16x32_bf16(Bt[n][k], At[m][k], acc[ai][bj][m][n], 0, 0, 0); __builtin_amdgcn_s_setprio(0); } while (0)
; #define PG8_WAIT_V(n) asm volatile("s_waitcnt vmcnt(" #n ")" ::: "memory")
; #define PG8_WAIT_L(n) asm volatile("s_waitcnt lgkmcnt(" #n ")" ::: "memory")
; #define PG8_BAR __builtin_amdgcn_s_barrier()
; #define PG8_SCHED __builtin_amdgcn_sched_barrier(0)
; template <class Epi, class Sched, bool ALIGN_EPI = false, bool SP2 = false>
; __device__ __forceinline__ void gemm_phase(PG8_LAS unsigned char* lds, const Gemm g, const Sched& S, const Epi& E, const int wid  ) {
;     ...
;             PG8_LDB(B0, 1, 0); PG8_LDB(B1, 1, 1); PG8_SCHED; PG8_LDA(At, 1, 0); PG8_STAGE(PG8_SA(0, 1), a2 + hstep, voffA);
;             PG8_WAIT_V(8); PG8_WAIT_L(0); PG8_BAR; PG8_MMA(0, 0, At, B0); PG8_MMA(0, 1, At, B1); PG8_BAR; PG8_SCHED;
;             PG8_LDA(At, 1, 1); PG8_STAGE(PG8_SB(1, 0), b3, voffB); PG8_STAGE(PG8_SB(1, 1), b3 + hstep, voffB); PG8_STAGE(PG8_SA(1, 0), a3, voffA);
;             PG8_WAIT_V(8); PG8_WAIT_L(0); PG8_BAR; PG8_MMA(1, 0, At, B0); PG8_MMA(1, 1, At, B1); PG8_BAR; PG8_SCHED;
;     ...
;         if constexpr (ALIGN_EPI) { if (wr == 0) PG8_BAR; }
	ds_read_b128 v[132:135], v143
	ds_read_b128 v[146:149], v143 offset:1024
	ds_read_b128 v[150:153], v143 offset:2048
	ds_read_b128 v[154:157], v143 offset:3072
	ds_read_b128 v[158:161], v144
	ds_read_b128 v[162:165], v144 offset:1024
	ds_read_b128 v[166:169], v144 offset:2048
	ds_read_b128 v[170:173], v144 offset:3072
	s_add_i32 s61, s61, 0x160000
	s_mov_b32 m0, s34
	ds_read_b128 v[174:177], v142 offset:32768
	ds_read_b128 v[178:181], v142 offset:33792
	ds_read_b128 v[182:185], v142 offset:34816
	ds_read_b128 v[186:189], v142 offset:35840
	ds_read_b128 v[190:193], v142 offset:36864
	ds_read_b128 v[194:197], v142 offset:37888
	ds_read_b128 v[198:201], v142 offset:38912
	ds_read_b128 v[202:205], v142 offset:39936
	buffer_load_dwordx4 v136, s[8:11], s61 offen lds
	s_mov_b32 m0, s35
	s_nop 0
	buffer_load_dwordx4 v138, s[8:11], s61 offen lds
	s_waitcnt vmcnt(8)
	s_waitcnt lgkmcnt(0)
	s_barrier
	s_waitcnt lgkmcnt(7)
	v_mfma_f32_16x16x32_bf16 v[124:127], v[132:135], v[174:177], v[124:127]
	v_mfma_f32_16x16x32_bf16 v[120:123], v[150:153], v[174:177], v[120:123]
	s_waitcnt lgkmcnt(5)
	v_mfma_f32_16x16x32_bf16 v[108:111], v[132:135], v[182:185], v[108:111]
	v_mfma_f32_16x16x32_bf16 v[104:107], v[150:153], v[182:185], v[104:107]
	s_waitcnt lgkmcnt(3)
	v_mfma_f32_16x16x32_bf16 v[92:95], v[132:135], v[190:193], v[92:95]
	v_mfma_f32_16x16x32_bf16 v[88:91], v[150:153], v[190:193], v[88:91]
	s_waitcnt lgkmcnt(1)
	v_mfma_f32_16x16x32_bf16 v[76:79], v[132:135], v[198:201], v[76:79]
	v_mfma_f32_16x16x32_bf16 v[72:75], v[150:153], v[198:201], v[72:75]
	v_mfma_f32_16x16x32_bf16 v[124:127], v[146:149], v[178:181], v[124:127]
	v_mfma_f32_16x16x32_bf16 v[120:123], v[154:157], v[178:181], v[120:123]
	v_mfma_f32_16x16x32_bf16 v[108:111], v[146:149], v[186:189], v[108:111]
	v_mfma_f32_16x16x32_bf16 v[104:107], v[154:157], v[186:189], v[104:107]
	v_mfma_f32_16x16x32_bf16 v[92:95], v[146:149], v[194:197], v[92:95]
	v_mfma_f32_16x16x32_bf16 v[88:91], v[154:157], v[194:197], v[88:91]
	s_waitcnt lgkmcnt(0)
	v_mfma_f32_16x16x32_bf16 v[76:79], v[146:149], v[202:205], v[76:79]
	v_mfma_f32_16x16x32_bf16 v[72:75], v[154:157], v[202:205], v[72:75]
	v_mfma_f32_16x16x32_bf16 v[116:119], v[158:161], v[174:177], v[116:119]
	v_mfma_f32_16x16x32_bf16 v[112:115], v[166:169], v[174:177], v[112:115]
	v_mfma_f32_16x16x32_bf16 v[100:103], v[158:161], v[182:185], v[100:103]
	v_mfma_f32_16x16x32_bf16 v[96:99], v[166:169], v[182:185], v[96:99]
	v_mfma_f32_16x16x32_bf16 v[84:87], v[158:161], v[190:193], v[84:87]
	v_mfma_f32_16x16x32_bf16 v[80:83], v[166:169], v[190:193], v[80:83]
	v_mfma_f32_16x16x32_bf16 v[68:71], v[158:161], v[198:201], v[68:71]
	v_mfma_f32_16x16x32_bf16 v[64:67], v[166:169], v[198:201], v[64:67]
	v_mfma_f32_16x16x32_bf16 v[116:119], v[162:165], v[178:181], v[116:119]
	v_mfma_f32_16x16x32_bf16 v[112:115], v[170:173], v[178:181], v[112:115]
	v_mfma_f32_16x16x32_bf16 v[100:103], v[162:165], v[186:189], v[100:103]
	v_mfma_f32_16x16x32_bf16 v[96:99], v[170:173], v[186:189], v[96:99]
	v_mfma_f32_16x16x32_bf16 v[84:87], v[162:165], v[194:197], v[84:87]
	v_mfma_f32_16x16x32_bf16 v[80:83], v[170:173], v[194:197], v[80:83]
	v_mfma_f32_16x16x32_bf16 v[68:71], v[162:165], v[202:205], v[68:71]
	v_mfma_f32_16x16x32_bf16 v[64:67], v[170:173], v[202:205], v[64:67]
	s_barrier
	s_mov_b32 m0, s36
	s_or_b32 s61, s60, 0x80
	ds_read_b128 v[174:177], v142 offset:49152
	ds_read_b128 v[178:181], v142 offset:50176
	ds_read_b128 v[182:185], v142 offset:51200
	ds_read_b128 v[186:189], v142 offset:52224
	ds_read_b128 v[190:193], v142 offset:53248
	ds_read_b128 v[194:197], v142 offset:54272
	ds_read_b128 v[198:201], v142 offset:55296
	ds_read_b128 v[202:205], v142 offset:56320
	buffer_load_dwordx4 v137, s[12:15], s61 offen lds
	s_mov_b32 m0, s37
	s_add_i32 s60, s60, 0x160080
	buffer_load_dwordx4 v139, s[12:15], s61 offen lds
	s_mov_b32 m0, s40
	s_nop 0
	buffer_load_dwordx4 v137, s[12:15], s60 offen lds
	s_mov_b32 m0, s41
	s_nop 0
	buffer_load_dwordx4 v139, s[12:15], s60 offen lds
	s_mov_b32 m0, s38
	s_nop 0
	buffer_load_dwordx4 v136, s[8:11], s59 offen lds
	s_mov_b32 m0, s39
	s_nop 0
	buffer_load_dwordx4 v138, s[8:11], s59 offen lds
	s_waitcnt vmcnt(8)
	s_waitcnt lgkmcnt(0)
	s_barrier
	s_waitcnt lgkmcnt(7)
	v_mfma_f32_16x16x32_bf16 v[60:63], v[132:135], v[174:177], v[60:63]
	v_mfma_f32_16x16x32_bf16 v[56:59], v[150:153], v[174:177], v[56:59]
	s_waitcnt lgkmcnt(5)
	v_mfma_f32_16x16x32_bf16 v[44:47], v[132:135], v[182:185], v[44:47]
	v_mfma_f32_16x16x32_bf16 v[40:43], v[150:153], v[182:185], v[40:43]
	s_waitcnt lgkmcnt(3)
	v_mfma_f32_16x16x32_bf16 v[28:31], v[132:135], v[190:193], v[28:31]
	v_mfma_f32_16x16x32_bf16 v[24:27], v[150:153], v[190:193], v[24:27]
	s_waitcnt lgkmcnt(1)
	v_mfma_f32_16x16x32_bf16 v[12:15], v[132:135], v[198:201], v[12:15]
	v_mfma_f32_16x16x32_bf16 v[8:11], v[150:153], v[198:201], v[8:11]
	v_mfma_f32_16x16x32_bf16 v[60:63], v[146:149], v[178:181], v[60:63]
	v_mfma_f32_16x16x32_bf16 v[56:59], v[154:157], v[178:181], v[56:59]
	v_mfma_f32_16x16x32_bf16 v[44:47], v[146:149], v[186:189], v[44:47]
	v_mfma_f32_16x16x32_bf16 v[40:43], v[154:157], v[186:189], v[40:43]
	v_mfma_f32_16x16x32_bf16 v[28:31], v[146:149], v[194:197], v[28:31]
	v_mfma_f32_16x16x32_bf16 v[24:27], v[154:157], v[194:197], v[24:27]
	s_waitcnt lgkmcnt(0)
	v_mfma_f32_16x16x32_bf16 v[12:15], v[146:149], v[202:205], v[12:15]
	v_mfma_f32_16x16x32_bf16 v[8:11], v[154:157], v[202:205], v[8:11]
	v_mfma_f32_16x16x32_bf16 v[52:55], v[158:161], v[174:177], v[52:55]
	v_mfma_f32_16x16x32_bf16 v[48:51], v[166:169], v[174:177], v[48:51]
	v_mfma_f32_16x16x32_bf16 v[36:39], v[158:161], v[182:185], v[36:39]
	v_mfma_f32_16x16x32_bf16 v[32:35], v[166:169], v[182:185], v[32:35]
	v_mfma_f32_16x16x32_bf16 v[20:23], v[158:161], v[190:193], v[20:23]
	v_mfma_f32_16x16x32_bf16 v[16:19], v[166:169], v[190:193], v[16:19]
	v_mfma_f32_16x16x32_bf16 v[4:7], v[158:161], v[198:201], v[4:7]
	v_mfma_f32_16x16x32_bf16 v[0:3], v[166:169], v[198:201], v[0:3]
	v_mfma_f32_16x16x32_bf16 v[52:55], v[162:165], v[178:181], v[52:55]
	v_mfma_f32_16x16x32_bf16 v[48:51], v[170:173], v[178:181], v[48:51]
	v_mfma_f32_16x16x32_bf16 v[36:39], v[162:165], v[186:189], v[36:39]
	v_mfma_f32_16x16x32_bf16 v[32:35], v[170:173], v[186:189], v[32:35]
	v_mfma_f32_16x16x32_bf16 v[20:23], v[162:165], v[194:197], v[20:23]
	v_mfma_f32_16x16x32_bf16 v[16:19], v[170:173], v[194:197], v[16:19]
	v_mfma_f32_16x16x32_bf16 v[4:7], v[162:165], v[202:205], v[4:7]
	v_mfma_f32_16x16x32_bf16 v[0:3], v[170:173], v[202:205], v[0:3]
	s_barrier
	s_add_i32 s58, s58, 2
	s_addk_i32 s16, 0x100
	s_addk_i32 s55, 0x100
	s_cmpk_gt_u32 s58, 0x55
	s_cbranch_scc0 .LBB0_2380
	s_and_b64 vcc, exec, s[24:25]
	s_cbranch_vccz .LBB0_2383
	s_barrier

; #define PG8_STAGE(bufoff, soff, voff) do { _Pragma("unroll") for (int _i = 0; _i < 2; ++_i) \
;         __builtin_amdgcn_raw_ptr_buffer_load_lds(rs_##voff, (PG8_LAS unsigned*)(lds + (bufoff) + ldsw + _i * 8192), 16, (int)(voff)[_i], (int)(soff), 0, 0); } while (0)
; #define PG8_LDA(dst, b, h) do { _Pragma("unroll") for (int m = 0; m < 4; ++m) _Pragma("unroll") for (int k = 0; k < 2; ++k) dst[m][k] = *(const PG8_LAS bf16x8*)(lds + PG8_SA(b, h) + aoff + m * 2048 + k * 1024); } while (0)
; #define PG8_LDB(dst, b, h) do { _Pragma("unroll") for (int n = 0; n < 2; ++n) _Pragma("unroll") for (int k = 0; k < 2; ++k) dst[n][k] = *(const PG8_LAS bf16x8*)(lds + PG8_SB(b, h) + boff + n * 2048 + k * 1024); } while (0)
; #define PG8_MMA(ai, bj, At, Bt) do { __builtin_amdgcn_s_setprio(1); _Pragma("unroll") for (int m = 0; m < 4; ++m) _Pragma("unroll") for (int n = 0; n < 2; ++n) _Pragma("unroll") for (int k = 0; k < 2; ++k) \
;         acc[ai][bj][m][n] = __builtin_amdgcn_mfma_f32_16x16x32_bf16(Bt[n][k], At[m][k], acc[ai][bj][m][n], 0, 0, 0); __builtin_amdgcn_s_setprio(0); } while (0)
; #define PG8_WAIT_V(n) asm volatile("s_waitcnt vmcnt(" #n ")" ::: "memory")
; #define PG8_WAIT_L(n) asm volatile("s_waitcnt lgkmcnt(" #n ")" ::: "memory")
; #define PG8_BAR __builtin_amdgcn_s_barrier()
; #define PG8_SCHED __builtin_amdgcn_sched_barrier(0)
; template <class Epi, class Sched, bool ALIGN_EPI = false, bool SP2 = false>
; __device__ __forceinline__ void gemm_phase(PG8_LAS unsigned char* lds, const Gemm g, const Sched& S, const Epi& E, const int wid  ) {
;     ...
;             PG8_LDB(B0, 0, 0); PG8_LDB(B1, 0, 1); PG8_SCHED; PG8_LDA(At, 0, 0); PG8_STAGE(PG8_SA(1, 1), a1 + hstep, voffA);
;             PG8_WAIT_V(8); PG8_WAIT_L(0); PG8_BAR; PG8_MMA(0, 0, At, B0); PG8_MMA(0, 1, At, B1); PG8_BAR; PG8_SCHED;
;             PG8_LDA(At, 0, 1); PG8_STAGE(PG8_SB(0, 0), b2, voffB); PG8_STAGE(PG8_SB(0, 1), b2 + hstep, voffB); PG8_STAGE(PG8_SA(0, 0), a2, voffA);
;             PG8_WAIT_V(8); PG8_WAIT_L(0); PG8_BAR; PG8_MMA(1, 0, At, B0); PG8_MMA(1, 1, At, B1); PG8_BAR; PG8_SCHED;
.Lprio_2575:
.LBB0_2575:
	ds_read_b128 v[132:135], v144
	ds_read_b128 v[150:153], v144 offset:1024
	ds_read_b128 v[154:157], v144 offset:2048
	ds_read_b128 v[158:161], v144 offset:3072
	ds_read_b128 v[162:165], v145
	ds_read_b128 v[166:169], v145 offset:1024
	ds_read_b128 v[170:173], v145 offset:2048
	ds_read_b128 v[174:177], v145 offset:3072
	s_add_i32 s14, s65, 0xfff80080
	s_cmp_eq_u32 s67, 28
	s_cselect_b32 s70, s63, s14
	s_cselect_b32 s69, s64, s66
	s_or_b32 s68, s70, 0x80
	s_mov_b32 m0, s47
	ds_read_b128 v[178:181], v146
	ds_read_b128 v[182:185], v146 offset:1024
	ds_read_b128 v[186:189], v146 offset:2048
	ds_read_b128 v[190:193], v146 offset:3072
	ds_read_b128 v[194:197], v146 offset:4096
	ds_read_b128 v[198:201], v146 offset:5120
	ds_read_b128 v[202:205], v146 offset:6144
	ds_read_b128 v[206:209], v146 offset:7168
	buffer_load_dwordx4 v138, s[8:11], s65 offen lds
	s_mov_b32 m0, s48
	s_nop 0
	buffer_load_dwordx4 v140, s[8:11], s65 offen lds
	s_waitcnt vmcnt(8)
	s_waitcnt lgkmcnt(0)
	s_barrier
	s_waitcnt lgkmcnt(7)
	v_mfma_f32_16x16x32_bf16 v[124:127], v[132:135], v[178:181], v[124:127]
	v_mfma_f32_16x16x32_bf16 v[120:123], v[154:157], v[178:181], v[120:123]
	s_waitcnt lgkmcnt(5)
	v_mfma_f32_16x16x32_bf16 v[112:115], v[132:135], v[186:189], v[112:115]
	v_mfma_f32_16x16x32_bf16 v[104:107], v[154:157], v[186:189], v[104:107]
	s_waitcnt lgkmcnt(3)
	v_mfma_f32_16x16x32_bf16 v[96:99], v[132:135], v[194:197], v[96:99]
	v_mfma_f32_16x16x32_bf16 v[88:91], v[154:157], v[194:197], v[88:91]
	s_waitcnt lgkmcnt(1)
	v_mfma_f32_16x16x32_bf16 v[80:83], v[132:135], v[202:205], v[80:83]
	v_mfma_f32_16x16x32_bf16 v[72:75], v[154:157], v[202:205], v[72:75]
	v_mfma_f32_16x16x32_bf16 v[124:127], v[150:153], v[182:185], v[124:127]
	v_mfma_f32_16x16x32_bf16 v[120:123], v[158:161], v[182:185], v[120:123]
	v_mfma_f32_16x16x32_bf16 v[112:115], v[150:153], v[190:193], v[112:115]
	v_mfma_f32_16x16x32_bf16 v[104:107], v[158:161], v[190:193], v[104:107]
	v_mfma_f32_16x16x32_bf16 v[96:99], v[150:153], v[198:201], v[96:99]
	v_mfma_f32_16x16x32_bf16 v[88:91], v[158:161], v[198:201], v[88:91]
	s_waitcnt lgkmcnt(0)
	v_mfma_f32_16x16x32_bf16 v[80:83], v[150:153], v[206:209], v[80:83]
	v_mfma_f32_16x16x32_bf16 v[72:75], v[158:161], v[206:209], v[72:75]
	v_mfma_f32_16x16x32_bf16 v[116:119], v[162:165], v[178:181], v[116:119]
	v_mfma_f32_16x16x32_bf16 v[108:111], v[170:173], v[178:181], v[108:111]
	v_mfma_f32_16x16x32_bf16 v[100:103], v[162:165], v[186:189], v[100:103]
	v_mfma_f32_16x16x32_bf16 v[92:95], v[170:173], v[186:189], v[92:95]
	v_mfma_f32_16x16x32_bf16 v[84:87], v[162:165], v[194:197], v[84:87]
	v_mfma_f32_16x16x32_bf16 v[76:79], v[170:173], v[194:197], v[76:79]
	v_mfma_f32_16x16x32_bf16 v[68:71], v[162:165], v[202:205], v[68:71]
	v_mfma_f32_16x16x32_bf16 v[64:67], v[170:173], v[202:205], v[64:67]
	v_mfma_f32_16x16x32_bf16 v[116:119], v[166:169], v[182:185], v[116:119]
	v_mfma_f32_16x16x32_bf16 v[108:111], v[174:177], v[182:185], v[108:111]
	v_mfma_f32_16x16x32_bf16 v[100:103], v[166:169], v[190:193], v[100:103]
	v_mfma_f32_16x16x32_bf16 v[92:95], v[174:177], v[190:193], v[92:95]
	v_mfma_f32_16x16x32_bf16 v[84:87], v[166:169], v[198:201], v[84:87]
	v_mfma_f32_16x16x32_bf16 v[76:79], v[174:177], v[198:201], v[76:79]
	v_mfma_f32_16x16x32_bf16 v[68:71], v[166:169], v[206:209], v[68:71]
	v_mfma_f32_16x16x32_bf16 v[64:67], v[174:177], v[206:209], v[64:67]
	s_barrier
	s_mov_b32 m0, s30
	s_mov_b32 s14, s10
	s_mov_b32 s15, s11
	ds_read_b128 v[178:181], v146 offset:16384
	ds_read_b128 v[182:185], v146 offset:17408
	ds_read_b128 v[186:189], v146 offset:18432
	ds_read_b128 v[190:193], v146 offset:19456
	ds_read_b128 v[194:197], v146 offset:20480
	ds_read_b128 v[198:201], v146 offset:21504
	ds_read_b128 v[202:205], v146 offset:22528
	ds_read_b128 v[206:209], v146 offset:23552
	buffer_load_dwordx4 v139, s[12:15], s69 offen lds
	s_mov_b32 m0, s31
	s_add_i32 s71, s69, 0x80000
	buffer_load_dwordx4 v141, s[12:15], s69 offen lds
	s_mov_b32 m0, s33
	s_nop 0
	buffer_load_dwordx4 v139, s[12:15], s71 offen lds
	s_mov_b32 m0, s34
	s_nop 0
	buffer_load_dwordx4 v141, s[12:15], s71 offen lds
	s_mov_b32 m0, s29
	s_nop 0
	buffer_load_dwordx4 v138, s[8:11], s70 offen lds
	s_mov_b32 m0, s35
	s_nop 0
	buffer_load_dwordx4 v140, s[8:11], s70 offen lds
	s_waitcnt vmcnt(8)
	s_waitcnt lgkmcnt(0)
	s_barrier
	s_waitcnt lgkmcnt(7)
	v_mfma_f32_16x16x32_bf16 v[60:63], v[132:135], v[178:181], v[60:63]
	v_mfma_f32_16x16x32_bf16 v[56:59], v[154:157], v[178:181], v[56:59]
	s_waitcnt lgkmcnt(5)
	v_mfma_f32_16x16x32_bf16 v[48:51], v[132:135], v[186:189], v[48:51]
	v_mfma_f32_16x16x32_bf16 v[40:43], v[154:157], v[186:189], v[40:43]
	s_waitcnt lgkmcnt(3)
	v_mfma_f32_16x16x32_bf16 v[32:35], v[132:135], v[194:197], v[32:35]
	v_mfma_f32_16x16x32_bf16 v[24:27], v[154:157], v[194:197], v[24:27]
	s_waitcnt lgkmcnt(1)
	v_mfma_f32_16x16x32_bf16 v[16:19], v[132:135], v[202:205], v[16:19]
	v_mfma_f32_16x16x32_bf16 v[8:11], v[154:157], v[202:205], v[8:11]
	v_mfma_f32_16x16x32_bf16 v[60:63], v[150:153], v[182:185], v[60:63]
	v_mfma_f32_16x16x32_bf16 v[56:59], v[158:161], v[182:185], v[56:59]
	v_mfma_f32_16x16x32_bf16 v[48:51], v[150:153], v[190:193], v[48:51]
	v_mfma_f32_16x16x32_bf16 v[40:43], v[158:161], v[190:193], v[40:43]
	v_mfma_f32_16x16x32_bf16 v[32:35], v[150:153], v[198:201], v[32:35]
	v_mfma_f32_16x16x32_bf16 v[24:27], v[158:161], v[198:201], v[24:27]
	s_waitcnt lgkmcnt(0)
	v_mfma_f32_16x16x32_bf16 v[16:19], v[150:153], v[206:209], v[16:19]
	v_mfma_f32_16x16x32_bf16 v[8:11], v[158:161], v[206:209], v[8:11]
	v_mfma_f32_16x16x32_bf16 v[52:55], v[162:165], v[178:181], v[52:55]
	v_mfma_f32_16x16x32_bf16 v[44:47], v[170:173], v[178:181], v[44:47]
	v_mfma_f32_16x16x32_bf16 v[36:39], v[162:165], v[186:189], v[36:39]
	v_mfma_f32_16x16x32_bf16 v[28:31], v[170:173], v[186:189], v[28:31]
	v_mfma_f32_16x16x32_bf16 v[20:23], v[162:165], v[194:197], v[20:23]
	v_mfma_f32_16x16x32_bf16 v[12:15], v[170:173], v[194:197], v[12:15]
	v_mfma_f32_16x16x32_bf16 v[4:7], v[162:165], v[202:205], v[4:7]
	v_mfma_f32_16x16x32_bf16 v[0:3], v[170:173], v[202:205], v[0:3]
	v_mfma_f32_16x16x32_bf16 v[52:55], v[166:169], v[182:185], v[52:55]
	v_mfma_f32_16x16x32_bf16 v[44:47], v[174:177], v[182:185], v[44:47]
	v_mfma_f32_16x16x32_bf16 v[36:39], v[166:169], v[190:193], v[36:39]
	v_mfma_f32_16x16x32_bf16 v[28:31], v[174:177], v[190:193], v[28:31]
	v_mfma_f32_16x16x32_bf16 v[20:23], v[166:169], v[198:201], v[20:23]
	v_mfma_f32_16x16x32_bf16 v[12:15], v[174:177], v[198:201], v[12:15]
	v_mfma_f32_16x16x32_bf16 v[4:7], v[166:169], v[206:209], v[4:7]
	v_mfma_f32_16x16x32_bf16 v[0:3], v[174:177], v[206:209], v[0:3]
	s_barrier
; #define PG8_STAGE(bufoff, soff, voff) do { _Pragma("unroll") for (int _i = 0; _i < 2; ++_i) \
;         __builtin_amdgcn_raw_ptr_buffer_load_lds(rs_##voff, (PG8_LAS unsigned*)(lds + (bufoff) + ldsw + _i * 8192), 16, (int)(voff)[_i], (int)(soff), 0, 0); } while (0)
; #define PG8_LDA(dst, b, h) do { _Pragma("unroll") for (int m = 0; m < 4; ++m) _Pragma("unroll") for (int k = 0; k < 2; ++k) dst[m][k] = *(const PG8_LAS bf16x8*)(lds + PG8_SA(b, h) + aoff + m * 2048 + k * 1024); } while (0)
; #define PG8_LDB(dst, b, h) do { _Pragma("unroll") for (int n = 0; n < 2; ++n) _Pragma("unroll") for (int k = 0; k < 2; ++k) dst[n][k] = *(const PG8_LAS bf16x8*)(lds + PG8_SB(b, h) + boff + n * 2048 + k * 1024); } while (0)
; #define PG8_MMA(ai, bj, At, Bt) do { __builtin_amdgcn_s_setprio(1); _Pragma("unroll") for (int m = 0; m < 4; ++m) _Pragma("unroll") for (int n = 0; n < 2; ++n) _Pragma("unroll") for (int k = 0; k < 2; ++k) \
;         acc[ai][bj][m][n] = __builtin_amdgcn_mfma_f32_16x16x32_bf16(Bt[n][k], At[m][k], acc[ai][bj][m][n], 0, 0, 0); __builtin_amdgcn_s_setprio(0); } while (0)
; #define PG8_WAIT_V(n) asm volatile("s_waitcnt vmcnt(" #n ")" ::: "memory")
; #define PG8_WAIT_L(n) asm volatile("s_waitcnt lgkmcnt(" #n ")" ::: "memory")
; #define PG8_BAR __builtin_amdgcn_s_barrier()
; #define PG8_SCHED __builtin_amdgcn_sched_barrier(0)
; template <class Epi, class Sched, bool ALIGN_EPI = false, bool SP2 = false>
; __device__ __forceinline__ void gemm_phase(PG8_LAS unsigned char* lds, const Gemm g, const Sched& S, const Epi& E, const int wid  ) {
;     ...
;             PG8_LDB(B0, 1, 0); PG8_LDB(B1, 1, 1); PG8_SCHED; PG8_LDA(At, 1, 0); PG8_STAGE(PG8_SA(0, 1), a2 + hstep, voffA);
;             PG8_WAIT_V(8); PG8_WAIT_L(0); PG8_BAR; PG8_MMA(0, 0, At, B0); PG8_MMA(0, 1, At, B1); PG8_BAR; PG8_SCHED;
;             PG8_LDA(At, 1, 1); PG8_STAGE(PG8_SB(1, 0), b3, voffB); PG8_STAGE(PG8_SB(1, 1), b3 + hstep, voffB); PG8_STAGE(PG8_SA(1, 0), a3, voffA);
;             PG8_WAIT_V(8); PG8_WAIT_L(0); PG8_BAR; PG8_MMA(1, 0, At, B0); PG8_MMA(1, 1, At, B1); PG8_BAR; PG8_SCHED;
;     ...
;         if constexpr (ALIGN_EPI) { if (wr == 0) PG8_BAR; }
	ds_read_b128 v[132:135], v147
	ds_read_b128 v[150:153], v147 offset:1024
	ds_read_b128 v[154:157], v147 offset:2048
	ds_read_b128 v[158:161], v147 offset:3072
	ds_read_b128 v[162:165], v148
	ds_read_b128 v[166:169], v148 offset:1024
	ds_read_b128 v[170:173], v148 offset:2048
	ds_read_b128 v[174:177], v148 offset:3072
	s_add_i32 s70, s70, 0x80000
	s_mov_b32 m0, s36
	ds_read_b128 v[178:181], v146 offset:32768
	ds_read_b128 v[182:185], v146 offset:33792
	ds_read_b128 v[186:189], v146 offset:34816
	ds_read_b128 v[190:193], v146 offset:35840
	ds_read_b128 v[194:197], v146 offset:36864
	ds_read_b128 v[198:201], v146 offset:37888
	ds_read_b128 v[202:205], v146 offset:38912
	ds_read_b128 v[206:209], v146 offset:39936
	buffer_load_dwordx4 v138, s[8:11], s70 offen lds
	s_mov_b32 m0, s37
	s_nop 0
	buffer_load_dwordx4 v140, s[8:11], s70 offen lds
	s_waitcnt vmcnt(8)
	s_waitcnt lgkmcnt(0)
	s_barrier
	s_waitcnt lgkmcnt(7)
	v_mfma_f32_16x16x32_bf16 v[124:127], v[132:135], v[178:181], v[124:127]
	v_mfma_f32_16x16x32_bf16 v[120:123], v[154:157], v[178:181], v[120:123]
	s_waitcnt lgkmcnt(5)
	v_mfma_f32_16x16x32_bf16 v[112:115], v[132:135], v[186:189], v[112:115]
	v_mfma_f32_16x16x32_bf16 v[104:107], v[154:157], v[186:189], v[104:107]
	s_waitcnt lgkmcnt(3)
	v_mfma_f32_16x16x32_bf16 v[96:99], v[132:135], v[194:197], v[96:99]
	v_mfma_f32_16x16x32_bf16 v[88:91], v[154:157], v[194:197], v[88:91]
	s_waitcnt lgkmcnt(1)
	v_mfma_f32_16x16x32_bf16 v[80:83], v[132:135], v[202:205], v[80:83]
	v_mfma_f32_16x16x32_bf16 v[72:75], v[154:157], v[202:205], v[72:75]
	v_mfma_f32_16x16x32_bf16 v[124:127], v[150:153], v[182:185], v[124:127]
	v_mfma_f32_16x16x32_bf16 v[120:123], v[158:161], v[182:185], v[120:123]
	v_mfma_f32_16x16x32_bf16 v[112:115], v[150:153], v[190:193], v[112:115]
	v_mfma_f32_16x16x32_bf16 v[104:107], v[158:161], v[190:193], v[104:107]
	v_mfma_f32_16x16x32_bf16 v[96:99], v[150:153], v[198:201], v[96:99]
	v_mfma_f32_16x16x32_bf16 v[88:91], v[158:161], v[198:201], v[88:91]
	s_waitcnt lgkmcnt(0)
	v_mfma_f32_16x16x32_bf16 v[80:83], v[150:153], v[206:209], v[80:83]
	v_mfma_f32_16x16x32_bf16 v[72:75], v[158:161], v[206:209], v[72:75]
	v_mfma_f32_16x16x32_bf16 v[116:119], v[162:165], v[178:181], v[116:119]
	v_mfma_f32_16x16x32_bf16 v[108:111], v[170:173], v[178:181], v[108:111]
	v_mfma_f32_16x16x32_bf16 v[100:103], v[162:165], v[186:189], v[100:103]
	v_mfma_f32_16x16x32_bf16 v[92:95], v[170:173], v[186:189], v[92:95]
	v_mfma_f32_16x16x32_bf16 v[84:87], v[162:165], v[194:197], v[84:87]
	v_mfma_f32_16x16x32_bf16 v[76:79], v[170:173], v[194:197], v[76:79]
	v_mfma_f32_16x16x32_bf16 v[68:71], v[162:165], v[202:205], v[68:71]
	v_mfma_f32_16x16x32_bf16 v[64:67], v[170:173], v[202:205], v[64:67]
	v_mfma_f32_16x16x32_bf16 v[116:119], v[166:169], v[182:185], v[116:119]
	v_mfma_f32_16x16x32_bf16 v[108:111], v[174:177], v[182:185], v[108:111]
	v_mfma_f32_16x16x32_bf16 v[100:103], v[166:169], v[190:193], v[100:103]
	v_mfma_f32_16x16x32_bf16 v[92:95], v[174:177], v[190:193], v[92:95]
	v_mfma_f32_16x16x32_bf16 v[84:87], v[166:169], v[198:201], v[84:87]
	v_mfma_f32_16x16x32_bf16 v[76:79], v[174:177], v[198:201], v[76:79]
	v_mfma_f32_16x16x32_bf16 v[68:71], v[166:169], v[206:209], v[68:71]
	v_mfma_f32_16x16x32_bf16 v[64:67], v[174:177], v[206:209], v[64:67]
	s_barrier
	s_mov_b32 m0, s39
	s_or_b32 s70, s69, 0x80
	ds_read_b128 v[178:181], v146 offset:49152
	ds_read_b128 v[182:185], v146 offset:50176
	ds_read_b128 v[186:189], v146 offset:51200
	ds_read_b128 v[190:193], v146 offset:52224
	ds_read_b128 v[194:197], v146 offset:53248
	ds_read_b128 v[198:201], v146 offset:54272
	ds_read_b128 v[202:205], v146 offset:55296
	ds_read_b128 v[206:209], v146 offset:56320
	buffer_load_dwordx4 v139, s[12:15], s70 offen lds
	s_mov_b32 m0, s40
	s_add_i32 s69, s69, 0x80080
	buffer_load_dwordx4 v141, s[12:15], s70 offen lds
	s_mov_b32 m0, s43
	s_nop 0
	buffer_load_dwordx4 v139, s[12:15], s69 offen lds
	s_mov_b32 m0, s44
	s_nop 0
	buffer_load_dwordx4 v141, s[12:15], s69 offen lds
	s_mov_b32 m0, s41
	s_nop 0
	buffer_load_dwordx4 v138, s[8:11], s68 offen lds
	s_mov_b32 m0, s42
	s_nop 0
	buffer_load_dwordx4 v140, s[8:11], s68 offen lds
	s_waitcnt vmcnt(8)
	s_waitcnt lgkmcnt(0)
	s_barrier
	s_waitcnt lgkmcnt(7)
	v_mfma_f32_16x16x32_bf16 v[60:63], v[132:135], v[178:181], v[60:63]
	v_mfma_f32_16x16x32_bf16 v[56:59], v[154:157], v[178:181], v[56:59]
	s_waitcnt lgkmcnt(5)
	v_mfma_f32_16x16x32_bf16 v[48:51], v[132:135], v[186:189], v[48:51]
	v_mfma_f32_16x16x32_bf16 v[40:43], v[154:157], v[186:189], v[40:43]
	s_waitcnt lgkmcnt(3)
	v_mfma_f32_16x16x32_bf16 v[32:35], v[132:135], v[194:197], v[32:35]
	v_mfma_f32_16x16x32_bf16 v[24:27], v[154:157], v[194:197], v[24:27]
	s_waitcnt lgkmcnt(1)
	v_mfma_f32_16x16x32_bf16 v[16:19], v[132:135], v[202:205], v[16:19]
	v_mfma_f32_16x16x32_bf16 v[8:11], v[154:157], v[202:205], v[8:11]
	v_mfma_f32_16x16x32_bf16 v[60:63], v[150:153], v[182:185], v[60:63]
	v_mfma_f32_16x16x32_bf16 v[56:59], v[158:161], v[182:185], v[56:59]
	v_mfma_f32_16x16x32_bf16 v[48:51], v[150:153], v[190:193], v[48:51]
	v_mfma_f32_16x16x32_bf16 v[40:43], v[158:161], v[190:193], v[40:43]
	v_mfma_f32_16x16x32_bf16 v[32:35], v[150:153], v[198:201], v[32:35]
	v_mfma_f32_16x16x32_bf16 v[24:27], v[158:161], v[198:201], v[24:27]
	s_waitcnt lgkmcnt(0)
	v_mfma_f32_16x16x32_bf16 v[16:19], v[150:153], v[206:209], v[16:19]
	v_mfma_f32_16x16x32_bf16 v[8:11], v[158:161], v[206:209], v[8:11]
	v_mfma_f32_16x16x32_bf16 v[52:55], v[162:165], v[178:181], v[52:55]
	v_mfma_f32_16x16x32_bf16 v[44:47], v[170:173], v[178:181], v[44:47]
	v_mfma_f32_16x16x32_bf16 v[36:39], v[162:165], v[186:189], v[36:39]
	v_mfma_f32_16x16x32_bf16 v[28:31], v[170:173], v[186:189], v[28:31]
	v_mfma_f32_16x16x32_bf16 v[20:23], v[162:165], v[194:197], v[20:23]
	v_mfma_f32_16x16x32_bf16 v[12:15], v[170:173], v[194:197], v[12:15]
	v_mfma_f32_16x16x32_bf16 v[4:7], v[162:165], v[202:205], v[4:7]
	v_mfma_f32_16x16x32_bf16 v[0:3], v[170:173], v[202:205], v[0:3]
	v_mfma_f32_16x16x32_bf16 v[52:55], v[166:169], v[182:185], v[52:55]
	v_mfma_f32_16x16x32_bf16 v[44:47], v[174:177], v[182:185], v[44:47]
	v_mfma_f32_16x16x32_bf16 v[36:39], v[166:169], v[190:193], v[36:39]
	v_mfma_f32_16x16x32_bf16 v[28:31], v[174:177], v[190:193], v[28:31]
	v_mfma_f32_16x16x32_bf16 v[20:23], v[166:169], v[198:201], v[20:23]
	v_mfma_f32_16x16x32_bf16 v[12:15], v[174:177], v[198:201], v[12:15]
	v_mfma_f32_16x16x32_bf16 v[4:7], v[166:169], v[206:209], v[4:7]
	v_mfma_f32_16x16x32_bf16 v[0:3], v[174:177], v[206:209], v[0:3]
	s_barrier
	s_add_i32 s67, s67, 2
	s_addk_i32 s65, 0x100
	s_addk_i32 s66, 0x100
	s_cmp_gt_u32 s67, 29
	s_cbranch_scc0 .LBB0_2575
	s_and_b64 vcc, exec, s[18:19]
	s_cbranch_vccz .LBB0_2578
	s_barrier

; __device__ __forceinline__ unsigned xb_ld(unsigned* p)              { return __hip_atomic_load(p, __ATOMIC_RELAXED, __HIP_MEMORY_SCOPE_AGENT); }
; __device__ __forceinline__ void xcd_barrier_complete(unsigned* bar, unsigned x, unsigned& nloc, unsigned& nx) {
;     const unsigned G = gridDim.x * gridDim.y * gridDim.z;
;     unsigned sum, cnt, mine, sp = 0u;
;     for (;;) {
;         sum = 0u; cnt = 0u; mine = 0u;
; #pragma unroll
;         for (unsigned j = 0; j < 16; ++j) { const unsigned c = xb_ld(&bar[XB_XCNT(j)]); sum += c; cnt += (c > 0u) ? 1u : 0u; mine = (j == x) ? c : mine; }
; __device__ __forceinline__ void xcd_barrier(const XcdBarrier& b) {
;     asm volatile("s_waitcnt vmcnt(0)" ::: "memory");
;     __syncthreads();
;     if (threadIdx.x == 0) {
;         unsigned* bar = b.bar;
;         __builtin_amdgcn_s_waitcnt(0);
;         unsigned nloc = b.st[0], nx = b.st[1];
;         if (nloc == 0u) { xcd_barrier_complete(bar, b.x, nloc, nx); b.st[0] = nloc; b.st[1] = nx; }
.LBB0_2586:
	s_cmp_lt_i32 s57, 24
	s_cbranch_scc1 .LBB0_2640
	s_setprio 0
	s_add_i32 s0, 0, 0x20520
	v_mov_b32_e32 v0, s0
	ds_read_b64 v[0:1], v0
	s_getreg_b32 s3, hwreg(HW_REG_XCC_ID, 0, 4)
	s_waitcnt vmcnt(0)
	s_waitcnt vmcnt(16) lgkmcnt(0)
	s_barrier
	v_readfirstlane_b32 s4, v0
	v_readfirstlane_b32 s5, v1
	s_mov_b64 s[0:1], exec
	v_readlane_b32 s6, v246, 2
	v_readlane_b32 s7, v246, 3
	s_and_b64 s[6:7], s[0:1], s[6:7]
	s_mov_b64 exec, s[6:7]
	s_cbranch_execz .LBB0_2639
	s_add_i32 s6, 0, 0x20160
	v_mov_b32_e32 v0, s6
	s_waitcnt vmcnt(0) expcnt(0) lgkmcnt(0)
	ds_read_b32 v2, v0
	s_add_i32 s6, 0, 0x20164
	v_mov_b32_e32 v0, s6
	ds_read_b32 v0, v0
	s_and_b32 s3, s3, 15
	s_waitcnt lgkmcnt(1)
	v_cmp_ne_u32_e32 vcc, 0, v2
	s_cbranch_vccnz .LBB0_2603
	v_readlane_b32 s6, v246, 0
	v_readlane_b32 s7, v246, 1
	s_load_dwordx2 s[10:11], s[6:7], 0x4
	s_add_u32 s6, s4, 0x4200
	s_addc_u32 s7, s5, 0
	s_add_u32 s8, s4, 0x4400
	s_addc_u32 s9, s5, 0
	s_waitcnt lgkmcnt(0)
	s_mul_i32 s33, s10, s52
	s_add_u32 s10, s4, 0x4500
	s_mul_i32 s33, s33, s11
	s_addc_u32 s11, s5, 0
	s_add_u32 s12, s4, 0x4600
	s_addc_u32 s13, s5, 0
	s_add_u32 s14, s4, 0x4700
	s_addc_u32 s15, s5, 0
	s_add_u32 s16, s4, 0x4800
	s_addc_u32 s17, s5, 0
	s_add_u32 s18, s4, 0x4900
	s_addc_u32 s19, s5, 0
	s_add_u32 s20, s4, 0x4a00
	s_addc_u32 s21, s5, 0
	s_add_u32 s22, s4, 0x4b00
	s_addc_u32 s23, s5, 0
	s_add_u32 s24, s4, 0x4c00
	s_addc_u32 s25, s5, 0
	s_add_u32 s26, s4, 0x4d00
	s_addc_u32 s27, s5, 0
	s_add_u32 s28, s4, 0x4e00
	s_addc_u32 s29, s5, 0
	s_add_u32 s30, s4, 0x4f00
	s_addc_u32 s31, s5, 0
	s_add_u32 s36, s4, 0x5000
	s_addc_u32 s37, s5, 0
	s_add_u32 s38, s4, 0x5100
	s_addc_u32 s39, s5, 0
	s_add_u32 s40, s4, 0x5200
	s_addc_u32 s41, s5, 0
	s_add_u32 s42, s4, 0x5300
	s_addc_u32 s43, s5, 0
	s_mov_b32 s34, 1
	v_mov_b32_e32 v16, 0
	s_branch .LBB0_2591

; __device__ __forceinline__ unsigned xb_ld(unsigned* p)              { return __hip_atomic_load(p, __ATOMIC_RELAXED, __HIP_MEMORY_SCOPE_AGENT); }
; __device__ __forceinline__ void xcd_barrier_complete(unsigned* bar, unsigned x, unsigned& nloc, unsigned& nx) {
;     const unsigned G = gridDim.x * gridDim.y * gridDim.z;
;     unsigned sum, cnt, mine, sp = 0u;
;     for (;;) {
;         sum = 0u; cnt = 0u; mine = 0u;
; #pragma unroll
;         for (unsigned j = 0; j < 16; ++j) { const unsigned c = xb_ld(&bar[XB_XCNT(j)]); sum += c; cnt += (c > 0u) ? 1u : 0u; mine = (j == x) ? c : mine; }
; __device__ __forceinline__ void xcd_barrier(const XcdBarrier& b) {
;     asm volatile("s_waitcnt vmcnt(0)" ::: "memory");
;     __syncthreads();
;     if (threadIdx.x == 0) {
;         unsigned* bar = b.bar;
;         __builtin_amdgcn_s_waitcnt(0);
;         unsigned nloc = b.st[0], nx = b.st[1];
;         if (nloc == 0u) { xcd_barrier_complete(bar, b.x, nloc, nx); b.st[0] = nloc; b.st[1] = nx; }
.LBB0_2648:
	s_or_b64 exec, exec, s[6:7]
	s_cmp_lt_i32 s57, 25
	s_cbranch_scc1 .LBB0_2702
	s_setprio 0
	s_add_i32 s0, 0, 0x20520
	v_mov_b32_e32 v0, s0
	ds_read_b64 v[0:1], v0
	s_getreg_b32 s3, hwreg(HW_REG_XCC_ID, 0, 4)
	s_waitcnt vmcnt(0)
	s_waitcnt lgkmcnt(0)
	s_barrier
	v_readfirstlane_b32 s4, v0
	v_readfirstlane_b32 s5, v1
	s_mov_b64 s[0:1], exec
	v_readlane_b32 s6, v246, 2
	v_readlane_b32 s7, v246, 3
	s_and_b64 s[6:7], s[0:1], s[6:7]
	s_mov_b64 exec, s[6:7]
	s_cbranch_execz .LBB0_2701
	s_add_i32 s6, 0, 0x20160
	v_mov_b32_e32 v0, s6
	s_waitcnt vmcnt(0) expcnt(0) lgkmcnt(0)
	ds_read_b32 v2, v0
	s_add_i32 s6, 0, 0x20164
	v_mov_b32_e32 v0, s6
	ds_read_b32 v0, v0
	s_and_b32 s3, s3, 15
	s_waitcnt lgkmcnt(1)
	v_cmp_ne_u32_e32 vcc, 0, v2
	s_cbranch_vccnz .LBB0_2665
	v_readlane_b32 s6, v246, 0
	v_readlane_b32 s7, v246, 1
	s_load_dwordx2 s[10:11], s[6:7], 0x4
	s_add_u32 s6, s4, 0x4200
	s_addc_u32 s7, s5, 0
	s_add_u32 s8, s4, 0x4400
	s_addc_u32 s9, s5, 0
	s_waitcnt lgkmcnt(0)
	s_mul_i32 s33, s10, s52
	s_add_u32 s10, s4, 0x4500
	s_mul_i32 s33, s33, s11
	s_addc_u32 s11, s5, 0
	s_add_u32 s12, s4, 0x4600
	s_addc_u32 s13, s5, 0
	s_add_u32 s14, s4, 0x4700
	s_addc_u32 s15, s5, 0
	s_add_u32 s16, s4, 0x4800
	s_addc_u32 s17, s5, 0
	s_add_u32 s18, s4, 0x4900
	s_addc_u32 s19, s5, 0
	s_add_u32 s20, s4, 0x4a00
	s_addc_u32 s21, s5, 0
	s_add_u32 s22, s4, 0x4b00
	s_addc_u32 s23, s5, 0
	s_add_u32 s24, s4, 0x4c00
	s_addc_u32 s25, s5, 0
	s_add_u32 s26, s4, 0x4d00
	s_addc_u32 s27, s5, 0
	s_add_u32 s28, s4, 0x4e00
	s_addc_u32 s29, s5, 0
	s_add_u32 s30, s4, 0x4f00
	s_addc_u32 s31, s5, 0
	s_add_u32 s36, s4, 0x5000
	s_addc_u32 s37, s5, 0
	s_add_u32 s38, s4, 0x5100
	s_addc_u32 s39, s5, 0
	s_add_u32 s40, s4, 0x5200
	s_addc_u32 s41, s5, 0
	s_add_u32 s42, s4, 0x5300
	s_addc_u32 s43, s5, 0
	s_mov_b32 s34, 1
	v_mov_b32_e32 v16, 0
	s_branch .LBB0_2653

; #define PG8_STAGE(bufoff, soff, voff) do { _Pragma("unroll") for (int _i = 0; _i < 2; ++_i) \
;         __builtin_amdgcn_raw_ptr_buffer_load_lds(rs_##voff, (PG8_LAS unsigned*)(lds + (bufoff) + ldsw + _i * 8192), 16, (int)(voff)[_i], (int)(soff), 0, 0); } while (0)
; #define PG8_LDA(dst, b, h) do { _Pragma("unroll") for (int m = 0; m < 4; ++m) _Pragma("unroll") for (int k = 0; k < 2; ++k) dst[m][k] = *(const PG8_LAS bf16x8*)(lds + PG8_SA(b, h) + aoff + m * 2048 + k * 1024); } while (0)
; #define PG8_LDB(dst, b, h) do { _Pragma("unroll") for (int n = 0; n < 2; ++n) _Pragma("unroll") for (int k = 0; k < 2; ++k) dst[n][k] = *(const PG8_LAS bf16x8*)(lds + PG8_SB(b, h) + boff + n * 2048 + k * 1024); } while (0)
; #define PG8_MMA(ai, bj, At, Bt) do { __builtin_amdgcn_s_setprio(1); _Pragma("unroll") for (int m = 0; m < 4; ++m) _Pragma("unroll") for (int n = 0; n < 2; ++n) _Pragma("unroll") for (int k = 0; k < 2; ++k) \
;         acc[ai][bj][m][n] = __builtin_amdgcn_mfma_f32_16x16x32_bf16(Bt[n][k], At[m][k], acc[ai][bj][m][n], 0, 0, 0); __builtin_amdgcn_s_setprio(0); } while (0)
; #define PG8_WAIT_V(n) asm volatile("s_waitcnt vmcnt(" #n ")" ::: "memory")
; #define PG8_WAIT_L(n) asm volatile("s_waitcnt lgkmcnt(" #n ")" ::: "memory")
; #define PG8_BAR __builtin_amdgcn_s_barrier()
; #define PG8_SCHED __builtin_amdgcn_sched_barrier(0)
; template <class Epi, class Sched, bool ALIGN_EPI = false, bool SP2 = false>
; __device__ __forceinline__ void gemm_phase(PG8_LAS unsigned char* lds, const Gemm g, const Sched& S, const Epi& E, const int wid  ) {
;     ...
;             PG8_LDB(B0, 0, 0); PG8_LDB(B1, 0, 1); PG8_SCHED; PG8_LDA(At, 0, 0); PG8_STAGE(PG8_SA(1, 1), a1 + hstep, voffA);
;             PG8_WAIT_V(8); PG8_WAIT_L(0); PG8_BAR; PG8_MMA(0, 0, At, B0); PG8_MMA(0, 1, At, B1); PG8_BAR; PG8_SCHED;
;             PG8_LDA(At, 0, 1); PG8_STAGE(PG8_SB(0, 0), b2, voffB); PG8_STAGE(PG8_SB(0, 1), b2 + hstep, voffB); PG8_STAGE(PG8_SA(0, 0), a2, voffA);
;             PG8_WAIT_V(8); PG8_WAIT_L(0); PG8_BAR; PG8_MMA(1, 0, At, B0); PG8_MMA(1, 1, At, B1); PG8_BAR; PG8_SCHED;
.Lprio_2813:
.LBB0_2813:
	s_waitcnt lgkmcnt(0)
	ds_read_b128 v[16:19], v188
	ds_read_b128 v[20:23], v188 offset:1024
	ds_read_b128 v[24:27], v188 offset:2048
	ds_read_b128 v[28:31], v188 offset:3072
	ds_read_b128 v[32:35], v189
	ds_read_b128 v[36:39], v189 offset:1024
	ds_read_b128 v[40:43], v189 offset:2048
	ds_read_b128 v[44:47], v189 offset:3072
	s_add_i32 s18, s8, 0xfff80080
	s_cmp_eq_u32 s48, 28
	s_cselect_b32 s93, s6, s18
	s_cselect_b32 s92, s7, s9
	s_or_b32 s49, s93, 0x80
	s_mov_b32 m0, s74
	ds_read_b128 v[160:163], v190
	ds_read_b128 v[170:173], v190 offset:1024
	ds_read_b128 v[174:177], v190 offset:2048
	ds_read_b128 v[178:181], v190 offset:3072
	ds_read_b128 v[194:197], v190 offset:4096
	ds_read_b128 v[198:201], v190 offset:5120
	ds_read_b128 v[202:205], v190 offset:6144
	ds_read_b128 v[206:209], v190 offset:7168
	buffer_load_dwordx4 v182, s[12:15], s8 offen lds
	s_mov_b32 m0, s76
	s_nop 0
	buffer_load_dwordx4 v184, s[12:15], s8 offen lds
	s_waitcnt vmcnt(8)
	s_waitcnt lgkmcnt(0)
	s_barrier
	s_waitcnt lgkmcnt(7)
	v_mfma_f32_16x16x32_bf16 v[152:155], v[16:19], v[160:163], v[152:155]
	v_mfma_f32_16x16x32_bf16 v[52:55], v[24:27], v[160:163], v[52:55]
	s_waitcnt lgkmcnt(5)
	v_mfma_f32_16x16x32_bf16 v[148:151], v[16:19], v[174:177], v[148:151]
	v_mfma_f32_16x16x32_bf16 v[144:147], v[24:27], v[174:177], v[144:147]
	s_waitcnt lgkmcnt(3)
	v_mfma_f32_16x16x32_bf16 v[140:143], v[16:19], v[194:197], v[140:143]
	v_mfma_f32_16x16x32_bf16 v[132:135], v[24:27], v[194:197], v[132:135]
	s_waitcnt lgkmcnt(1)
	v_mfma_f32_16x16x32_bf16 v[156:159], v[16:19], v[202:205], v[156:159]
	v_mfma_f32_16x16x32_bf16 v[120:123], v[24:27], v[202:205], v[120:123]
	v_mfma_f32_16x16x32_bf16 v[152:155], v[20:23], v[170:173], v[152:155]
	v_mfma_f32_16x16x32_bf16 v[52:55], v[28:31], v[170:173], v[52:55]
	v_mfma_f32_16x16x32_bf16 v[148:151], v[20:23], v[178:181], v[148:151]
	v_mfma_f32_16x16x32_bf16 v[144:147], v[28:31], v[178:181], v[144:147]
	v_mfma_f32_16x16x32_bf16 v[140:143], v[20:23], v[198:201], v[140:143]
	v_mfma_f32_16x16x32_bf16 v[132:135], v[28:31], v[198:201], v[132:135]
	s_waitcnt lgkmcnt(0)
	v_mfma_f32_16x16x32_bf16 v[156:159], v[20:23], v[206:209], v[156:159]
	v_mfma_f32_16x16x32_bf16 v[120:123], v[28:31], v[206:209], v[120:123]
	v_mfma_f32_16x16x32_bf16 v[12:15], v[32:35], v[160:163], v[12:15]
	v_mfma_f32_16x16x32_bf16 v[8:11], v[40:43], v[160:163], v[8:11]
	v_mfma_f32_16x16x32_bf16 v[136:139], v[32:35], v[174:177], v[136:139]
	v_mfma_f32_16x16x32_bf16 v[128:131], v[40:43], v[174:177], v[128:131]
	v_mfma_f32_16x16x32_bf16 v[124:127], v[32:35], v[194:197], v[124:127]
	v_mfma_f32_16x16x32_bf16 v[116:119], v[40:43], v[194:197], v[116:119]
	v_mfma_f32_16x16x32_bf16 v[112:115], v[32:35], v[202:205], v[112:115]
	v_mfma_f32_16x16x32_bf16 v[108:111], v[40:43], v[202:205], v[108:111]
	v_mfma_f32_16x16x32_bf16 v[12:15], v[36:39], v[170:173], v[12:15]
	v_mfma_f32_16x16x32_bf16 v[8:11], v[44:47], v[170:173], v[8:11]
	v_mfma_f32_16x16x32_bf16 v[136:139], v[36:39], v[178:181], v[136:139]
	v_mfma_f32_16x16x32_bf16 v[128:131], v[44:47], v[178:181], v[128:131]
	v_mfma_f32_16x16x32_bf16 v[124:127], v[36:39], v[198:201], v[124:127]
	v_mfma_f32_16x16x32_bf16 v[116:119], v[44:47], v[198:201], v[116:119]
	v_mfma_f32_16x16x32_bf16 v[112:115], v[36:39], v[206:209], v[112:115]
	v_mfma_f32_16x16x32_bf16 v[108:111], v[44:47], v[206:209], v[108:111]
	s_barrier
	s_mov_b32 m0, s34
	s_mov_b32 s18, s14
	s_mov_b32 s19, s15
	ds_read_b128 v[160:163], v190 offset:16384
	ds_read_b128 v[170:173], v190 offset:17408
	ds_read_b128 v[174:177], v190 offset:18432
	ds_read_b128 v[178:181], v190 offset:19456
	ds_read_b128 v[194:197], v190 offset:20480
	ds_read_b128 v[198:201], v190 offset:21504
	ds_read_b128 v[202:205], v190 offset:22528
	ds_read_b128 v[206:209], v190 offset:23552
	buffer_load_dwordx4 v183, s[16:19], s92 offen lds
	s_mov_b32 m0, s35
	s_add_i32 s94, s92, 0x80000
	buffer_load_dwordx4 v185, s[16:19], s92 offen lds
	s_mov_b32 m0, s50
	s_nop 0
	buffer_load_dwordx4 v183, s[16:19], s94 offen lds
	s_mov_b32 m0, s51
	s_nop 0
	buffer_load_dwordx4 v185, s[16:19], s94 offen lds
	s_mov_b32 m0, s33
	s_nop 0
	buffer_load_dwordx4 v182, s[12:15], s93 offen lds
	s_mov_b32 m0, s53
	s_nop 0
	buffer_load_dwordx4 v184, s[12:15], s93 offen lds
	s_waitcnt vmcnt(8)
	s_waitcnt lgkmcnt(0)
	s_barrier
	s_waitcnt lgkmcnt(7)
	v_mfma_f32_16x16x32_bf16 v[104:107], v[16:19], v[160:163], v[104:107]
	v_mfma_f32_16x16x32_bf16 v[100:103], v[24:27], v[160:163], v[100:103]
	s_waitcnt lgkmcnt(5)
	v_mfma_f32_16x16x32_bf16 v[96:99], v[16:19], v[174:177], v[96:99]
	v_mfma_f32_16x16x32_bf16 v[88:91], v[24:27], v[174:177], v[88:91]
	s_waitcnt lgkmcnt(3)
	v_mfma_f32_16x16x32_bf16 v[84:87], v[16:19], v[194:197], v[84:87]
	v_mfma_f32_16x16x32_bf16 v[76:79], v[24:27], v[194:197], v[76:79]
	s_waitcnt lgkmcnt(1)
	v_mfma_f32_16x16x32_bf16 v[16:19], v[16:19], v[202:205], v[92:95]
	v_mfma_f32_16x16x32_bf16 v[104:107], v[20:23], v[170:173], v[104:107]
	v_mfma_f32_16x16x32_bf16 v[100:103], v[28:31], v[170:173], v[100:103]
	v_mfma_f32_16x16x32_bf16 v[96:99], v[20:23], v[178:181], v[96:99]
	v_mfma_f32_16x16x32_bf16 v[88:91], v[28:31], v[178:181], v[88:91]
	v_mfma_f32_16x16x32_bf16 v[84:87], v[20:23], v[198:201], v[84:87]
	v_mfma_f32_16x16x32_bf16 v[76:79], v[28:31], v[198:201], v[76:79]
	s_waitcnt lgkmcnt(0)
	v_mfma_f32_16x16x32_bf16 v[16:19], v[20:23], v[206:209], v[16:19]
	v_mfma_f32_16x16x32_bf16 v[20:23], v[24:27], v[202:205], v[48:51]
	v_mfma_f32_16x16x32_bf16 v[20:23], v[28:31], v[206:209], v[20:23]
	v_mfma_f32_16x16x32_bf16 v[48:51], v[32:35], v[194:197], v[68:71]
	v_mfma_f32_16x16x32_bf16 v[4:7], v[32:35], v[160:163], v[4:7]
	v_mfma_f32_16x16x32_bf16 v[0:3], v[40:43], v[160:163], v[0:3]
	v_mfma_f32_16x16x32_bf16 v[24:27], v[32:35], v[174:177], v[80:83]
	v_mfma_f32_16x16x32_bf16 v[68:71], v[36:39], v[198:201], v[48:51]
	v_mfma_f32_16x16x32_bf16 v[48:51], v[40:43], v[194:197], v[64:67]
	v_mfma_f32_16x16x32_bf16 v[32:35], v[32:35], v[202:205], v[60:63]
	v_mfma_f32_16x16x32_bf16 v[4:7], v[36:39], v[170:173], v[4:7]
	v_mfma_f32_16x16x32_bf16 v[0:3], v[44:47], v[170:173], v[0:3]
	v_mfma_f32_16x16x32_bf16 v[24:27], v[36:39], v[178:181], v[24:27]
	v_mfma_f32_16x16x32_bf16 v[28:31], v[40:43], v[174:177], v[72:75]
	v_mfma_f32_16x16x32_bf16 v[64:67], v[44:47], v[198:201], v[48:51]
	v_mfma_f32_16x16x32_bf16 v[32:35], v[36:39], v[206:209], v[32:35]
	v_mfma_f32_16x16x32_bf16 v[36:39], v[40:43], v[202:205], v[56:59]
	v_mfma_f32_16x16x32_bf16 v[28:31], v[44:47], v[178:181], v[28:31]
	v_mfma_f32_16x16x32_bf16 v[36:39], v[44:47], v[206:209], v[36:39]
	s_barrier
; #define PG8_STAGE(bufoff, soff, voff) do { _Pragma("unroll") for (int _i = 0; _i < 2; ++_i) \
;         __builtin_amdgcn_raw_ptr_buffer_load_lds(rs_##voff, (PG8_LAS unsigned*)(lds + (bufoff) + ldsw + _i * 8192), 16, (int)(voff)[_i], (int)(soff), 0, 0); } while (0)
; #define PG8_LDA(dst, b, h) do { _Pragma("unroll") for (int m = 0; m < 4; ++m) _Pragma("unroll") for (int k = 0; k < 2; ++k) dst[m][k] = *(const PG8_LAS bf16x8*)(lds + PG8_SA(b, h) + aoff + m * 2048 + k * 1024); } while (0)
; #define PG8_LDB(dst, b, h) do { _Pragma("unroll") for (int n = 0; n < 2; ++n) _Pragma("unroll") for (int k = 0; k < 2; ++k) dst[n][k] = *(const PG8_LAS bf16x8*)(lds + PG8_SB(b, h) + boff + n * 2048 + k * 1024); } while (0)
; #define PG8_MMA(ai, bj, At, Bt) do { __builtin_amdgcn_s_setprio(1); _Pragma("unroll") for (int m = 0; m < 4; ++m) _Pragma("unroll") for (int n = 0; n < 2; ++n) _Pragma("unroll") for (int k = 0; k < 2; ++k) \
;         acc[ai][bj][m][n] = __builtin_amdgcn_mfma_f32_16x16x32_bf16(Bt[n][k], At[m][k], acc[ai][bj][m][n], 0, 0, 0); __builtin_amdgcn_s_setprio(0); } while (0)
; #define PG8_WAIT_V(n) asm volatile("s_waitcnt vmcnt(" #n ")" ::: "memory")
; #define PG8_WAIT_L(n) asm volatile("s_waitcnt lgkmcnt(" #n ")" ::: "memory")
; #define PG8_BAR __builtin_amdgcn_s_barrier()
; #define PG8_SCHED __builtin_amdgcn_sched_barrier(0)
; template <class Epi, class Sched, bool ALIGN_EPI = false, bool SP2 = false>
; __device__ __forceinline__ void gemm_phase(PG8_LAS unsigned char* lds, const Gemm g, const Sched& S, const Epi& E, const int wid  ) {
;     ...
;             PG8_LDB(B0, 1, 0); PG8_LDB(B1, 1, 1); PG8_SCHED; PG8_LDA(At, 1, 0); PG8_STAGE(PG8_SA(0, 1), a2 + hstep, voffA);
;             PG8_WAIT_V(8); PG8_WAIT_L(0); PG8_BAR; PG8_MMA(0, 0, At, B0); PG8_MMA(0, 1, At, B1); PG8_BAR; PG8_SCHED;
;             PG8_LDA(At, 1, 1); PG8_STAGE(PG8_SB(1, 0), b3, voffB); PG8_STAGE(PG8_SB(1, 1), b3 + hstep, voffB); PG8_STAGE(PG8_SA(1, 0), a3, voffA);
;             PG8_WAIT_V(8); PG8_WAIT_L(0); PG8_BAR; PG8_MMA(1, 0, At, B0); PG8_MMA(1, 1, At, B1); PG8_BAR; PG8_SCHED;
;     ...
;         if constexpr (ALIGN_EPI) { if (wr == 0) PG8_BAR; }
	ds_read_b128 v[40:43], v191
	ds_read_b128 v[44:47], v191 offset:1024
	ds_read_b128 v[48:51], v191 offset:2048
	ds_read_b128 v[56:59], v191 offset:3072
	ds_read_b128 v[60:63], v192
	ds_read_b128 v[160:163], v192 offset:1024
	ds_read_b128 v[170:173], v192 offset:2048
	ds_read_b128 v[174:177], v192 offset:3072
	s_add_i32 s93, s93, 0x80000
	s_mov_b32 m0, s54
	ds_read_b128 v[72:75], v190 offset:32768
	ds_read_b128 v[80:83], v190 offset:33792
	ds_read_b128 v[92:95], v190 offset:34816
	ds_read_b128 v[178:181], v190 offset:35840
	ds_read_b128 v[194:197], v190 offset:36864
	ds_read_b128 v[198:201], v190 offset:37888
	ds_read_b128 v[202:205], v190 offset:38912
	ds_read_b128 v[206:209], v190 offset:39936
	buffer_load_dwordx4 v182, s[12:15], s93 offen lds
	s_mov_b32 m0, s58
	s_nop 0
	buffer_load_dwordx4 v184, s[12:15], s93 offen lds
	s_waitcnt vmcnt(8)
	s_waitcnt lgkmcnt(0)
	s_barrier
	s_waitcnt lgkmcnt(7)
	v_mfma_f32_16x16x32_bf16 v[152:155], v[40:43], v[72:75], v[152:155]
	v_mfma_f32_16x16x32_bf16 v[52:55], v[48:51], v[72:75], v[52:55]
	s_waitcnt lgkmcnt(5)
	v_mfma_f32_16x16x32_bf16 v[148:151], v[40:43], v[92:95], v[148:151]
	v_mfma_f32_16x16x32_bf16 v[144:147], v[48:51], v[92:95], v[144:147]
	s_waitcnt lgkmcnt(3)
	v_mfma_f32_16x16x32_bf16 v[140:143], v[40:43], v[194:197], v[140:143]
	v_mfma_f32_16x16x32_bf16 v[132:135], v[48:51], v[194:197], v[132:135]
	s_waitcnt lgkmcnt(1)
	v_mfma_f32_16x16x32_bf16 v[156:159], v[40:43], v[202:205], v[156:159]
	v_mfma_f32_16x16x32_bf16 v[120:123], v[48:51], v[202:205], v[120:123]
	v_mfma_f32_16x16x32_bf16 v[152:155], v[44:47], v[80:83], v[152:155]
	v_mfma_f32_16x16x32_bf16 v[52:55], v[56:59], v[80:83], v[52:55]
	v_mfma_f32_16x16x32_bf16 v[148:151], v[44:47], v[178:181], v[148:151]
	v_mfma_f32_16x16x32_bf16 v[144:147], v[56:59], v[178:181], v[144:147]
	v_mfma_f32_16x16x32_bf16 v[140:143], v[44:47], v[198:201], v[140:143]
	v_mfma_f32_16x16x32_bf16 v[132:135], v[56:59], v[198:201], v[132:135]
	s_waitcnt lgkmcnt(0)
	v_mfma_f32_16x16x32_bf16 v[156:159], v[44:47], v[206:209], v[156:159]
	v_mfma_f32_16x16x32_bf16 v[120:123], v[56:59], v[206:209], v[120:123]
	v_mfma_f32_16x16x32_bf16 v[12:15], v[60:63], v[72:75], v[12:15]
	v_mfma_f32_16x16x32_bf16 v[8:11], v[170:173], v[72:75], v[8:11]
	v_mfma_f32_16x16x32_bf16 v[72:75], v[60:63], v[92:95], v[136:139]
	v_mfma_f32_16x16x32_bf16 v[136:139], v[160:163], v[178:181], v[72:75]
	v_mfma_f32_16x16x32_bf16 v[72:75], v[170:173], v[92:95], v[128:131]
	v_mfma_f32_16x16x32_bf16 v[128:131], v[174:177], v[178:181], v[72:75]
	v_mfma_f32_16x16x32_bf16 v[72:75], v[60:63], v[194:197], v[124:127]
	v_mfma_f32_16x16x32_bf16 v[124:127], v[160:163], v[198:201], v[72:75]
	v_mfma_f32_16x16x32_bf16 v[72:75], v[170:173], v[194:197], v[116:119]
	v_mfma_f32_16x16x32_bf16 v[116:119], v[174:177], v[198:201], v[72:75]
	v_mfma_f32_16x16x32_bf16 v[72:75], v[60:63], v[202:205], v[112:115]
	v_mfma_f32_16x16x32_bf16 v[112:115], v[160:163], v[206:209], v[72:75]
	v_mfma_f32_16x16x32_bf16 v[72:75], v[170:173], v[202:205], v[108:111]
	v_mfma_f32_16x16x32_bf16 v[12:15], v[160:163], v[80:83], v[12:15]
	v_mfma_f32_16x16x32_bf16 v[8:11], v[174:177], v[80:83], v[8:11]
	v_mfma_f32_16x16x32_bf16 v[108:111], v[174:177], v[206:209], v[72:75]
	s_barrier
	s_mov_b32 m0, s63
	s_or_b32 s93, s92, 0x80
	s_nop 0
	ds_read_b128 v[72:75], v190 offset:49152
	ds_read_b128 v[80:83], v190 offset:50176
	ds_read_b128 v[178:181], v190 offset:51200
	ds_read_b128 v[194:197], v190 offset:52224
	ds_read_b128 v[198:201], v190 offset:53248
	ds_read_b128 v[202:205], v190 offset:54272
	ds_read_b128 v[206:209], v190 offset:55296
	ds_read_b128 v[210:213], v190 offset:56320
	buffer_load_dwordx4 v183, s[16:19], s93 offen lds
	s_mov_b32 m0, s65
	s_add_i32 s92, s92, 0x80080
	buffer_load_dwordx4 v185, s[16:19], s93 offen lds
	s_mov_b32 m0, s68
	s_nop 0
	buffer_load_dwordx4 v183, s[16:19], s92 offen lds
	s_mov_b32 m0, s69
	s_nop 0
	buffer_load_dwordx4 v185, s[16:19], s92 offen lds
	s_mov_b32 m0, s66
	s_nop 0
	buffer_load_dwordx4 v182, s[12:15], s49 offen lds
	s_mov_b32 m0, s67
	s_nop 0
	buffer_load_dwordx4 v184, s[12:15], s49 offen lds
	s_waitcnt vmcnt(8)
	s_waitcnt lgkmcnt(0)
	s_barrier
	s_waitcnt lgkmcnt(7)
	v_mfma_f32_16x16x32_bf16 v[92:95], v[40:43], v[72:75], v[104:107]
	s_waitcnt lgkmcnt(6)
	v_mfma_f32_16x16x32_bf16 v[104:107], v[44:47], v[80:83], v[92:95]
	v_mfma_f32_16x16x32_bf16 v[92:95], v[48:51], v[72:75], v[100:103]
	v_mfma_f32_16x16x32_bf16 v[100:103], v[56:59], v[80:83], v[92:95]
	s_waitcnt lgkmcnt(5)
	v_mfma_f32_16x16x32_bf16 v[92:95], v[40:43], v[178:181], v[96:99]
	s_waitcnt lgkmcnt(1)
	v_mfma_f32_16x16x32_bf16 v[16:19], v[40:43], v[206:209], v[16:19]
	v_mfma_f32_16x16x32_bf16 v[96:99], v[44:47], v[194:197], v[92:95]
	v_mfma_f32_16x16x32_bf16 v[88:91], v[48:51], v[178:181], v[88:91]
	v_mfma_f32_16x16x32_bf16 v[84:87], v[40:43], v[198:201], v[84:87]
	v_mfma_f32_16x16x32_bf16 v[76:79], v[48:51], v[198:201], v[76:79]
	s_waitcnt lgkmcnt(0)
	v_mfma_f32_16x16x32_bf16 v[92:95], v[44:47], v[210:213], v[16:19]
	v_mfma_f32_16x16x32_bf16 v[16:19], v[48:51], v[206:209], v[20:23]
	v_mfma_f32_16x16x32_bf16 v[88:91], v[56:59], v[194:197], v[88:91]
	v_mfma_f32_16x16x32_bf16 v[84:87], v[44:47], v[202:205], v[84:87]
	v_mfma_f32_16x16x32_bf16 v[76:79], v[56:59], v[202:205], v[76:79]
	v_mfma_f32_16x16x32_bf16 v[48:51], v[56:59], v[210:213], v[16:19]
	v_mfma_f32_16x16x32_bf16 v[4:7], v[60:63], v[72:75], v[4:7]
	v_mfma_f32_16x16x32_bf16 v[0:3], v[170:173], v[72:75], v[0:3]
	v_mfma_f32_16x16x32_bf16 v[16:19], v[60:63], v[178:181], v[24:27]
	v_mfma_f32_16x16x32_bf16 v[4:7], v[160:163], v[80:83], v[4:7]
	v_mfma_f32_16x16x32_bf16 v[0:3], v[174:177], v[80:83], v[0:3]
	v_mfma_f32_16x16x32_bf16 v[80:83], v[160:163], v[194:197], v[16:19]
	v_mfma_f32_16x16x32_bf16 v[16:19], v[170:173], v[178:181], v[28:31]
	v_mfma_f32_16x16x32_bf16 v[72:75], v[174:177], v[194:197], v[16:19]
	v_mfma_f32_16x16x32_bf16 v[16:19], v[60:63], v[198:201], v[68:71]
	v_mfma_f32_16x16x32_bf16 v[68:71], v[160:163], v[202:205], v[16:19]
	v_mfma_f32_16x16x32_bf16 v[16:19], v[170:173], v[198:201], v[64:67]
	v_mfma_f32_16x16x32_bf16 v[64:67], v[174:177], v[202:205], v[16:19]
	v_mfma_f32_16x16x32_bf16 v[16:19], v[60:63], v[206:209], v[32:35]
	v_mfma_f32_16x16x32_bf16 v[60:63], v[160:163], v[210:213], v[16:19]
	v_mfma_f32_16x16x32_bf16 v[16:19], v[170:173], v[206:209], v[36:39]
	v_mfma_f32_16x16x32_bf16 v[56:59], v[174:177], v[210:213], v[16:19]
	s_barrier
	s_add_i32 s48, s48, 2
	s_addk_i32 s8, 0x100
	s_addk_i32 s9, 0x100
	s_cmp_gt_u32 s48, 29
	s_cbranch_scc0 .LBB0_2813
	s_and_b64 vcc, exec, s[26:27]
	s_cbranch_vccz .LBB0_2816
	s_barrier

; __device__ __forceinline__ unsigned xb_ld(unsigned* p)              { return __hip_atomic_load(p, __ATOMIC_RELAXED, __HIP_MEMORY_SCOPE_AGENT); }
; __device__ __forceinline__ void xcd_barrier_complete(unsigned* bar, unsigned x, unsigned& nloc, unsigned& nx) {
;     const unsigned G = gridDim.x * gridDim.y * gridDim.z;
;     unsigned sum, cnt, mine, sp = 0u;
;     for (;;) {
;         sum = 0u; cnt = 0u; mine = 0u;
; #pragma unroll
;         for (unsigned j = 0; j < 16; ++j) { const unsigned c = xb_ld(&bar[XB_XCNT(j)]); sum += c; cnt += (c > 0u) ? 1u : 0u; mine = (j == x) ? c : mine; }
; __device__ __forceinline__ void xcd_barrier(const XcdBarrier& b) {
;     asm volatile("s_waitcnt vmcnt(0)" ::: "memory");
;     __syncthreads();
;     if (threadIdx.x == 0) {
;         unsigned* bar = b.bar;
;         __builtin_amdgcn_s_waitcnt(0);
;         unsigned nloc = b.st[0], nx = b.st[1];
;         if (nloc == 0u) { xcd_barrier_complete(bar, b.x, nloc, nx); b.st[0] = nloc; b.st[1] = nx; }
.LBB0_2958:
	s_cmp_lt_i32 s57, 30
	s_cbranch_scc1 .LBB0_3127
	s_setprio 0
	s_add_i32 s0, 0, 0x20520
	v_mov_b32_e32 v0, s0
	ds_read_b64 v[0:1], v0
	s_getreg_b32 s3, hwreg(HW_REG_XCC_ID, 0, 4)
	s_waitcnt vmcnt(0)
	s_waitcnt vmcnt(16) lgkmcnt(0)
	s_barrier
	v_readfirstlane_b32 s4, v0
	v_readfirstlane_b32 s5, v1
	s_mov_b64 s[0:1], exec
	v_readlane_b32 s6, v246, 2
	v_readlane_b32 s7, v246, 3
	s_and_b64 s[6:7], s[0:1], s[6:7]
	s_mov_b64 exec, s[6:7]
	s_cbranch_execz .LBB0_3126
	s_add_i32 s6, 0, 0x20160
	v_mov_b32_e32 v0, s6
	s_waitcnt vmcnt(0) expcnt(0) lgkmcnt(0)
	ds_read_b32 v2, v0
	s_add_i32 s6, 0, 0x20164
	v_mov_b32_e32 v0, s6
	ds_read_b32 v0, v0
	s_and_b32 s3, s3, 15
	s_waitcnt lgkmcnt(1)
	v_cmp_ne_u32_e32 vcc, 0, v2
	s_cbranch_vccnz .LBB0_3090
	v_readlane_b32 s6, v246, 0
	v_readlane_b32 s7, v246, 1
	s_load_dwordx2 s[10:11], s[6:7], 0x4
	s_add_u32 s6, s4, 0x4200
	s_addc_u32 s7, s5, 0
	s_add_u32 s8, s4, 0x4400
	s_addc_u32 s9, s5, 0
	s_waitcnt lgkmcnt(0)
	s_mul_i32 s33, s10, s52
	s_add_u32 s10, s4, 0x4500
	s_mul_i32 s33, s33, s11
	s_addc_u32 s11, s5, 0
	s_add_u32 s12, s4, 0x4600
	s_addc_u32 s13, s5, 0
	s_add_u32 s14, s4, 0x4700
	s_addc_u32 s15, s5, 0
	s_add_u32 s16, s4, 0x4800
	s_addc_u32 s17, s5, 0
	s_add_u32 s18, s4, 0x4900
	s_addc_u32 s19, s5, 0
	s_add_u32 s20, s4, 0x4a00
	s_addc_u32 s21, s5, 0
	s_add_u32 s22, s4, 0x4b00
	s_addc_u32 s23, s5, 0
	s_add_u32 s24, s4, 0x4c00
	s_addc_u32 s25, s5, 0
	s_add_u32 s26, s4, 0x4d00
	s_addc_u32 s27, s5, 0
	s_add_u32 s28, s4, 0x4e00
	s_addc_u32 s29, s5, 0
	s_add_u32 s30, s4, 0x4f00
	s_addc_u32 s31, s5, 0
	s_add_u32 s36, s4, 0x5000
	s_addc_u32 s37, s5, 0
	s_add_u32 s38, s4, 0x5100
	s_addc_u32 s39, s5, 0
	s_add_u32 s40, s4, 0x5200
	s_addc_u32 s41, s5, 0
	s_add_u32 s42, s4, 0x5300
	s_addc_u32 s43, s5, 0
	s_mov_b32 s34, 1
	v_mov_b32_e32 v16, 0
	s_branch .LBB0_2963

; __device__ __forceinline__ unsigned xb_ld(unsigned* p)              { return __hip_atomic_load(p, __ATOMIC_RELAXED, __HIP_MEMORY_SCOPE_AGENT); }
; __device__ __forceinline__ void xcd_barrier_complete(unsigned* bar, unsigned x, unsigned& nloc, unsigned& nx) {
;     const unsigned G = gridDim.x * gridDim.y * gridDim.z;
;     unsigned sum, cnt, mine, sp = 0u;
;     for (;;) {
;         sum = 0u; cnt = 0u; mine = 0u;
; #pragma unroll
;         for (unsigned j = 0; j < 16; ++j) { const unsigned c = xb_ld(&bar[XB_XCNT(j)]); sum += c; cnt += (c > 0u) ? 1u : 0u; mine = (j == x) ? c : mine; }
; __device__ __forceinline__ void xcd_barrier(const XcdBarrier& b) {
;     asm volatile("s_waitcnt vmcnt(0)" ::: "memory");
;     __syncthreads();
;     if (threadIdx.x == 0) {
;         unsigned* bar = b.bar;
;         __builtin_amdgcn_s_waitcnt(0);
;         unsigned nloc = b.st[0], nx = b.st[1];
;         if (nloc == 0u) { xcd_barrier_complete(bar, b.x, nloc, nx); b.st[0] = nloc; b.st[1] = nx; }
.LBB0_3365:
	s_cmp_lt_i32 s57, 34
	s_cbranch_scc1 .LBB0_3419
	s_setprio 0
	s_add_i32 s0, 0, 0x20520
	v_mov_b32_e32 v0, s0
	ds_read_b64 v[0:1], v0
	s_getreg_b32 s3, hwreg(HW_REG_XCC_ID, 0, 4)
	s_waitcnt vmcnt(0)
	s_waitcnt vmcnt(16) lgkmcnt(0)
	s_barrier
	v_readfirstlane_b32 s4, v0
	v_readfirstlane_b32 s5, v1
	s_mov_b64 s[0:1], exec
	v_readlane_b32 s6, v246, 2
	v_readlane_b32 s7, v246, 3
	s_and_b64 s[6:7], s[0:1], s[6:7]
	s_mov_b64 exec, s[6:7]
	s_cbranch_execz .LBB0_3418
	s_add_i32 s6, 0, 0x20160
	v_mov_b32_e32 v0, s6
	s_waitcnt vmcnt(0) expcnt(0) lgkmcnt(0)
	ds_read_b32 v2, v0
	s_add_i32 s6, 0, 0x20164
	v_mov_b32_e32 v0, s6
	ds_read_b32 v0, v0
	s_and_b32 s3, s3, 15
	s_waitcnt lgkmcnt(1)
	v_cmp_ne_u32_e32 vcc, 0, v2
	s_cbranch_vccnz .LBB0_3382
	v_readlane_b32 s6, v246, 0
	v_readlane_b32 s7, v246, 1
	s_load_dwordx2 s[10:11], s[6:7], 0x4
	s_add_u32 s6, s4, 0x4200
	s_addc_u32 s7, s5, 0
	s_add_u32 s8, s4, 0x4400
	s_addc_u32 s9, s5, 0
	s_waitcnt lgkmcnt(0)
	s_mul_i32 s33, s10, s52
	s_add_u32 s10, s4, 0x4500
	s_mul_i32 s33, s33, s11
	s_addc_u32 s11, s5, 0
	s_add_u32 s12, s4, 0x4600
	s_addc_u32 s13, s5, 0
	s_add_u32 s14, s4, 0x4700
	s_addc_u32 s15, s5, 0
	s_add_u32 s16, s4, 0x4800
	s_addc_u32 s17, s5, 0
	s_add_u32 s18, s4, 0x4900
	s_addc_u32 s19, s5, 0
	s_add_u32 s20, s4, 0x4a00
	s_addc_u32 s21, s5, 0
	s_add_u32 s22, s4, 0x4b00
	s_addc_u32 s23, s5, 0
	s_add_u32 s24, s4, 0x4c00
	s_addc_u32 s25, s5, 0
	s_add_u32 s26, s4, 0x4d00
	s_addc_u32 s27, s5, 0
	s_add_u32 s28, s4, 0x4e00
	s_addc_u32 s29, s5, 0
	s_add_u32 s30, s4, 0x4f00
	s_addc_u32 s31, s5, 0
	s_add_u32 s36, s4, 0x5000
	s_addc_u32 s37, s5, 0
	s_add_u32 s38, s4, 0x5100
	s_addc_u32 s39, s5, 0
	s_add_u32 s40, s4, 0x5200
	s_addc_u32 s41, s5, 0
	s_add_u32 s42, s4, 0x5300
	s_addc_u32 s43, s5, 0
	s_mov_b32 s34, 1
	v_mov_b32_e32 v16, 0
	s_branch .LBB0_3370

; __device__ __forceinline__ unsigned xb_ld(unsigned* p)              { return __hip_atomic_load(p, __ATOMIC_RELAXED, __HIP_MEMORY_SCOPE_AGENT); }
; __device__ __forceinline__ void xcd_barrier_complete(unsigned* bar, unsigned x, unsigned& nloc, unsigned& nx) {
;     const unsigned G = gridDim.x * gridDim.y * gridDim.z;
;     unsigned sum, cnt, mine, sp = 0u;
;     for (;;) {
;         sum = 0u; cnt = 0u; mine = 0u;
; #pragma unroll
;         for (unsigned j = 0; j < 16; ++j) { const unsigned c = xb_ld(&bar[XB_XCNT(j)]); sum += c; cnt += (c > 0u) ? 1u : 0u; mine = (j == x) ? c : mine; }
; __device__ __forceinline__ void xcd_barrier(const XcdBarrier& b) {
;     asm volatile("s_waitcnt vmcnt(0)" ::: "memory");
;     __syncthreads();
;     if (threadIdx.x == 0) {
;         unsigned* bar = b.bar;
;         __builtin_amdgcn_s_waitcnt(0);
;         unsigned nloc = b.st[0], nx = b.st[1];
;         if (nloc == 0u) { xcd_barrier_complete(bar, b.x, nloc, nx); b.st[0] = nloc; b.st[1] = nx; }
.LBB0_3504:
	s_cmp_lt_i32 s57, 35
	v_readlane_b32 s96, v246, 4
	v_readlane_b32 s80, v246, 6
	s_waitcnt vmcnt(16)
	s_barrier
	v_readlane_b32 s97, v246, 5
	s_cbranch_scc1 .LBB0_3558
	s_setprio 0
	s_add_i32 s0, 0, 0x20520
	v_mov_b32_e32 v0, s0
	ds_read_b64 v[0:1], v0
	s_getreg_b32 s3, hwreg(HW_REG_XCC_ID, 0, 4)
	s_waitcnt vmcnt(0)
	s_waitcnt lgkmcnt(0)
	s_barrier
	v_readfirstlane_b32 s4, v0
	v_readfirstlane_b32 s5, v1
	s_mov_b64 s[0:1], exec
	v_readlane_b32 s6, v246, 2
	v_readlane_b32 s7, v246, 3
	s_and_b64 s[6:7], s[0:1], s[6:7]
	s_mov_b64 exec, s[6:7]
	s_cbranch_execz .LBB0_3557
	s_add_i32 s6, 0, 0x20160
	v_mov_b32_e32 v0, s6
	s_waitcnt vmcnt(0) expcnt(0) lgkmcnt(0)
	ds_read_b32 v2, v0
	s_add_i32 s6, 0, 0x20164
	v_mov_b32_e32 v0, s6
	ds_read_b32 v0, v0
	s_and_b32 s3, s3, 15
	s_waitcnt lgkmcnt(1)
	v_cmp_ne_u32_e32 vcc, 0, v2
	s_cbranch_vccnz .LBB0_3521
	v_readlane_b32 s6, v246, 0
	v_readlane_b32 s7, v246, 1
	s_load_dwordx2 s[10:11], s[6:7], 0x4
	s_add_u32 s6, s4, 0x4200
	s_addc_u32 s7, s5, 0
	s_add_u32 s8, s4, 0x4400
	s_addc_u32 s9, s5, 0
	s_waitcnt lgkmcnt(0)
	s_mul_i32 s33, s10, s52
	s_add_u32 s10, s4, 0x4500
	s_mul_i32 s33, s33, s11
	s_addc_u32 s11, s5, 0
	s_add_u32 s12, s4, 0x4600
	s_addc_u32 s13, s5, 0
	s_add_u32 s14, s4, 0x4700
	s_addc_u32 s15, s5, 0
	s_add_u32 s16, s4, 0x4800
	s_addc_u32 s17, s5, 0
	s_add_u32 s18, s4, 0x4900
	s_addc_u32 s19, s5, 0
	s_add_u32 s20, s4, 0x4a00
	s_addc_u32 s21, s5, 0
	s_add_u32 s22, s4, 0x4b00
	s_addc_u32 s23, s5, 0
	s_add_u32 s24, s4, 0x4c00
	s_addc_u32 s25, s5, 0
	s_add_u32 s26, s4, 0x4d00
	s_addc_u32 s27, s5, 0
	s_add_u32 s28, s4, 0x4e00
	s_addc_u32 s29, s5, 0
	s_add_u32 s30, s4, 0x4f00
	s_addc_u32 s31, s5, 0
	s_add_u32 s36, s4, 0x5000
	s_addc_u32 s37, s5, 0
	s_add_u32 s38, s4, 0x5100
	s_addc_u32 s39, s5, 0
	s_add_u32 s40, s4, 0x5200
	s_addc_u32 s41, s5, 0
	s_add_u32 s42, s4, 0x5300
	s_addc_u32 s43, s5, 0
	s_mov_b32 s34, 1
	v_mov_b32_e32 v16, 0
	s_branch .LBB0_3509

; __device__ __forceinline__ unsigned xb_ld(unsigned* p)              { return __hip_atomic_load(p, __ATOMIC_RELAXED, __HIP_MEMORY_SCOPE_AGENT); }
; __device__ __forceinline__ void xcd_barrier_complete(unsigned* bar, unsigned x, unsigned& nloc, unsigned& nx) {
;     const unsigned G = gridDim.x * gridDim.y * gridDim.z;
;     unsigned sum, cnt, mine, sp = 0u;
;     for (;;) {
;         sum = 0u; cnt = 0u; mine = 0u;
; #pragma unroll
;         for (unsigned j = 0; j < 16; ++j) { const unsigned c = xb_ld(&bar[XB_XCNT(j)]); sum += c; cnt += (c > 0u) ? 1u : 0u; mine = (j == x) ? c : mine; }
; __device__ __forceinline__ void xcd_barrier(const XcdBarrier& b) {
;     asm volatile("s_waitcnt vmcnt(0)" ::: "memory");
;     __syncthreads();
;     if (threadIdx.x == 0) {
;         unsigned* bar = b.bar;
;         __builtin_amdgcn_s_waitcnt(0);
;         unsigned nloc = b.st[0], nx = b.st[1];
;         if (nloc == 0u) { xcd_barrier_complete(bar, b.x, nloc, nx); b.st[0] = nloc; b.st[1] = nx; }
.LBB0_3643:
	s_cmp_lt_i32 s57, 36
	v_readlane_b32 s96, v246, 4
	v_readlane_b32 s80, v246, 6
	s_waitcnt vmcnt(16)
	s_barrier
	v_readlane_b32 s97, v246, 5
	s_cbranch_scc1 .LBB0_3697
	s_setprio 0
	s_add_i32 s0, 0, 0x20520
	v_mov_b32_e32 v0, s0
	ds_read_b64 v[0:1], v0
	s_getreg_b32 s3, hwreg(HW_REG_XCC_ID, 0, 4)
	s_waitcnt vmcnt(0)
	s_waitcnt lgkmcnt(0)
	s_barrier
	v_readfirstlane_b32 s4, v0
	v_readfirstlane_b32 s5, v1
	s_mov_b64 s[0:1], exec
	v_readlane_b32 s6, v246, 2
	v_readlane_b32 s7, v246, 3
	s_and_b64 s[6:7], s[0:1], s[6:7]
	s_mov_b64 exec, s[6:7]
	s_cbranch_execz .LBB0_3696
	s_add_i32 s6, 0, 0x20160
	v_mov_b32_e32 v0, s6
	s_waitcnt vmcnt(0) expcnt(0) lgkmcnt(0)
	ds_read_b32 v2, v0
	s_add_i32 s6, 0, 0x20164
	v_mov_b32_e32 v0, s6
	ds_read_b32 v0, v0
	s_and_b32 s3, s3, 15
	s_waitcnt lgkmcnt(1)
	v_cmp_ne_u32_e32 vcc, 0, v2
	s_cbranch_vccnz .LBB0_3660
	v_readlane_b32 s6, v246, 0
	v_readlane_b32 s7, v246, 1
	s_load_dwordx2 s[10:11], s[6:7], 0x4
	s_add_u32 s6, s4, 0x4200
	s_addc_u32 s7, s5, 0
	s_add_u32 s8, s4, 0x4400
	s_addc_u32 s9, s5, 0
	s_waitcnt lgkmcnt(0)
	s_mul_i32 s33, s10, s52
	s_add_u32 s10, s4, 0x4500
	s_mul_i32 s33, s33, s11
	s_addc_u32 s11, s5, 0
	s_add_u32 s12, s4, 0x4600
	s_addc_u32 s13, s5, 0
	s_add_u32 s14, s4, 0x4700
	s_addc_u32 s15, s5, 0
	s_add_u32 s16, s4, 0x4800
	s_addc_u32 s17, s5, 0
	s_add_u32 s18, s4, 0x4900
	s_addc_u32 s19, s5, 0
	s_add_u32 s20, s4, 0x4a00
	s_addc_u32 s21, s5, 0
	s_add_u32 s22, s4, 0x4b00
	s_addc_u32 s23, s5, 0
	s_add_u32 s24, s4, 0x4c00
	s_addc_u32 s25, s5, 0
	s_add_u32 s26, s4, 0x4d00
	s_addc_u32 s27, s5, 0
	s_add_u32 s28, s4, 0x4e00
	s_addc_u32 s29, s5, 0
	s_add_u32 s30, s4, 0x4f00
	s_addc_u32 s31, s5, 0
	s_add_u32 s36, s4, 0x5000
	s_addc_u32 s37, s5, 0
	s_add_u32 s38, s4, 0x5100
	s_addc_u32 s39, s5, 0
	s_add_u32 s40, s4, 0x5200
	s_addc_u32 s41, s5, 0
	s_add_u32 s42, s4, 0x5300
	s_addc_u32 s43, s5, 0
	s_mov_b32 s34, 1
	v_mov_b32_e32 v16, 0
	s_branch .LBB0_3648

; #define PG8_STAGE(bufoff, soff, voff) do { _Pragma("unroll") for (int _i = 0; _i < 2; ++_i) \
;         __builtin_amdgcn_raw_ptr_buffer_load_lds(rs_##voff, (PG8_LAS unsigned*)(lds + (bufoff) + ldsw + _i * 8192), 16, (int)(voff)[_i], (int)(soff), 0, 0); } while (0)
; #define PG8_LDA(dst, b, h) do { _Pragma("unroll") for (int m = 0; m < 4; ++m) _Pragma("unroll") for (int k = 0; k < 2; ++k) dst[m][k] = *(const PG8_LAS bf16x8*)(lds + PG8_SA(b, h) + aoff + m * 2048 + k * 1024); } while (0)
; #define PG8_LDB(dst, b, h) do { _Pragma("unroll") for (int n = 0; n < 2; ++n) _Pragma("unroll") for (int k = 0; k < 2; ++k) dst[n][k] = *(const PG8_LAS bf16x8*)(lds + PG8_SB(b, h) + boff + n * 2048 + k * 1024); } while (0)
; #define PG8_MMA(ai, bj, At, Bt) do { __builtin_amdgcn_s_setprio(1); _Pragma("unroll") for (int m = 0; m < 4; ++m) _Pragma("unroll") for (int n = 0; n < 2; ++n) _Pragma("unroll") for (int k = 0; k < 2; ++k) \
;         acc[ai][bj][m][n] = __builtin_amdgcn_mfma_f32_16x16x32_bf16(Bt[n][k], At[m][k], acc[ai][bj][m][n], 0, 0, 0); __builtin_amdgcn_s_setprio(0); } while (0)
; #define PG8_WAIT_V(n) asm volatile("s_waitcnt vmcnt(" #n ")" ::: "memory")
; #define PG8_WAIT_L(n) asm volatile("s_waitcnt lgkmcnt(" #n ")" ::: "memory")
; #define PG8_BAR __builtin_amdgcn_s_barrier()
; #define PG8_SCHED __builtin_amdgcn_sched_barrier(0)
; template <class Epi, class Sched, bool ALIGN_EPI = false, bool SP2 = false>
; __device__ __forceinline__ void gemm_phase(PG8_LAS unsigned char* lds, const Gemm g, const Sched& S, const Epi& E, const int wid  ) {
;     ...
;             PG8_LDB(B0, 0, 0); PG8_LDB(B1, 0, 1); PG8_SCHED; PG8_LDA(At, 0, 0); PG8_STAGE(PG8_SA(1, 1), a1 + hstep, voffA);
;             PG8_WAIT_V(8); PG8_WAIT_L(0); PG8_BAR; PG8_MMA(0, 0, At, B0); PG8_MMA(0, 1, At, B1); PG8_BAR; PG8_SCHED;
;             PG8_LDA(At, 0, 1); PG8_STAGE(PG8_SB(0, 0), b2, voffB); PG8_STAGE(PG8_SB(0, 1), b2 + hstep, voffB); PG8_STAGE(PG8_SA(0, 0), a2, voffA);
;             PG8_WAIT_V(8); PG8_WAIT_L(0); PG8_BAR; PG8_MMA(1, 0, At, B0); PG8_MMA(1, 1, At, B1); PG8_BAR; PG8_SCHED;
.Lprio_4016:
.LBB0_4016:
	ds_read_b128 v[132:135], v152
	ds_read_b128 v[136:139], v152 offset:1024
	ds_read_b128 v[140:143], v152 offset:2048
	ds_read_b128 v[158:161], v152 offset:3072
	ds_read_b128 v[162:165], v153
	ds_read_b128 v[166:169], v153 offset:1024
	ds_read_b128 v[170:173], v153 offset:2048
	ds_read_b128 v[174:177], v153 offset:3072
	s_add_i32 s14, s41, 0xfff80080
	s_cmp_eq_u32 s73, 28
	s_cselect_b32 s76, s33, s14
	s_cselect_b32 s75, s40, s72
	s_or_b32 s74, s76, 0x80
	s_mov_b32 m0, s60
	ds_read_b128 v[178:181], v154
	ds_read_b128 v[182:185], v154 offset:1024
	ds_read_b128 v[186:189], v154 offset:2048
	ds_read_b128 v[190:193], v154 offset:3072
	ds_read_b128 v[194:197], v154 offset:4096
	ds_read_b128 v[198:201], v154 offset:5120
	ds_read_b128 v[202:205], v154 offset:6144
	ds_read_b128 v[206:209], v154 offset:7168
	buffer_load_dwordx4 v146, s[8:11], s41 offen lds
	s_mov_b32 m0, s61
	s_nop 0
	buffer_load_dwordx4 v148, s[8:11], s41 offen lds
	s_waitcnt vmcnt(8)
	s_waitcnt lgkmcnt(0)
	s_barrier
	s_waitcnt lgkmcnt(7)
	v_mfma_f32_16x16x32_bf16 v[124:127], v[132:135], v[178:181], v[124:127]
	v_mfma_f32_16x16x32_bf16 v[120:123], v[140:143], v[178:181], v[120:123]
	s_waitcnt lgkmcnt(5)
	v_mfma_f32_16x16x32_bf16 v[108:111], v[132:135], v[186:189], v[108:111]
	v_mfma_f32_16x16x32_bf16 v[104:107], v[140:143], v[186:189], v[104:107]
	s_waitcnt lgkmcnt(3)
	v_mfma_f32_16x16x32_bf16 v[92:95], v[132:135], v[194:197], v[92:95]
	v_mfma_f32_16x16x32_bf16 v[88:91], v[140:143], v[194:197], v[88:91]
	s_waitcnt lgkmcnt(1)
	v_mfma_f32_16x16x32_bf16 v[76:79], v[132:135], v[202:205], v[76:79]
	v_mfma_f32_16x16x32_bf16 v[72:75], v[140:143], v[202:205], v[72:75]
	v_mfma_f32_16x16x32_bf16 v[124:127], v[136:139], v[182:185], v[124:127]
	v_mfma_f32_16x16x32_bf16 v[120:123], v[158:161], v[182:185], v[120:123]
	v_mfma_f32_16x16x32_bf16 v[108:111], v[136:139], v[190:193], v[108:111]
	v_mfma_f32_16x16x32_bf16 v[104:107], v[158:161], v[190:193], v[104:107]
	v_mfma_f32_16x16x32_bf16 v[92:95], v[136:139], v[198:201], v[92:95]
	v_mfma_f32_16x16x32_bf16 v[88:91], v[158:161], v[198:201], v[88:91]
	s_waitcnt lgkmcnt(0)
	v_mfma_f32_16x16x32_bf16 v[76:79], v[136:139], v[206:209], v[76:79]
	v_mfma_f32_16x16x32_bf16 v[72:75], v[158:161], v[206:209], v[72:75]
	v_mfma_f32_16x16x32_bf16 v[116:119], v[162:165], v[178:181], v[116:119]
	v_mfma_f32_16x16x32_bf16 v[112:115], v[170:173], v[178:181], v[112:115]
	v_mfma_f32_16x16x32_bf16 v[100:103], v[162:165], v[186:189], v[100:103]
	v_mfma_f32_16x16x32_bf16 v[96:99], v[170:173], v[186:189], v[96:99]
	v_mfma_f32_16x16x32_bf16 v[84:87], v[162:165], v[194:197], v[84:87]
	v_mfma_f32_16x16x32_bf16 v[80:83], v[170:173], v[194:197], v[80:83]
	v_mfma_f32_16x16x32_bf16 v[68:71], v[162:165], v[202:205], v[68:71]
	v_mfma_f32_16x16x32_bf16 v[64:67], v[170:173], v[202:205], v[64:67]
	v_mfma_f32_16x16x32_bf16 v[116:119], v[166:169], v[182:185], v[116:119]
	v_mfma_f32_16x16x32_bf16 v[112:115], v[174:177], v[182:185], v[112:115]
	v_mfma_f32_16x16x32_bf16 v[100:103], v[166:169], v[190:193], v[100:103]
	v_mfma_f32_16x16x32_bf16 v[96:99], v[174:177], v[190:193], v[96:99]
	v_mfma_f32_16x16x32_bf16 v[84:87], v[166:169], v[198:201], v[84:87]
	v_mfma_f32_16x16x32_bf16 v[80:83], v[174:177], v[198:201], v[80:83]
	v_mfma_f32_16x16x32_bf16 v[68:71], v[166:169], v[206:209], v[68:71]
	v_mfma_f32_16x16x32_bf16 v[64:67], v[174:177], v[206:209], v[64:67]
	s_barrier
	s_mov_b32 m0, s35
	s_mov_b32 s14, s10
	s_mov_b32 s15, s11
	ds_read_b128 v[178:181], v154 offset:16384
	ds_read_b128 v[182:185], v154 offset:17408
	ds_read_b128 v[186:189], v154 offset:18432
	ds_read_b128 v[190:193], v154 offset:19456
	ds_read_b128 v[194:197], v154 offset:20480
	ds_read_b128 v[198:201], v154 offset:21504
	ds_read_b128 v[202:205], v154 offset:22528
	ds_read_b128 v[206:209], v154 offset:23552
	buffer_load_dwordx4 v147, s[12:15], s75 offen lds
	s_mov_b32 m0, s42
	s_add_i32 s77, s75, 0x80000
	buffer_load_dwordx4 v149, s[12:15], s75 offen lds
	s_mov_b32 m0, s43
	s_nop 0
	buffer_load_dwordx4 v147, s[12:15], s77 offen lds
	s_mov_b32 m0, s44
	s_nop 0
	buffer_load_dwordx4 v149, s[12:15], s77 offen lds
	s_mov_b32 m0, s34
	s_nop 0
	buffer_load_dwordx4 v146, s[8:11], s76 offen lds
	s_mov_b32 m0, s45
	s_nop 0
	buffer_load_dwordx4 v148, s[8:11], s76 offen lds
	s_waitcnt vmcnt(8)
	s_waitcnt lgkmcnt(0)
	s_barrier
	s_waitcnt lgkmcnt(7)
	v_mfma_f32_16x16x32_bf16 v[60:63], v[132:135], v[178:181], v[60:63]
	v_mfma_f32_16x16x32_bf16 v[56:59], v[140:143], v[178:181], v[56:59]
	s_waitcnt lgkmcnt(5)
	v_mfma_f32_16x16x32_bf16 v[44:47], v[132:135], v[186:189], v[44:47]
	v_mfma_f32_16x16x32_bf16 v[40:43], v[140:143], v[186:189], v[40:43]
	s_waitcnt lgkmcnt(3)
	v_mfma_f32_16x16x32_bf16 v[28:31], v[132:135], v[194:197], v[28:31]
	v_mfma_f32_16x16x32_bf16 v[24:27], v[140:143], v[194:197], v[24:27]
	s_waitcnt lgkmcnt(1)
	v_mfma_f32_16x16x32_bf16 v[12:15], v[132:135], v[202:205], v[12:15]
	v_mfma_f32_16x16x32_bf16 v[8:11], v[140:143], v[202:205], v[8:11]
	v_mfma_f32_16x16x32_bf16 v[60:63], v[136:139], v[182:185], v[60:63]
	v_mfma_f32_16x16x32_bf16 v[56:59], v[158:161], v[182:185], v[56:59]
	v_mfma_f32_16x16x32_bf16 v[44:47], v[136:139], v[190:193], v[44:47]
	v_mfma_f32_16x16x32_bf16 v[40:43], v[158:161], v[190:193], v[40:43]
	v_mfma_f32_16x16x32_bf16 v[28:31], v[136:139], v[198:201], v[28:31]
	v_mfma_f32_16x16x32_bf16 v[24:27], v[158:161], v[198:201], v[24:27]
	s_waitcnt lgkmcnt(0)
	v_mfma_f32_16x16x32_bf16 v[12:15], v[136:139], v[206:209], v[12:15]
	v_mfma_f32_16x16x32_bf16 v[8:11], v[158:161], v[206:209], v[8:11]
	v_mfma_f32_16x16x32_bf16 v[52:55], v[162:165], v[178:181], v[52:55]
	v_mfma_f32_16x16x32_bf16 v[48:51], v[170:173], v[178:181], v[48:51]
	v_mfma_f32_16x16x32_bf16 v[36:39], v[162:165], v[186:189], v[36:39]
	v_mfma_f32_16x16x32_bf16 v[32:35], v[170:173], v[186:189], v[32:35]
	v_mfma_f32_16x16x32_bf16 v[20:23], v[162:165], v[194:197], v[20:23]
	v_mfma_f32_16x16x32_bf16 v[16:19], v[170:173], v[194:197], v[16:19]
	v_mfma_f32_16x16x32_bf16 v[4:7], v[162:165], v[202:205], v[4:7]
	v_mfma_f32_16x16x32_bf16 v[0:3], v[170:173], v[202:205], v[0:3]
	v_mfma_f32_16x16x32_bf16 v[52:55], v[166:169], v[182:185], v[52:55]
	v_mfma_f32_16x16x32_bf16 v[48:51], v[174:177], v[182:185], v[48:51]
	v_mfma_f32_16x16x32_bf16 v[36:39], v[166:169], v[190:193], v[36:39]
	v_mfma_f32_16x16x32_bf16 v[32:35], v[174:177], v[190:193], v[32:35]
	v_mfma_f32_16x16x32_bf16 v[20:23], v[166:169], v[198:201], v[20:23]
	v_mfma_f32_16x16x32_bf16 v[16:19], v[174:177], v[198:201], v[16:19]
	v_mfma_f32_16x16x32_bf16 v[4:7], v[166:169], v[206:209], v[4:7]
	v_mfma_f32_16x16x32_bf16 v[0:3], v[174:177], v[206:209], v[0:3]
	s_barrier
; #define PG8_STAGE(bufoff, soff, voff) do { _Pragma("unroll") for (int _i = 0; _i < 2; ++_i) \
;         __builtin_amdgcn_raw_ptr_buffer_load_lds(rs_##voff, (PG8_LAS unsigned*)(lds + (bufoff) + ldsw + _i * 8192), 16, (int)(voff)[_i], (int)(soff), 0, 0); } while (0)
; #define PG8_LDA(dst, b, h) do { _Pragma("unroll") for (int m = 0; m < 4; ++m) _Pragma("unroll") for (int k = 0; k < 2; ++k) dst[m][k] = *(const PG8_LAS bf16x8*)(lds + PG8_SA(b, h) + aoff + m * 2048 + k * 1024); } while (0)
; #define PG8_LDB(dst, b, h) do { _Pragma("unroll") for (int n = 0; n < 2; ++n) _Pragma("unroll") for (int k = 0; k < 2; ++k) dst[n][k] = *(const PG8_LAS bf16x8*)(lds + PG8_SB(b, h) + boff + n * 2048 + k * 1024); } while (0)
; #define PG8_MMA(ai, bj, At, Bt) do { __builtin_amdgcn_s_setprio(1); _Pragma("unroll") for (int m = 0; m < 4; ++m) _Pragma("unroll") for (int n = 0; n < 2; ++n) _Pragma("unroll") for (int k = 0; k < 2; ++k) \
;         acc[ai][bj][m][n] = __builtin_amdgcn_mfma_f32_16x16x32_bf16(Bt[n][k], At[m][k], acc[ai][bj][m][n], 0, 0, 0); __builtin_amdgcn_s_setprio(0); } while (0)
; #define PG8_WAIT_V(n) asm volatile("s_waitcnt vmcnt(" #n ")" ::: "memory")
; #define PG8_WAIT_L(n) asm volatile("s_waitcnt lgkmcnt(" #n ")" ::: "memory")
; #define PG8_BAR __builtin_amdgcn_s_barrier()
; #define PG8_SCHED __builtin_amdgcn_sched_barrier(0)
; template <class Epi, class Sched, bool ALIGN_EPI = false, bool SP2 = false>
; __device__ __forceinline__ void gemm_phase(PG8_LAS unsigned char* lds, const Gemm g, const Sched& S, const Epi& E, const int wid  ) {
;     ...
;             PG8_LDB(B0, 1, 0); PG8_LDB(B1, 1, 1); PG8_SCHED; PG8_LDA(At, 1, 0); PG8_STAGE(PG8_SA(0, 1), a2 + hstep, voffA);
;             PG8_WAIT_V(8); PG8_WAIT_L(0); PG8_BAR; PG8_MMA(0, 0, At, B0); PG8_MMA(0, 1, At, B1); PG8_BAR; PG8_SCHED;
;             PG8_LDA(At, 1, 1); PG8_STAGE(PG8_SB(1, 0), b3, voffB); PG8_STAGE(PG8_SB(1, 1), b3 + hstep, voffB); PG8_STAGE(PG8_SA(1, 0), a3, voffA);
;             PG8_WAIT_V(8); PG8_WAIT_L(0); PG8_BAR; PG8_MMA(1, 0, At, B0); PG8_MMA(1, 1, At, B1); PG8_BAR; PG8_SCHED;
;     ...
;         if constexpr (ALIGN_EPI) { if (wr == 0) PG8_BAR; }
	ds_read_b128 v[132:135], v155
	ds_read_b128 v[136:139], v155 offset:1024
	ds_read_b128 v[140:143], v155 offset:2048
	ds_read_b128 v[158:161], v155 offset:3072
	ds_read_b128 v[162:165], v156
	ds_read_b128 v[166:169], v156 offset:1024
	ds_read_b128 v[170:173], v156 offset:2048
	ds_read_b128 v[174:177], v156 offset:3072
	s_add_i32 s76, s76, 0x80000
	s_mov_b32 m0, s46
	ds_read_b128 v[178:181], v154 offset:32768
	ds_read_b128 v[182:185], v154 offset:33792
	ds_read_b128 v[186:189], v154 offset:34816
	ds_read_b128 v[190:193], v154 offset:35840
	ds_read_b128 v[194:197], v154 offset:36864
	ds_read_b128 v[198:201], v154 offset:37888
	ds_read_b128 v[202:205], v154 offset:38912
	ds_read_b128 v[206:209], v154 offset:39936
	buffer_load_dwordx4 v146, s[8:11], s76 offen lds
	s_mov_b32 m0, s48
	s_nop 0
	buffer_load_dwordx4 v148, s[8:11], s76 offen lds
	s_waitcnt vmcnt(8)
	s_waitcnt lgkmcnt(0)
	s_barrier
	s_waitcnt lgkmcnt(7)
	v_mfma_f32_16x16x32_bf16 v[124:127], v[132:135], v[178:181], v[124:127]
	v_mfma_f32_16x16x32_bf16 v[120:123], v[140:143], v[178:181], v[120:123]
	s_waitcnt lgkmcnt(5)
	v_mfma_f32_16x16x32_bf16 v[108:111], v[132:135], v[186:189], v[108:111]
	v_mfma_f32_16x16x32_bf16 v[104:107], v[140:143], v[186:189], v[104:107]
	s_waitcnt lgkmcnt(3)
	v_mfma_f32_16x16x32_bf16 v[92:95], v[132:135], v[194:197], v[92:95]
	v_mfma_f32_16x16x32_bf16 v[88:91], v[140:143], v[194:197], v[88:91]
	s_waitcnt lgkmcnt(1)
	v_mfma_f32_16x16x32_bf16 v[76:79], v[132:135], v[202:205], v[76:79]
	v_mfma_f32_16x16x32_bf16 v[72:75], v[140:143], v[202:205], v[72:75]
	v_mfma_f32_16x16x32_bf16 v[124:127], v[136:139], v[182:185], v[124:127]
	v_mfma_f32_16x16x32_bf16 v[120:123], v[158:161], v[182:185], v[120:123]
	v_mfma_f32_16x16x32_bf16 v[108:111], v[136:139], v[190:193], v[108:111]
	v_mfma_f32_16x16x32_bf16 v[104:107], v[158:161], v[190:193], v[104:107]
	v_mfma_f32_16x16x32_bf16 v[92:95], v[136:139], v[198:201], v[92:95]
	v_mfma_f32_16x16x32_bf16 v[88:91], v[158:161], v[198:201], v[88:91]
	s_waitcnt lgkmcnt(0)
	v_mfma_f32_16x16x32_bf16 v[76:79], v[136:139], v[206:209], v[76:79]
	v_mfma_f32_16x16x32_bf16 v[72:75], v[158:161], v[206:209], v[72:75]
	v_mfma_f32_16x16x32_bf16 v[116:119], v[162:165], v[178:181], v[116:119]
	v_mfma_f32_16x16x32_bf16 v[112:115], v[170:173], v[178:181], v[112:115]
	v_mfma_f32_16x16x32_bf16 v[100:103], v[162:165], v[186:189], v[100:103]
	v_mfma_f32_16x16x32_bf16 v[96:99], v[170:173], v[186:189], v[96:99]
	v_mfma_f32_16x16x32_bf16 v[84:87], v[162:165], v[194:197], v[84:87]
	v_mfma_f32_16x16x32_bf16 v[80:83], v[170:173], v[194:197], v[80:83]
	v_mfma_f32_16x16x32_bf16 v[68:71], v[162:165], v[202:205], v[68:71]
	v_mfma_f32_16x16x32_bf16 v[64:67], v[170:173], v[202:205], v[64:67]
	v_mfma_f32_16x16x32_bf16 v[116:119], v[166:169], v[182:185], v[116:119]
	v_mfma_f32_16x16x32_bf16 v[112:115], v[174:177], v[182:185], v[112:115]
	v_mfma_f32_16x16x32_bf16 v[100:103], v[166:169], v[190:193], v[100:103]
	v_mfma_f32_16x16x32_bf16 v[96:99], v[174:177], v[190:193], v[96:99]
	v_mfma_f32_16x16x32_bf16 v[84:87], v[166:169], v[198:201], v[84:87]
	v_mfma_f32_16x16x32_bf16 v[80:83], v[174:177], v[198:201], v[80:83]
	v_mfma_f32_16x16x32_bf16 v[68:71], v[166:169], v[206:209], v[68:71]
	v_mfma_f32_16x16x32_bf16 v[64:67], v[174:177], v[206:209], v[64:67]
	s_barrier
	s_mov_b32 m0, s50
	s_or_b32 s76, s75, 0x80
	ds_read_b128 v[178:181], v154 offset:49152
	ds_read_b128 v[182:185], v154 offset:50176
	ds_read_b128 v[186:189], v154 offset:51200
	ds_read_b128 v[190:193], v154 offset:52224
	ds_read_b128 v[194:197], v154 offset:53248
	ds_read_b128 v[198:201], v154 offset:54272
	ds_read_b128 v[202:205], v154 offset:55296
	ds_read_b128 v[206:209], v154 offset:56320
	buffer_load_dwordx4 v147, s[12:15], s76 offen lds
	s_mov_b32 m0, s51
	s_add_i32 s75, s75, 0x80080
	buffer_load_dwordx4 v149, s[12:15], s76 offen lds
	s_mov_b32 m0, s55
	s_nop 0
	buffer_load_dwordx4 v147, s[12:15], s75 offen lds
	s_mov_b32 m0, s58
	s_nop 0
	buffer_load_dwordx4 v149, s[12:15], s75 offen lds
	s_mov_b32 m0, s53
	s_nop 0
	buffer_load_dwordx4 v146, s[8:11], s74 offen lds
	s_mov_b32 m0, s54
	s_nop 0
	buffer_load_dwordx4 v148, s[8:11], s74 offen lds
	s_waitcnt vmcnt(8)
	s_waitcnt lgkmcnt(0)
	s_barrier
	s_waitcnt lgkmcnt(7)
	v_mfma_f32_16x16x32_bf16 v[60:63], v[132:135], v[178:181], v[60:63]
	v_mfma_f32_16x16x32_bf16 v[56:59], v[140:143], v[178:181], v[56:59]
	s_waitcnt lgkmcnt(5)
	v_mfma_f32_16x16x32_bf16 v[44:47], v[132:135], v[186:189], v[44:47]
	v_mfma_f32_16x16x32_bf16 v[40:43], v[140:143], v[186:189], v[40:43]
	s_waitcnt lgkmcnt(3)
	v_mfma_f32_16x16x32_bf16 v[28:31], v[132:135], v[194:197], v[28:31]
	v_mfma_f32_16x16x32_bf16 v[24:27], v[140:143], v[194:197], v[24:27]
	s_waitcnt lgkmcnt(1)
	v_mfma_f32_16x16x32_bf16 v[12:15], v[132:135], v[202:205], v[12:15]
	v_mfma_f32_16x16x32_bf16 v[8:11], v[140:143], v[202:205], v[8:11]
	v_mfma_f32_16x16x32_bf16 v[60:63], v[136:139], v[182:185], v[60:63]
	v_mfma_f32_16x16x32_bf16 v[56:59], v[158:161], v[182:185], v[56:59]
	v_mfma_f32_16x16x32_bf16 v[44:47], v[136:139], v[190:193], v[44:47]
	v_mfma_f32_16x16x32_bf16 v[40:43], v[158:161], v[190:193], v[40:43]
	v_mfma_f32_16x16x32_bf16 v[28:31], v[136:139], v[198:201], v[28:31]
	v_mfma_f32_16x16x32_bf16 v[24:27], v[158:161], v[198:201], v[24:27]
	s_waitcnt lgkmcnt(0)
	v_mfma_f32_16x16x32_bf16 v[12:15], v[136:139], v[206:209], v[12:15]
	v_mfma_f32_16x16x32_bf16 v[8:11], v[158:161], v[206:209], v[8:11]
	v_mfma_f32_16x16x32_bf16 v[52:55], v[162:165], v[178:181], v[52:55]
	v_mfma_f32_16x16x32_bf16 v[48:51], v[170:173], v[178:181], v[48:51]
	v_mfma_f32_16x16x32_bf16 v[36:39], v[162:165], v[186:189], v[36:39]
	v_mfma_f32_16x16x32_bf16 v[32:35], v[170:173], v[186:189], v[32:35]
	v_mfma_f32_16x16x32_bf16 v[20:23], v[162:165], v[194:197], v[20:23]
	v_mfma_f32_16x16x32_bf16 v[16:19], v[170:173], v[194:197], v[16:19]
	v_mfma_f32_16x16x32_bf16 v[4:7], v[162:165], v[202:205], v[4:7]
	v_mfma_f32_16x16x32_bf16 v[0:3], v[170:173], v[202:205], v[0:3]
	v_mfma_f32_16x16x32_bf16 v[52:55], v[166:169], v[182:185], v[52:55]
	v_mfma_f32_16x16x32_bf16 v[48:51], v[174:177], v[182:185], v[48:51]
	v_mfma_f32_16x16x32_bf16 v[36:39], v[166:169], v[190:193], v[36:39]
	v_mfma_f32_16x16x32_bf16 v[32:35], v[174:177], v[190:193], v[32:35]
	v_mfma_f32_16x16x32_bf16 v[20:23], v[166:169], v[198:201], v[20:23]
	v_mfma_f32_16x16x32_bf16 v[16:19], v[174:177], v[198:201], v[16:19]
	v_mfma_f32_16x16x32_bf16 v[4:7], v[166:169], v[206:209], v[4:7]
	v_mfma_f32_16x16x32_bf16 v[0:3], v[174:177], v[206:209], v[0:3]
	s_barrier
	s_add_i32 s73, s73, 2
	s_addk_i32 s41, 0x100
	s_addk_i32 s72, 0x100
	s_cmp_gt_u32 s73, 29
	s_cbranch_scc0 .LBB0_4016
	s_and_b64 vcc, exec, s[26:27]
	s_cbranch_vccz .LBB0_4019
	s_barrier

; __device__ __forceinline__ unsigned xb_ld(unsigned* p)              { return __hip_atomic_load(p, __ATOMIC_RELAXED, __HIP_MEMORY_SCOPE_AGENT); }
; __device__ __forceinline__ void xcd_barrier_complete(unsigned* bar, unsigned x, unsigned& nloc, unsigned& nx) {
;     const unsigned G = gridDim.x * gridDim.y * gridDim.z;
;     unsigned sum, cnt, mine, sp = 0u;
;     for (;;) {
;         sum = 0u; cnt = 0u; mine = 0u;
; #pragma unroll
;         for (unsigned j = 0; j < 16; ++j) { const unsigned c = xb_ld(&bar[XB_XCNT(j)]); sum += c; cnt += (c > 0u) ? 1u : 0u; mine = (j == x) ? c : mine; }
; __device__ __forceinline__ void xcd_barrier(const XcdBarrier& b) {
;     asm volatile("s_waitcnt vmcnt(0)" ::: "memory");
;     __syncthreads();
;     if (threadIdx.x == 0) {
;         unsigned* bar = b.bar;
;         __builtin_amdgcn_s_waitcnt(0);
;         unsigned nloc = b.st[0], nx = b.st[1];
;         if (nloc == 0u) { xcd_barrier_complete(bar, b.x, nloc, nx); b.st[0] = nloc; b.st[1] = nx; }
.LBB0_4047:
	s_setprio 0
	s_add_i32 s0, 0, 0x20520
	v_mov_b32_e32 v0, s0
	s_waitcnt lgkmcnt(0)
	ds_read_b64 v[0:1], v0
	s_getreg_b32 s4, hwreg(HW_REG_XCC_ID, 0, 4)
	s_waitcnt vmcnt(0)
	s_waitcnt vmcnt(16) lgkmcnt(0)
	s_barrier
	v_readfirstlane_b32 s2, v0
	v_readfirstlane_b32 s3, v1
	s_mov_b64 s[0:1], exec
	v_readlane_b32 s6, v246, 2
	v_readlane_b32 s7, v246, 3
	s_and_b64 s[6:7], s[0:1], s[6:7]
	s_mov_b64 exec, s[6:7]
	s_cbranch_execz .LBB0_4099
	s_add_i32 s5, 0, 0x20160
	v_mov_b32_e32 v0, s5
	s_waitcnt vmcnt(0) expcnt(0) lgkmcnt(0)
	ds_read_b32 v2, v0
	s_add_i32 s5, 0, 0x20164
	v_mov_b32_e32 v0, s5
	ds_read_b32 v0, v0
	s_and_b32 s33, s4, 15
	s_waitcnt lgkmcnt(1)
	v_cmp_ne_u32_e32 vcc, 0, v2
	s_cbranch_vccnz .LBB0_4063
	v_readlane_b32 s4, v246, 0
	v_readlane_b32 s5, v246, 1
	s_load_dwordx2 s[8:9], s[4:5], 0x4
	s_add_u32 s4, s2, 0x4200
	s_addc_u32 s5, s3, 0
	s_add_u32 s6, s2, 0x4400
	s_addc_u32 s7, s3, 0
	s_waitcnt lgkmcnt(0)
	s_mul_i32 s46, s8, s52
	s_add_u32 s8, s2, 0x4500
	s_mul_i32 s46, s46, s9
	s_addc_u32 s9, s3, 0
	s_add_u32 s10, s2, 0x4600
	s_addc_u32 s11, s3, 0
	s_add_u32 s12, s2, 0x4700
	s_addc_u32 s13, s3, 0
	s_add_u32 s14, s2, 0x4800
	s_addc_u32 s15, s3, 0
	s_add_u32 s16, s2, 0x4900
	s_addc_u32 s17, s3, 0
	s_add_u32 s18, s2, 0x4a00
	s_addc_u32 s19, s3, 0
	s_add_u32 s20, s2, 0x4b00
	s_addc_u32 s21, s3, 0
	s_add_u32 s22, s2, 0x4c00
	s_addc_u32 s23, s3, 0
	s_add_u32 s24, s2, 0x4d00
	s_addc_u32 s25, s3, 0
	s_add_u32 s26, s2, 0x4e00
	s_addc_u32 s27, s3, 0
	s_add_u32 s28, s2, 0x4f00
	s_addc_u32 s29, s3, 0
	s_add_u32 s30, s2, 0x5000
	s_addc_u32 s31, s3, 0
	s_add_u32 s34, s2, 0x5100
	s_addc_u32 s35, s3, 0
	s_add_u32 s36, s2, 0x5200
	s_addc_u32 s37, s3, 0
	s_add_u32 s38, s2, 0x5300
	s_addc_u32 s39, s3, 0
	s_mov_b32 s47, 1
	v_mov_b32_e32 v16, 0
	s_branch .LBB0_4051
